# de-serialised compiler chains: pool window loads (exec-masked, one wait), residual GEMM epilogues (12 loads in flight), SSD MFMA stage (ring-buffered LDS fragments, grouped masked reads); attention lo
# speedup vs baseline: 1.0410x; 1.0218x over previous
.LBB0_208:
	s_or_b64 exec, exec, s[44:45]
	v_add_u32_e32 v58, s95, v83
	v_min_i32_e32 v58, 3, v58
	v_add_u32_e32 v58, 1, v58
	v_cvt_f32_i32_e32 v58, v58
	s_waitcnt vmcnt(26)
	v_cndmask_b32_e32 v9, 0, v9, vcc
	s_waitcnt vmcnt(8)
	v_cndmask_b32_e64 v0, 0, v52, s[38:39]
	v_cndmask_b32_e64 v10, 0, v10, s[0:1]
	v_lshlrev_b32_e32 v52, 16, v9
	v_and_b32_e32 v9, 0xffff0000, v9
	v_cndmask_b32_e64 v11, 0, v11, s[2:3]
	v_add_f32_e32 v53, 0, v52
	v_add_f32_e32 v54, 0, v9
	v_lshlrev_b32_e32 v55, 16, v10
	v_and_b32_e32 v10, 0xffff0000, v10
	v_rcp_iflag_f32_e32 v58, v58
	v_cndmask_b32_e64 v12, 0, v12, s[6:7]
	v_add_f32_e32 v53, v53, v55
	v_add_f32_e32 v54, v54, v10
	v_lshlrev_b32_e32 v56, 16, v11
	v_and_b32_e32 v11, 0xffff0000, v11
	v_add_f32_e32 v53, v53, v56
	v_add_f32_e32 v54, v54, v11
	v_lshlrev_b32_e32 v57, 16, v12
	v_and_b32_e32 v12, 0xffff0000, v12
	v_add_f32_e32 v53, v53, v57
	v_add_f32_e32 v54, v54, v12
	v_fma_f32 v59, v58, v53, -v57
	v_fma_f32 v58, v58, v54, -v12
	v_sub_f32_e32 v9, v54, v9
	v_add_u32_e32 v54, s95, v127
	v_min_i32_e32 v54, 3, v54
	v_add_u32_e32 v54, 1, v54
	v_cvt_f32_i32_e32 v54, v54
	v_cndmask_b32_e64 v13, v13, 0, s[8:9]
	v_sub_f32_e32 v52, v53, v52
	v_lshlrev_b32_e32 v53, 16, v13
	v_rcp_iflag_f32_e32 v54, v54
	v_and_b32_e32 v13, 0xffff0000, v13
	v_cvt_pk_bf16_f32 v58, v59, v58
	v_add_u32_e32 v116, 0, v145
	v_add_f32_e32 v52, v52, v53
	v_add_f32_e32 v9, v9, v13
	s_waitcnt lgkmcnt(0)
	s_barrier
	ds_write_b32 v116, v58 offset:34816
	v_fma_f32 v58, v54, v52, -v53
	v_fma_f32 v54, v54, v9, -v13
	v_cvt_pk_bf16_f32 v54, v58, v54
	v_add_u32_e32 v117, 0, v146
	ds_write_b32 v117, v54 offset:34816
	v_add_u32_e32 v54, s95, v128
	v_min_i32_e32 v54, 3, v54
	v_add_u32_e32 v54, 1, v54
	v_cvt_f32_i32_e32 v54, v54
	v_cndmask_b32_e64 v14, 0, v14, s[10:11]
	v_sub_f32_e32 v52, v52, v55
	v_sub_f32_e32 v9, v9, v10
	v_rcp_iflag_f32_e32 v54, v54
	v_lshlrev_b32_e32 v10, 16, v14
	v_and_b32_e32 v14, 0xffff0000, v14
	v_add_f32_e32 v52, v52, v10
	v_add_f32_e32 v9, v9, v14
	v_fma_f32 v55, v54, v52, -v10
	v_fma_f32 v54, v54, v9, -v14
	v_cvt_pk_bf16_f32 v54, v55, v54
	v_add_u32_e32 v168, 0, v147
	ds_write_b32 v168, v54 offset:34816
	v_add_u32_e32 v54, s95, v129
	v_min_i32_e32 v54, 3, v54
	v_add_u32_e32 v54, 1, v54
	v_cvt_f32_i32_e32 v54, v54
	v_cndmask_b32_e64 v15, 0, v15, s[12:13]
	v_sub_f32_e32 v52, v52, v56
	v_sub_f32_e32 v9, v9, v11
	v_rcp_iflag_f32_e32 v54, v54
	v_lshlrev_b32_e32 v11, 16, v15
	v_and_b32_e32 v15, 0xffff0000, v15
	v_add_f32_e32 v52, v52, v11
	v_add_f32_e32 v9, v9, v15
	v_fma_f32 v55, v54, v52, -v11
	v_fma_f32 v54, v54, v9, -v15
	v_cvt_pk_bf16_f32 v54, v55, v54
	v_add_u32_e32 v169, 0, v148
	ds_write_b32 v169, v54 offset:34816
	v_add_u32_e32 v54, s95, v130
	v_min_i32_e32 v54, 3, v54
	v_add_u32_e32 v54, 1, v54
	v_cvt_f32_i32_e32 v54, v54
	v_cndmask_b32_e64 v16, 0, v16, s[14:15]
	v_sub_f32_e32 v52, v52, v57
	v_sub_f32_e32 v9, v9, v12
	v_rcp_iflag_f32_e32 v54, v54
	v_lshlrev_b32_e32 v12, 16, v16
	v_add_f32_e32 v52, v52, v12
	v_and_b32_e32 v16, 0xffff0000, v16
	v_fma_f32 v55, v54, v52, -v12
	v_sub_f32_e32 v52, v52, v53
	v_add_u32_e32 v53, s95, v131
	v_min_i32_e32 v53, 3, v53
	v_add_u32_e32 v53, 1, v53
	v_cvt_f32_i32_e32 v53, v53
	v_cndmask_b32_e64 v17, 0, v17, s[16:17]
	v_add_f32_e32 v9, v9, v16
	v_fma_f32 v54, v54, v9, -v16
	v_rcp_iflag_f32_e32 v53, v53
	v_sub_f32_e32 v9, v9, v13
	v_lshlrev_b32_e32 v13, 16, v17
	v_cvt_pk_bf16_f32 v54, v55, v54
	v_add_u32_e32 v170, 0, v149
	v_add_f32_e32 v52, v52, v13
	ds_write_b32 v170, v54 offset:34816
	v_fma_f32 v54, v53, v52, -v13
	v_sub_f32_e32 v10, v52, v10
	v_add_u32_e32 v52, s95, v132
	v_min_i32_e32 v52, 3, v52
	v_add_u32_e32 v52, 1, v52
	v_cvt_f32_i32_e32 v52, v52
	v_and_b32_e32 v17, 0xffff0000, v17
	v_cndmask_b32_e64 v50, 0, v50, s[18:19]
	v_add_f32_e32 v9, v9, v17
	v_rcp_iflag_f32_e32 v52, v52
	v_fma_f32 v53, v53, v9, -v17
	v_sub_f32_e32 v9, v9, v14
	v_lshlrev_b32_e32 v14, 16, v50
	v_and_b32_e32 v50, 0xffff0000, v50
	v_cndmask_b32_e64 v51, 0, v51, s[20:21]
	v_cvt_pk_bf16_f32 v53, v54, v53
	v_add_u32_e32 v171, 0, v150
	v_add_f32_e32 v10, v10, v14
	v_add_f32_e32 v9, v9, v50
	ds_write_b32 v171, v53 offset:34816
	v_fma_f32 v53, v52, v10, -v14
	v_fma_f32 v52, v52, v9, -v50
	v_sub_f32_e32 v10, v10, v11
	v_sub_f32_e32 v9, v9, v15
	v_lshlrev_b32_e32 v11, 16, v51
	v_and_b32_e32 v15, 0xffff0000, v51
	v_add_u32_e32 v51, s95, v133
	v_min_i32_e32 v51, 3, v51
	v_add_u32_e32 v51, 1, v51
	v_cvt_f32_i32_e32 v51, v51
	v_cvt_pk_bf16_f32 v52, v53, v52
	v_add_u32_e32 v172, 0, v151
	v_add_f32_e32 v10, v10, v11
	v_rcp_iflag_f32_e32 v51, v51
	v_add_f32_e32 v9, v9, v15
	ds_write_b32 v172, v52 offset:34816
	v_cndmask_b32_e64 v8, 0, v8, s[22:23]
	v_fma_f32 v52, v51, v10, -v11
	v_fma_f32 v51, v51, v9, -v15
	v_sub_f32_e32 v9, v9, v16
	v_add_u32_e32 v16, s95, v134
	v_min_i32_e32 v16, 3, v16
	v_add_u32_e32 v16, 1, v16
	v_cvt_f32_i32_e32 v16, v16
	v_sub_f32_e32 v10, v10, v12
	v_lshlrev_b32_e32 v12, 16, v8
	v_and_b32_e32 v8, 0xffff0000, v8
	v_rcp_iflag_f32_e32 v16, v16
	v_cvt_pk_bf16_f32 v51, v52, v51
	v_add_u32_e32 v173, 0, v152
	v_add_f32_e32 v10, v10, v12
	v_add_f32_e32 v9, v9, v8
	ds_write_b32 v173, v51 offset:34816
	v_fma_f32 v51, v16, v10, -v12
	v_fma_f32 v16, v16, v9, -v8
	v_cvt_pk_bf16_f32 v16, v51, v16
	v_add_u32_e32 v174, 0, v153
	ds_write_b32 v174, v16 offset:34816
	v_add_u32_e32 v16, s95, v135
	v_min_i32_e32 v16, 3, v16
	v_add_u32_e32 v16, 1, v16
	v_cvt_f32_i32_e32 v16, v16
	v_cndmask_b32_e64 v7, 0, v7, s[24:25]
	v_sub_f32_e32 v10, v10, v13
	v_sub_f32_e32 v9, v9, v17
	v_rcp_iflag_f32_e32 v16, v16
	v_lshlrev_b32_e32 v13, 16, v7
	v_and_b32_e32 v7, 0xffff0000, v7
	v_add_f32_e32 v10, v10, v13
	v_add_f32_e32 v9, v9, v7
	v_fma_f32 v17, v16, v10, -v13
	v_fma_f32 v16, v16, v9, -v7
	v_cvt_pk_bf16_f32 v16, v17, v16
	v_add_u32_e32 v175, 0, v154
	ds_write_b32 v175, v16 offset:34816
	v_add_u32_e32 v16, s95, v136
	v_min_i32_e32 v16, 3, v16
	v_add_u32_e32 v16, 1, v16
	v_cvt_f32_i32_e32 v16, v16
	v_cndmask_b32_e64 v6, 0, v6, s[26:27]
	v_sub_f32_e32 v10, v10, v14
	v_sub_f32_e32 v9, v9, v50
	v_rcp_iflag_f32_e32 v16, v16
	v_lshlrev_b32_e32 v14, 16, v6
	v_and_b32_e32 v6, 0xffff0000, v6
	v_add_f32_e32 v10, v10, v14
	v_add_f32_e32 v9, v9, v6
	v_fma_f32 v17, v16, v10, -v14
	v_fma_f32 v16, v16, v9, -v6
	v_sub_f32_e32 v9, v9, v15
	v_add_u32_e32 v15, s95, v137
	v_min_i32_e32 v15, 3, v15
	v_add_u32_e32 v15, 1, v15
	v_cvt_f32_i32_e32 v15, v15
	v_cndmask_b32_e64 v5, 0, v5, s[28:29]
	v_sub_f32_e32 v10, v10, v11
	v_lshlrev_b32_e32 v11, 16, v5
	v_rcp_iflag_f32_e32 v15, v15
	v_cvt_pk_bf16_f32 v16, v17, v16
	v_add_u32_e32 v176, 0, v155
	v_add_f32_e32 v10, v10, v11
	ds_write_b32 v176, v16 offset:34816
	v_fma_f32 v16, v15, v10, -v11
	v_sub_f32_e32 v10, v10, v12
	v_add_u32_e32 v12, s95, v138
	v_min_i32_e32 v12, 3, v12
	v_add_u32_e32 v12, 1, v12
	v_cvt_f32_i32_e32 v12, v12
	v_and_b32_e32 v5, 0xffff0000, v5
	v_cndmask_b32_e64 v4, 0, v4, s[42:43]
	v_add_f32_e32 v9, v9, v5
	v_rcp_iflag_f32_e32 v12, v12
	v_fma_f32 v15, v15, v9, -v5
	v_sub_f32_e32 v8, v9, v8
	v_lshlrev_b32_e32 v9, 16, v4
	v_and_b32_e32 v4, 0xffff0000, v4
	v_add_f32_e32 v10, v10, v9
	v_add_f32_e32 v8, v8, v4
	v_fma_f32 v9, v12, v10, -v9
	v_fma_f32 v4, v12, v8, -v4
	v_cvt_pk_bf16_f32 v4, v9, v4
	v_add_u32_e32 v9, s95, v139
	v_min_i32_e32 v9, 3, v9
	v_add_u32_e32 v9, 1, v9
	v_cvt_f32_i32_e32 v9, v9
	v_cndmask_b32_e64 v3, 0, v3, s[34:35]
	v_add_u32_e32 v177, 0, v156
	v_add_u32_e32 v178, 0, v157
	v_rcp_iflag_f32_e32 v9, v9
	v_sub_f32_e32 v7, v8, v7
	v_lshlrev_b32_e32 v8, 16, v3
	v_and_b32_e32 v3, 0xffff0000, v3
	v_cvt_pk_bf16_f32 v15, v16, v15
	ds_write_b32 v177, v15 offset:34816
	ds_write_b32 v178, v4 offset:34816
	v_sub_f32_e32 v4, v10, v13
	v_add_f32_e32 v7, v7, v3
	v_add_f32_e32 v4, v4, v8
	v_fma_f32 v3, v9, v7, -v3
	v_fma_f32 v8, v9, v4, -v8
	v_cvt_pk_bf16_f32 v3, v8, v3
	v_add_u32_e32 v179, 0, v158
	ds_write_b32 v179, v3 offset:34816
	v_sub_f32_e32 v3, v4, v14
	v_sub_f32_e32 v4, v7, v6
	v_add_u32_e32 v7, s95, v140
	v_min_i32_e32 v7, 3, v7
	v_add_u32_e32 v7, 1, v7
	v_cvt_f32_i32_e32 v7, v7
	v_cndmask_b32_e64 v2, 0, v2, s[36:37]
	v_lshlrev_b32_e32 v6, 16, v2
	v_and_b32_e32 v2, 0xffff0000, v2
	v_rcp_iflag_f32_e32 v7, v7
	v_add_f32_e32 v4, v4, v2
	v_add_f32_e32 v3, v3, v6
	v_add_u32_e32 v180, 0, v159
	v_fma_f32 v2, v7, v4, -v2
	v_fma_f32 v6, v7, v3, -v6
	v_cvt_pk_bf16_f32 v2, v6, v2
	ds_write_b32 v180, v2 offset:34816
	v_sub_f32_e32 v2, v3, v11
	v_sub_f32_e32 v3, v4, v5
	v_add_u32_e32 v5, s95, v141
	v_min_i32_e32 v5, 3, v5
	v_add_u32_e32 v5, 1, v5
	v_cvt_f32_i32_e32 v5, v5
	s_or_b32 s0, s94, 0x80
	v_lshlrev_b32_e32 v4, 16, v0
	v_and_b32_e32 v0, 0xffff0000, v0
	v_rcp_iflag_f32_e32 v5, v5
	s_xor_b32 s1, s95, 0xffffff7f
	s_mul_i32 s2, s0, 0x1e00
	v_add_f32_e32 v2, v2, v4
	v_add_f32_e32 v3, v3, v0
	s_mul_hi_i32 s3, s0, 0x1e00
	s_add_u32 s2, s91, s2
	v_fma_f32 v2, v5, v2, -v4
	v_fma_f32 v0, v5, v3, -v0
	s_addc_u32 s3, s92, s3
	v_mov_b32_e32 v105, v1
	v_cvt_pk_bf16_f32 v0, v2, v0
	v_add_u32_e32 v181, 0, v160
	v_cmp_lt_i32_e32 vcc, s1, v141
	v_lshl_add_u64 v[2:3], s[2:3], 0, v[104:105]
	s_mov_b64 s[2:3], 0x1520
	ds_write_b32 v181, v0 offset:34816
	v_lshl_add_u64 v[2:3], v[2:3], 0, s[2:3]
	v_cndmask_b32_e32 v0, 0, v141, vcc
	s_movk_i32 s6, 0x1e00
	v_mad_i64_i32 v[4:5], s[2:3], v0, s6, v[2:3]
	global_load_dword v0, v[4:5], off
	v_add_u32_e32 v185, v144, v143
	v_add_u32_e32 v184, v144, v161
	v_lshlrev_b32_e32 v104, 1, v90
	v_mov_b32_e32 v103, v1
	v_add_u32_e32 v183, v144, v163
	v_lshlrev_b32_e32 v114, 1, v98
	v_mov_b32_e32 v115, v1
	s_waitcnt vmcnt(0)
	v_cndmask_b32_e32 v182, 0, v0, vcc
	v_cmp_lt_i32_e32 vcc, s1, v124
	v_mov_b32_e32 v211, 0
	s_nop 0
	v_cndmask_b32_e32 v0, 0, v124, vcc
	v_mad_i64_i32 v[4:5], s[2:3], v0, s6, v[2:3]
	s_and_saveexec_b64 s[98:99], vcc
	global_load_dword v211, v[4:5], off
	s_mov_b64 exec, s[98:99]
	v_cmp_lt_i32_e32 vcc, s1, v125
	v_mov_b32_e32 v212, 0
	s_nop 0
	v_cndmask_b32_e32 v0, 0, v125, vcc
	v_mad_i64_i32 v[4:5], s[2:3], v0, s6, v[2:3]
	s_and_saveexec_b64 s[98:99], vcc
	global_load_dword v212, v[4:5], off
	s_mov_b64 exec, s[98:99]
	v_cmp_lt_i32_e32 vcc, s1, v126
	v_mov_b32_e32 v213, 0
	s_nop 0
	v_cndmask_b32_e32 v0, 0, v126, vcc
	v_mad_i64_i32 v[4:5], s[2:3], v0, s6, v[2:3]
	s_and_saveexec_b64 s[98:99], vcc
	global_load_dword v213, v[4:5], off
	s_mov_b64 exec, s[98:99]
	v_cmp_lt_i32_e32 vcc, s1, v83
	v_mov_b32_e32 v214, 0
	s_nop 0
	v_cndmask_b32_e32 v0, 0, v83, vcc
	v_mad_i64_i32 v[4:5], s[2:3], v0, s6, v[2:3]
	s_and_saveexec_b64 s[98:99], vcc
	global_load_dword v214, v[4:5], off
	s_mov_b64 exec, s[98:99]
	v_cmp_gt_i32_e32 vcc, s1, v83
	s_nop 1
	v_cndmask_b32_e64 v0, v127, 0, vcc
	v_mad_i64_i32 v[4:5], s[2:3], v0, s6, v[2:3]
	global_load_dword v0, v[4:5], off
	s_waitcnt vmcnt(0)
	v_cndmask_b32_e64 v191, v0, 0, vcc
	v_cmp_lt_i32_e32 vcc, s1, v128
	v_mov_b32_e32 v210, 0
	s_nop 0
	v_cndmask_b32_e32 v0, 0, v128, vcc
	v_mad_i64_i32 v[4:5], s[2:3], v0, s6, v[2:3]
	s_and_saveexec_b64 s[98:99], vcc
	global_load_dword v210, v[4:5], off
	s_mov_b64 exec, s[98:99]
	v_cmp_lt_i32_e32 vcc, s1, v129
	v_mov_b32_e32 v209, 0
	s_nop 0
	v_cndmask_b32_e32 v0, 0, v129, vcc
	v_mad_i64_i32 v[4:5], s[2:3], v0, s6, v[2:3]
	s_and_saveexec_b64 s[98:99], vcc
	global_load_dword v209, v[4:5], off
	s_mov_b64 exec, s[98:99]
	v_cmp_lt_i32_e32 vcc, s1, v130
	v_mov_b32_e32 v208, 0
	s_nop 0
	v_cndmask_b32_e32 v0, 0, v130, vcc
	v_mad_i64_i32 v[4:5], s[2:3], v0, s6, v[2:3]
	s_and_saveexec_b64 s[98:99], vcc
	global_load_dword v208, v[4:5], off
	s_mov_b64 exec, s[98:99]
	v_cmp_lt_i32_e32 vcc, s1, v131
	v_mov_b32_e32 v207, 0
	s_nop 0
	v_cndmask_b32_e32 v0, 0, v131, vcc
	v_mad_i64_i32 v[4:5], s[2:3], v0, s6, v[2:3]
	s_and_saveexec_b64 s[98:99], vcc
	global_load_dword v207, v[4:5], off
	s_mov_b64 exec, s[98:99]
	v_cmp_lt_i32_e32 vcc, s1, v132
	v_mov_b32_e32 v206, 0
	s_nop 0
	v_cndmask_b32_e32 v0, 0, v132, vcc
	v_mad_i64_i32 v[4:5], s[2:3], v0, s6, v[2:3]
	s_and_saveexec_b64 s[98:99], vcc
	global_load_dword v206, v[4:5], off
	s_mov_b64 exec, s[98:99]
	v_cmp_lt_i32_e32 vcc, s1, v133
	v_mov_b32_e32 v205, 0
	s_nop 0
	v_cndmask_b32_e32 v0, 0, v133, vcc
	v_mad_i64_i32 v[4:5], s[2:3], v0, s6, v[2:3]
	s_and_saveexec_b64 s[98:99], vcc
	global_load_dword v205, v[4:5], off
	s_mov_b64 exec, s[98:99]
	v_cmp_lt_i32_e32 vcc, s1, v134
	v_mov_b32_e32 v204, 0
	s_nop 0
	v_cndmask_b32_e32 v0, 0, v134, vcc
	v_mad_i64_i32 v[4:5], s[2:3], v0, s6, v[2:3]
	s_and_saveexec_b64 s[98:99], vcc
	global_load_dword v204, v[4:5], off
	s_mov_b64 exec, s[98:99]
	v_cmp_lt_i32_e32 vcc, s1, v135
	v_mov_b32_e32 v192, 0
	s_nop 0
	v_cndmask_b32_e32 v0, 0, v135, vcc
	v_mad_i64_i32 v[4:5], s[2:3], v0, s6, v[2:3]
	s_and_saveexec_b64 s[98:99], vcc
	global_load_dword v192, v[4:5], off
	s_mov_b64 exec, s[98:99]
	v_cmp_lt_i32_e32 vcc, s1, v136
	v_mov_b32_e32 v190, 0
	s_nop 0
	v_cndmask_b32_e32 v0, 0, v136, vcc
	v_mad_i64_i32 v[4:5], s[2:3], v0, s6, v[2:3]
	s_and_saveexec_b64 s[98:99], vcc
	global_load_dword v190, v[4:5], off
	s_mov_b64 exec, s[98:99]
	v_cmp_lt_i32_e32 vcc, s1, v137
	v_mov_b32_e32 v189, 0
	s_nop 0
	v_cndmask_b32_e32 v0, 0, v137, vcc
	v_mad_i64_i32 v[4:5], s[2:3], v0, s6, v[2:3]
	s_and_saveexec_b64 s[98:99], vcc
	global_load_dword v189, v[4:5], off
	s_mov_b64 exec, s[98:99]
	v_cmp_lt_i32_e32 vcc, s1, v138
	v_mov_b32_e32 v188, 0
	s_nop 0
	v_cndmask_b32_e32 v0, 0, v138, vcc
	v_mad_i64_i32 v[4:5], s[2:3], v0, s6, v[2:3]
	s_and_saveexec_b64 s[98:99], vcc
	global_load_dword v188, v[4:5], off
	s_mov_b64 exec, s[98:99]
	v_cmp_lt_i32_e32 vcc, s1, v139
	v_mov_b32_e32 v187, 0
	s_nop 0
	v_cndmask_b32_e32 v0, 0, v139, vcc
	v_mad_i64_i32 v[4:5], s[2:3], v0, s6, v[2:3]
	s_and_saveexec_b64 s[98:99], vcc
	global_load_dword v187, v[4:5], off
	s_mov_b64 exec, s[98:99]
	v_cmp_lt_i32_e32 vcc, s1, v140
	s_and_b32 s1, s0, 0xf80
	s_nop 0
	v_cndmask_b32_e32 v0, 0, v140, vcc
	v_mad_i64_i32 v[2:3], s[2:3], v0, s6, v[2:3]
	global_load_dword v0, v[2:3], off
	v_add_u32_e32 v2, s94, v142
	v_ashrrev_i32_e32 v3, 31, v2
	v_lshlrev_b64 v[2:3], 12, v[2:3]
	s_waitcnt lgkmcnt(0)
	s_barrier
	v_lshl_add_u64 v[2:3], s[70:71], 0, v[2:3]
	s_mov_b64 s[2:3], 0x26000900
	ds_read_b128 v[74:77], v185 offset:34816
	ds_read_b128 v[78:81], v185 offset:34848
	ds_read_b128 v[70:73], v185 offset:34880
	ds_read_b128 v[66:69], v185 offset:34912
	ds_read_b128 v[62:65], v185 offset:34944
	ds_read_b128 v[58:61], v185 offset:34976
	ds_read_b128 v[54:57], v185 offset:35008
	ds_read_b128 v[50:53], v185 offset:35040
	v_lshl_add_u64 v[106:107], v[2:3], 0, s[2:3]
	ds_read_b128 v[2:5], v184
	ds_read_b128 v[108:111], v184 offset:32
	s_waitcnt lgkmcnt(1)
	v_mfma_f32_32x32x16_bf16 v[2:17], v[2:5], v[74:77], 0
	s_waitcnt vmcnt(0)
	v_cndmask_b32_e32 v186, 0, v0, vcc
	s_waitcnt lgkmcnt(0)
	v_mfma_f32_32x32x16_bf16 v[2:17], v[108:111], v[78:81], v[2:17]
	ds_read_b128 v[108:111], v184 offset:64
	s_waitcnt lgkmcnt(0)
	v_mfma_f32_32x32x16_bf16 v[2:17], v[108:111], v[70:73], v[2:17]
	ds_read_b128 v[108:111], v184 offset:96
	s_waitcnt lgkmcnt(0)
	v_mfma_f32_32x32x16_bf16 v[2:17], v[108:111], v[66:69], v[2:17]
	ds_read_b128 v[108:111], v184 offset:128
	s_waitcnt lgkmcnt(0)
	v_mfma_f32_32x32x16_bf16 v[2:17], v[108:111], v[62:65], v[2:17]
	ds_read_b128 v[108:111], v184 offset:160
	s_waitcnt lgkmcnt(0)
	v_mfma_f32_32x32x16_bf16 v[2:17], v[108:111], v[58:61], v[2:17]
	ds_read_b128 v[108:111], v184 offset:192
	s_waitcnt lgkmcnt(0)
	v_mfma_f32_32x32x16_bf16 v[2:17], v[108:111], v[54:57], v[2:17]
	ds_read_b128 v[108:111], v184 offset:224
	s_waitcnt lgkmcnt(0)
	v_mfma_f32_32x32x16_bf16 v[2:17], v[108:111], v[50:53], v[2:17]
	v_lshlrev_b32_e32 v108, 1, v92
	v_mov_b32_e32 v109, v1
	s_nop 9
	v_mul_f32_e32 v0, v46, v2
	v_mul_f32_e32 v2, v47, v3
	v_cvt_pk_bf16_f32 v2, v0, v2
	v_mul_f32_e32 v0, v48, v4
	v_mul_f32_e32 v3, v49, v5
	v_cvt_pk_bf16_f32 v3, v0, v3
	v_lshlrev_b32_e32 v0, 1, v88
	v_lshl_add_u64 v[4:5], v[106:107], 0, v[0:1]
	global_store_dwordx2 v[4:5], v[2:3], off
	v_mul_f32_e32 v2, v42, v6
	v_mul_f32_e32 v3, v43, v7
	v_cvt_pk_bf16_f32 v2, v2, v3
	v_mul_f32_e32 v3, v44, v8
	v_mul_f32_e32 v4, v45, v9
	v_cvt_pk_bf16_f32 v3, v3, v4
	v_lshl_add_u64 v[4:5], v[106:107], 0, v[104:105]
	global_store_dwordx2 v[4:5], v[2:3], off
	v_mul_f32_e32 v2, v38, v10
	v_mul_f32_e32 v3, v39, v11
	v_cvt_pk_bf16_f32 v2, v2, v3
	v_mul_f32_e32 v3, v40, v12
	v_mul_f32_e32 v4, v41, v13
	v_cvt_pk_bf16_f32 v3, v3, v4
	v_lshl_add_u64 v[4:5], v[106:107], 0, v[108:109]
	global_store_dwordx2 v[4:5], v[2:3], off
	v_mul_f32_e32 v2, v34, v14
	v_mul_f32_e32 v3, v35, v15
	v_cvt_pk_bf16_f32 v2, v2, v3
	v_mul_f32_e32 v3, v36, v16
	v_mul_f32_e32 v4, v37, v17
	v_cvt_pk_bf16_f32 v3, v3, v4
	v_lshl_add_u64 v[4:5], v[106:107], 0, v[102:103]
	global_store_dwordx2 v[4:5], v[2:3], off
	ds_read_b128 v[2:5], v183
	ds_read_b128 v[110:113], v183 offset:32
	s_waitcnt lgkmcnt(1)
	v_mfma_f32_32x32x16_bf16 v[2:17], v[2:5], v[74:77], 0
	ds_read_b128 v[74:77], v183 offset:64
	s_waitcnt lgkmcnt(1)
	v_mfma_f32_32x32x16_bf16 v[2:17], v[110:113], v[78:81], v[2:17]
	v_lshlrev_b32_e32 v110, 1, v94
	v_mov_b32_e32 v111, v1
	v_lshlrev_b32_e32 v112, 1, v96
	v_mov_b32_e32 v113, v1
	s_waitcnt lgkmcnt(0)
	v_mfma_f32_32x32x16_bf16 v[2:17], v[74:77], v[70:73], v[2:17]
	ds_read_b128 v[70:73], v183 offset:96
	s_waitcnt lgkmcnt(0)
	v_mfma_f32_32x32x16_bf16 v[2:17], v[70:73], v[66:69], v[2:17]
	ds_read_b128 v[66:69], v183 offset:128
	s_waitcnt lgkmcnt(0)
	v_mfma_f32_32x32x16_bf16 v[2:17], v[66:69], v[62:65], v[2:17]
	ds_read_b128 v[62:65], v183 offset:160
	s_waitcnt lgkmcnt(0)
	v_mfma_f32_32x32x16_bf16 v[2:17], v[62:65], v[58:61], v[2:17]
	ds_read_b128 v[58:61], v183 offset:192
	s_waitcnt lgkmcnt(0)
	v_mfma_f32_32x32x16_bf16 v[2:17], v[58:61], v[54:57], v[2:17]
	ds_read_b128 v[54:57], v183 offset:224
	s_waitcnt lgkmcnt(0)
	v_mfma_f32_32x32x16_bf16 v[2:17], v[54:57], v[50:53], v[2:17]
	s_nop 11
	v_mul_f32_e32 v2, v30, v2
	v_mul_f32_e32 v3, v31, v3
	v_cvt_pk_bf16_f32 v2, v2, v3
	v_mul_f32_e32 v3, v32, v4
	v_mul_f32_e32 v4, v33, v5
	v_cvt_pk_bf16_f32 v3, v3, v4
	v_lshl_add_u64 v[4:5], v[106:107], 0, v[110:111]
	global_store_dwordx2 v[4:5], v[2:3], off
	v_mul_f32_e32 v2, v26, v6
	v_mul_f32_e32 v3, v27, v7
	v_cvt_pk_bf16_f32 v2, v2, v3
	v_mul_f32_e32 v3, v28, v8
	v_mul_f32_e32 v4, v29, v9
	v_cvt_pk_bf16_f32 v3, v3, v4
	v_lshl_add_u64 v[4:5], v[106:107], 0, v[112:113]
	global_store_dwordx2 v[4:5], v[2:3], off
	v_mul_f32_e32 v2, v22, v10
	v_mul_f32_e32 v3, v23, v11
	v_cvt_pk_bf16_f32 v2, v2, v3
	v_mul_f32_e32 v3, v24, v12
	v_mul_f32_e32 v4, v25, v13
	v_add_u32_e32 v12, s1, v83
	v_cvt_pk_bf16_f32 v3, v3, v4
	v_lshl_add_u64 v[4:5], v[106:107], 0, v[114:115]
	v_min_i32_e32 v12, 3, v12
	global_store_dwordx2 v[4:5], v[2:3], off
	v_mul_f32_e32 v2, v18, v14
	v_mul_f32_e32 v3, v19, v15
	v_add_u32_e32 v12, 1, v12
	v_cvt_pk_bf16_f32 v2, v2, v3
	v_mul_f32_e32 v3, v20, v16
	v_mul_f32_e32 v4, v21, v17
	v_cvt_f32_i32_e32 v12, v12
	v_cvt_pk_bf16_f32 v3, v3, v4
	v_lshlrev_b32_e32 v4, 1, v100
	v_mov_b32_e32 v5, v1
	v_lshl_add_u64 v[4:5], v[106:107], 0, v[4:5]
	global_store_dwordx2 v[4:5], v[2:3], off
	v_lshlrev_b32_e32 v2, 16, v211
	v_and_b32_e32 v4, 0xffff0000, v211
	v_add_f32_e32 v3, 0, v2
	v_add_f32_e32 v5, 0, v4
	v_lshlrev_b32_e32 v6, 16, v212
	v_and_b32_e32 v7, 0xffff0000, v212
	v_rcp_iflag_f32_e32 v12, v12
	v_add_f32_e32 v3, v3, v6
	v_add_f32_e32 v5, v5, v7
	v_lshlrev_b32_e32 v8, 16, v213
	v_and_b32_e32 v9, 0xffff0000, v213
	v_add_f32_e32 v3, v3, v8
	v_add_f32_e32 v5, v5, v9
	v_lshlrev_b32_e32 v10, 16, v214
	v_and_b32_e32 v11, 0xffff0000, v214
	v_add_f32_e32 v3, v3, v10
	v_add_f32_e32 v5, v5, v11
	v_fma_f32 v13, v12, v3, -v10
	v_fma_f32 v12, v12, v5, -v11
	v_cvt_pk_bf16_f32 v12, v13, v12
	s_waitcnt lgkmcnt(0)
	s_barrier
	ds_write_b32 v116, v12 offset:34816
	v_add_u32_e32 v12, s1, v127
	v_min_i32_e32 v12, 3, v12
	v_add_u32_e32 v12, 1, v12
	v_cvt_f32_i32_e32 v12, v12
	v_sub_f32_e32 v2, v3, v2
	v_sub_f32_e32 v3, v5, v4
	v_lshlrev_b32_e32 v4, 16, v191
	v_rcp_iflag_f32_e32 v12, v12
	v_and_b32_e32 v5, 0xffff0000, v191
	v_add_f32_e32 v2, v2, v4
	v_add_f32_e32 v3, v3, v5
	v_fma_f32 v13, v12, v2, -v4
	v_fma_f32 v12, v12, v3, -v5
	v_cvt_pk_bf16_f32 v12, v13, v12
	ds_write_b32 v117, v12 offset:34816
	v_add_u32_e32 v12, s1, v128
	v_min_i32_e32 v12, 3, v12
	v_add_u32_e32 v12, 1, v12
	v_cvt_f32_i32_e32 v12, v12
	v_sub_f32_e32 v2, v2, v6
	v_sub_f32_e32 v3, v3, v7
	v_lshlrev_b32_e32 v6, 16, v210
	v_rcp_iflag_f32_e32 v12, v12
	v_and_b32_e32 v7, 0xffff0000, v210
	v_add_f32_e32 v2, v2, v6
	v_add_f32_e32 v3, v3, v7
	v_fma_f32 v13, v12, v2, -v6
	v_fma_f32 v12, v12, v3, -v7
	v_cvt_pk_bf16_f32 v12, v13, v12
	ds_write_b32 v168, v12 offset:34816
	v_add_u32_e32 v12, s1, v129
	v_min_i32_e32 v12, 3, v12
	v_add_u32_e32 v12, 1, v12
	v_cvt_f32_i32_e32 v12, v12
	v_sub_f32_e32 v2, v2, v8
	v_sub_f32_e32 v3, v3, v9
	v_lshlrev_b32_e32 v8, 16, v209
	v_rcp_iflag_f32_e32 v12, v12
	v_and_b32_e32 v9, 0xffff0000, v209
	v_add_f32_e32 v2, v2, v8
	v_add_f32_e32 v3, v3, v9
	v_fma_f32 v13, v12, v2, -v8
	v_fma_f32 v12, v12, v3, -v9
	v_cvt_pk_bf16_f32 v12, v13, v12
	ds_write_b32 v169, v12 offset:34816
	v_add_u32_e32 v12, s1, v130
	v_min_i32_e32 v12, 3, v12
	v_add_u32_e32 v12, 1, v12
	v_cvt_f32_i32_e32 v12, v12
	v_sub_f32_e32 v2, v2, v10
	v_sub_f32_e32 v3, v3, v11
	v_lshlrev_b32_e32 v10, 16, v208
	v_rcp_iflag_f32_e32 v12, v12
	v_and_b32_e32 v11, 0xffff0000, v208
	v_add_f32_e32 v2, v2, v10
	v_add_f32_e32 v3, v3, v11
	v_fma_f32 v13, v12, v2, -v10
	v_fma_f32 v12, v12, v3, -v11
	v_cvt_pk_bf16_f32 v12, v13, v12
	ds_write_b32 v170, v12 offset:34816
	v_add_u32_e32 v12, s1, v131
	v_min_i32_e32 v12, 3, v12
	v_add_u32_e32 v12, 1, v12
	v_cvt_f32_i32_e32 v12, v12
	v_sub_f32_e32 v2, v2, v4
	v_sub_f32_e32 v3, v3, v5
	v_lshlrev_b32_e32 v4, 16, v207
	v_rcp_iflag_f32_e32 v12, v12
	v_and_b32_e32 v5, 0xffff0000, v207
	v_add_f32_e32 v2, v2, v4
	v_add_f32_e32 v3, v3, v5
	v_fma_f32 v13, v12, v2, -v4
	v_fma_f32 v12, v12, v3, -v5
	v_cvt_pk_bf16_f32 v12, v13, v12
	ds_write_b32 v171, v12 offset:34816
	v_add_u32_e32 v12, s1, v132
	v_min_i32_e32 v12, 3, v12
	v_add_u32_e32 v12, 1, v12
	v_cvt_f32_i32_e32 v12, v12
	v_sub_f32_e32 v2, v2, v6
	v_sub_f32_e32 v3, v3, v7
	v_lshlrev_b32_e32 v6, 16, v206
	v_rcp_iflag_f32_e32 v12, v12
	v_and_b32_e32 v7, 0xffff0000, v206
	v_add_f32_e32 v2, v2, v6
	v_add_f32_e32 v3, v3, v7
	v_fma_f32 v13, v12, v2, -v6
	v_fma_f32 v12, v12, v3, -v7
	v_cvt_pk_bf16_f32 v12, v13, v12
	ds_write_b32 v172, v12 offset:34816
	v_add_u32_e32 v12, s1, v133
	v_min_i32_e32 v12, 3, v12
	v_add_u32_e32 v12, 1, v12
	v_cvt_f32_i32_e32 v12, v12
	v_sub_f32_e32 v2, v2, v8
	v_sub_f32_e32 v3, v3, v9
	v_lshlrev_b32_e32 v8, 16, v205
	v_rcp_iflag_f32_e32 v12, v12
	v_and_b32_e32 v9, 0xffff0000, v205
	v_add_f32_e32 v2, v2, v8
	v_add_f32_e32 v3, v3, v9
	v_fma_f32 v13, v12, v2, -v8
	v_fma_f32 v12, v12, v3, -v9
	v_cvt_pk_bf16_f32 v12, v13, v12
	ds_write_b32 v173, v12 offset:34816
	v_add_u32_e32 v12, s1, v134
	v_min_i32_e32 v12, 3, v12
	v_add_u32_e32 v12, 1, v12
	v_cvt_f32_i32_e32 v12, v12
	v_sub_f32_e32 v2, v2, v10
	v_sub_f32_e32 v3, v3, v11
	v_lshlrev_b32_e32 v10, 16, v204
	v_rcp_iflag_f32_e32 v12, v12
	v_and_b32_e32 v11, 0xffff0000, v204
	v_add_f32_e32 v2, v2, v10
	v_add_f32_e32 v3, v3, v11
	v_fma_f32 v13, v12, v2, -v10
	v_fma_f32 v12, v12, v3, -v11
	v_cvt_pk_bf16_f32 v12, v13, v12
	ds_write_b32 v174, v12 offset:34816
	v_add_u32_e32 v12, s1, v135
	v_min_i32_e32 v12, 3, v12
	v_add_u32_e32 v12, 1, v12
	v_cvt_f32_i32_e32 v12, v12
	v_sub_f32_e32 v2, v2, v4
	v_sub_f32_e32 v3, v3, v5
	v_lshlrev_b32_e32 v4, 16, v192
	v_rcp_iflag_f32_e32 v12, v12
	v_and_b32_e32 v5, 0xffff0000, v192
	v_add_f32_e32 v2, v2, v4
	v_add_f32_e32 v3, v3, v5
	v_fma_f32 v13, v12, v2, -v4
	v_fma_f32 v12, v12, v3, -v5
	v_cvt_pk_bf16_f32 v12, v13, v12
	ds_write_b32 v175, v12 offset:34816
	v_add_u32_e32 v12, s1, v136
	v_min_i32_e32 v12, 3, v12
	v_add_u32_e32 v12, 1, v12
	v_cvt_f32_i32_e32 v12, v12
	v_sub_f32_e32 v2, v2, v6
	v_sub_f32_e32 v3, v3, v7
	v_lshlrev_b32_e32 v6, 16, v190
	v_rcp_iflag_f32_e32 v12, v12
	v_and_b32_e32 v7, 0xffff0000, v190
	v_add_f32_e32 v2, v2, v6
	v_add_f32_e32 v3, v3, v7
	v_fma_f32 v13, v12, v2, -v6
	v_fma_f32 v12, v12, v3, -v7
	v_cvt_pk_bf16_f32 v12, v13, v12
	ds_write_b32 v176, v12 offset:34816
	v_add_u32_e32 v12, s1, v137
	v_min_i32_e32 v12, 3, v12
	v_add_u32_e32 v12, 1, v12
	v_cvt_f32_i32_e32 v12, v12
	v_sub_f32_e32 v2, v2, v8
	v_sub_f32_e32 v3, v3, v9
	v_lshlrev_b32_e32 v8, 16, v189
	v_rcp_iflag_f32_e32 v12, v12
	v_and_b32_e32 v9, 0xffff0000, v189
	v_add_f32_e32 v2, v2, v8
	v_add_f32_e32 v3, v3, v9
	v_fma_f32 v13, v12, v2, -v8
	v_fma_f32 v12, v12, v3, -v9
	v_cvt_pk_bf16_f32 v12, v13, v12
	ds_write_b32 v177, v12 offset:34816
	v_add_u32_e32 v12, s1, v138
	v_min_i32_e32 v12, 3, v12
	v_add_u32_e32 v12, 1, v12
	v_cvt_f32_i32_e32 v12, v12
	v_sub_f32_e32 v2, v2, v10
	v_lshlrev_b32_e32 v10, 16, v188
	v_sub_f32_e32 v3, v3, v11
	v_rcp_iflag_f32_e32 v12, v12
	v_and_b32_e32 v11, 0xffff0000, v188
	v_add_f32_e32 v2, v2, v10
	v_add_f32_e32 v3, v3, v11
	v_fma_f32 v10, v12, v2, -v10
	v_fma_f32 v11, v12, v3, -v11
	v_cvt_pk_bf16_f32 v10, v10, v11
	ds_write_b32 v178, v10 offset:34816
	v_add_u32_e32 v10, s1, v139
	v_min_i32_e32 v10, 3, v10
	v_add_u32_e32 v10, 1, v10
	v_cvt_f32_i32_e32 v10, v10
	v_sub_f32_e32 v2, v2, v4
	v_lshlrev_b32_e32 v4, 16, v187
	v_add_f32_e32 v2, v2, v4
	v_rcp_iflag_f32_e32 v10, v10
	v_sub_f32_e32 v3, v3, v5
	v_and_b32_e32 v5, 0xffff0000, v187
	v_add_f32_e32 v3, v3, v5
	v_fma_f32 v4, v10, v2, -v4
	v_sub_f32_e32 v2, v2, v6
	v_add_u32_e32 v6, s1, v140
	v_min_i32_e32 v6, 3, v6
	v_add_u32_e32 v6, 1, v6
	v_cvt_f32_i32_e32 v6, v6
	v_fma_f32 v5, v10, v3, -v5
	v_cvt_pk_bf16_f32 v4, v4, v5
	ds_write_b32 v179, v4 offset:34816
	v_rcp_iflag_f32_e32 v6, v6
	v_sub_f32_e32 v3, v3, v7
	v_lshlrev_b32_e32 v4, 16, v186
	v_and_b32_e32 v5, 0xffff0000, v186
	v_add_f32_e32 v2, v2, v4
	v_add_f32_e32 v3, v3, v5
	v_fma_f32 v4, v6, v2, -v4
	v_fma_f32 v5, v6, v3, -v5
	v_add_u32_e32 v6, s1, v141
	v_min_i32_e32 v6, 3, v6
	v_add_u32_e32 v6, 1, v6
	v_cvt_f32_i32_e32 v6, v6
	v_cvt_pk_bf16_f32 v4, v4, v5
	ds_write_b32 v180, v4 offset:34816
	v_sub_f32_e32 v2, v2, v8
	v_rcp_iflag_f32_e32 v6, v6
	v_lshlrev_b32_e32 v4, 16, v182
	v_sub_f32_e32 v3, v3, v9
	v_and_b32_e32 v5, 0xffff0000, v182
	v_add_f32_e32 v2, v2, v4
	v_add_f32_e32 v3, v3, v5
	v_fma_f32 v2, v6, v2, -v4
	v_fma_f32 v3, v6, v3, -v5
	v_cvt_pk_bf16_f32 v2, v2, v3
	ds_write_b32 v181, v2 offset:34816
	v_add_u32_e32 v2, s0, v142
	v_ashrrev_i32_e32 v3, 31, v2
	v_lshlrev_b64 v[2:3], 12, v[2:3]
	s_waitcnt lgkmcnt(0)
	s_barrier
	v_lshl_add_u64 v[2:3], s[70:71], 0, v[2:3]
	ds_read_b128 v[74:77], v185 offset:34816
	ds_read_b128 v[78:81], v185 offset:34848
	ds_read_b128 v[70:73], v185 offset:34880
	ds_read_b128 v[66:69], v185 offset:34912
	ds_read_b128 v[62:65], v185 offset:34944
	ds_read_b128 v[58:61], v185 offset:34976
	ds_read_b128 v[54:57], v185 offset:35008
	ds_read_b128 v[50:53], v185 offset:35040
	v_lshl_add_u64 v[106:107], v[2:3], 0, s[2:3]
	ds_read_b128 v[2:5], v184
	ds_read_b128 v[168:171], v184 offset:32
	s_waitcnt lgkmcnt(1)
	v_mfma_f32_32x32x16_bf16 v[2:17], v[2:5], v[74:77], 0
	s_waitcnt lgkmcnt(0)
	v_mfma_f32_32x32x16_bf16 v[2:17], v[168:171], v[78:81], v[2:17]
	ds_read_b128 v[168:171], v184 offset:64
	s_waitcnt lgkmcnt(0)
	v_mfma_f32_32x32x16_bf16 v[2:17], v[168:171], v[70:73], v[2:17]
	ds_read_b128 v[168:171], v184 offset:96
	s_waitcnt lgkmcnt(0)
	v_mfma_f32_32x32x16_bf16 v[2:17], v[168:171], v[66:69], v[2:17]
	ds_read_b128 v[168:171], v184 offset:128
	s_waitcnt lgkmcnt(0)
	v_mfma_f32_32x32x16_bf16 v[2:17], v[168:171], v[62:65], v[2:17]
	ds_read_b128 v[168:171], v184 offset:160
	s_waitcnt lgkmcnt(0)
	v_mfma_f32_32x32x16_bf16 v[2:17], v[168:171], v[58:61], v[2:17]
	ds_read_b128 v[168:171], v184 offset:192
	s_waitcnt lgkmcnt(0)
	v_mfma_f32_32x32x16_bf16 v[2:17], v[168:171], v[54:57], v[2:17]
	ds_read_b128 v[168:171], v184 offset:224
	s_waitcnt lgkmcnt(0)
	v_mfma_f32_32x32x16_bf16 v[2:17], v[168:171], v[50:53], v[2:17]
	s_nop 11
	v_mul_f32_e32 v2, v46, v2
	v_mul_f32_e32 v3, v47, v3
	v_cvt_pk_bf16_f32 v2, v2, v3
	v_mul_f32_e32 v3, v48, v4
	v_mul_f32_e32 v4, v49, v5
	v_cvt_pk_bf16_f32 v3, v3, v4
	v_lshl_add_u64 v[4:5], v[106:107], 0, v[0:1]
	global_store_dwordx2 v[4:5], v[2:3], off
	v_mul_f32_e32 v0, v42, v6
	v_mul_f32_e32 v2, v43, v7
	v_mul_f32_e32 v3, v45, v9
	v_cvt_pk_bf16_f32 v2, v0, v2
	v_mul_f32_e32 v0, v44, v8
	v_cvt_pk_bf16_f32 v3, v0, v3
	v_lshl_add_u64 v[4:5], v[106:107], 0, v[104:105]
	global_store_dwordx2 v[4:5], v[2:3], off
	v_mul_f32_e32 v0, v38, v10
	v_mul_f32_e32 v2, v39, v11
	v_mul_f32_e32 v3, v41, v13
	v_cvt_pk_bf16_f32 v2, v0, v2
	v_mul_f32_e32 v0, v40, v12
	v_cvt_pk_bf16_f32 v3, v0, v3
	v_lshl_add_u64 v[4:5], v[106:107], 0, v[108:109]
	global_store_dwordx2 v[4:5], v[2:3], off
	v_mul_f32_e32 v0, v34, v14
	v_mul_f32_e32 v2, v35, v15
	v_mul_f32_e32 v3, v37, v17
	v_lshl_add_u64 v[4:5], v[106:107], 0, v[102:103]
	v_cvt_pk_bf16_f32 v2, v0, v2
	v_mul_f32_e32 v0, v36, v16
	v_cvt_pk_bf16_f32 v3, v0, v3
	global_store_dwordx2 v[4:5], v[2:3], off
	ds_read_b128 v[2:5], v183
	ds_read_b128 v[34:37], v183 offset:32
	s_waitcnt lgkmcnt(1)
	v_mfma_f32_32x32x16_bf16 v[2:17], v[2:5], v[74:77], 0
	s_waitcnt lgkmcnt(0)
	v_mfma_f32_32x32x16_bf16 v[2:17], v[34:37], v[78:81], v[2:17]
	ds_read_b128 v[34:37], v183 offset:64
	s_waitcnt lgkmcnt(0)
	v_mfma_f32_32x32x16_bf16 v[2:17], v[34:37], v[70:73], v[2:17]
	ds_read_b128 v[34:37], v183 offset:96
	s_waitcnt lgkmcnt(0)
	v_mfma_f32_32x32x16_bf16 v[2:17], v[34:37], v[66:69], v[2:17]
	ds_read_b128 v[34:37], v183 offset:128
	s_waitcnt lgkmcnt(0)
	v_mfma_f32_32x32x16_bf16 v[2:17], v[34:37], v[62:65], v[2:17]
	ds_read_b128 v[34:37], v183 offset:160
	s_waitcnt lgkmcnt(0)
	v_mfma_f32_32x32x16_bf16 v[2:17], v[34:37], v[58:61], v[2:17]
	ds_read_b128 v[34:37], v183 offset:192
	s_waitcnt lgkmcnt(0)
	v_mfma_f32_32x32x16_bf16 v[2:17], v[34:37], v[54:57], v[2:17]
	ds_read_b128 v[34:37], v183 offset:224
	s_waitcnt lgkmcnt(0)
	v_mfma_f32_32x32x16_bf16 v[2:17], v[34:37], v[50:53], v[2:17]
	s_nop 11
	v_mul_f32_e32 v0, v30, v2
	v_mul_f32_e32 v2, v31, v3
	v_mul_f32_e32 v3, v33, v5
	v_cvt_pk_bf16_f32 v2, v0, v2
	v_mul_f32_e32 v0, v32, v4
	v_cvt_pk_bf16_f32 v3, v0, v3
	v_lshl_add_u64 v[4:5], v[106:107], 0, v[110:111]
	global_store_dwordx2 v[4:5], v[2:3], off
	v_mul_f32_e32 v0, v26, v6
	v_mul_f32_e32 v2, v27, v7
	v_mul_f32_e32 v3, v29, v9
	v_cvt_pk_bf16_f32 v2, v0, v2
	v_mul_f32_e32 v0, v28, v8
	v_cvt_pk_bf16_f32 v3, v0, v3
	v_lshl_add_u64 v[4:5], v[106:107], 0, v[112:113]
	global_store_dwordx2 v[4:5], v[2:3], off
	v_mul_f32_e32 v0, v22, v10
	v_mul_f32_e32 v2, v23, v11
	v_mul_f32_e32 v3, v25, v13
	v_cvt_pk_bf16_f32 v2, v0, v2
	v_mul_f32_e32 v0, v24, v12
	v_cvt_pk_bf16_f32 v3, v0, v3
	v_lshl_add_u64 v[4:5], v[106:107], 0, v[114:115]
	global_store_dwordx2 v[4:5], v[2:3], off
	v_mul_f32_e32 v0, v18, v14
	v_mul_f32_e32 v2, v19, v15
	v_mul_f32_e32 v3, v21, v17
	v_cvt_pk_bf16_f32 v2, v0, v2
	v_mul_f32_e32 v0, v20, v16
	v_cvt_pk_bf16_f32 v3, v0, v3

.LBB0_215:
	s_or_b64 exec, exec, s[84:85]
	s_waitcnt vmcnt(38)
	v_cndmask_b32_e64 v4, 0, v4, s[8:9]
	s_waitcnt vmcnt(37)
	v_cndmask_b32_e64 v5, 0, v5, s[10:11]
	v_lshlrev_b32_e32 v71, 16, v4
	v_and_b32_e32 v72, 0xffff0000, v4
	s_waitcnt vmcnt(28)
	v_cndmask_b32_e64 v70, 0, v51, s[2:3]
	v_cndmask_b32_e64 v7, 0, v7, s[12:13]
	v_add_f32_e32 v51, 0, v71
	v_add_f32_e32 v4, 0, v72
	v_lshlrev_b32_e32 v73, 16, v5
	v_and_b32_e32 v74, 0xffff0000, v5
	v_cndmask_b32_e64 v8, 0, v8, s[14:15]
	v_add_f32_e32 v51, v51, v73
	v_add_f32_e32 v4, v4, v74
	v_lshlrev_b32_e32 v75, 16, v7
	v_and_b32_e32 v76, 0xffff0000, v7
	v_cndmask_b32_e64 v10, 0, v10, s[16:17]
	v_add_f32_e32 v5, v51, v75
	v_add_f32_e32 v4, v4, v76
	v_lshlrev_b32_e32 v77, 16, v8
	v_and_b32_e32 v78, 0xffff0000, v8
	v_cndmask_b32_e64 v11, 0, v11, s[18:19]
	v_add_f32_e32 v5, v5, v77
	v_add_f32_e32 v4, v4, v78
	v_lshlrev_b32_e32 v79, 16, v10
	v_and_b32_e32 v80, 0xffff0000, v10
	v_cndmask_b32_e64 v13, 0, v13, s[20:21]
	v_add_f32_e32 v5, v5, v79
	v_add_f32_e32 v4, v4, v80
	v_lshlrev_b32_e32 v81, 16, v11
	v_and_b32_e32 v103, 0xffff0000, v11
	s_waitcnt vmcnt(27)
	v_cndmask_b32_e64 v69, 0, v52, s[6:7]
	v_cndmask_b32_e64 v14, 0, v14, s[22:23]
	v_add_f32_e32 v5, v5, v81
	v_add_f32_e32 v4, v4, v103
	v_lshlrev_b32_e32 v104, 16, v13
	v_and_b32_e32 v105, 0xffff0000, v13
	s_waitcnt vmcnt(8)
	v_cndmask_b32_e64 v0, 0, v65, s[62:63]
	v_cndmask_b32_e64 v65, 0, v57, s[68:69]
	v_cndmask_b32_e64 v66, 0, v56, s[28:29]
	v_cndmask_b32_e32 v16, 0, v16, vcc
	v_add_f32_e32 v5, v5, v104
	v_add_f32_e32 v4, v4, v105
	v_lshlrev_b32_e32 v56, 16, v14
	v_and_b32_e32 v57, 0xffff0000, v14
	v_lshlrev_b32_e32 v13, 16, v69
	v_and_b32_e32 v14, 0xffff0000, v69
	v_add_u32_e32 v69, s95, v83
	v_cndmask_b32_e64 v67, 0, v54, s[26:27]
	v_cndmask_b32_e64 v68, 0, v53, s[24:25]
	v_cndmask_b32_e64 v17, 0, v17, s[0:1]
	v_add_f32_e32 v5, v5, v56
	v_add_f32_e32 v4, v4, v57
	v_lshlrev_b32_e32 v53, 16, v16
	v_and_b32_e32 v54, 0xffff0000, v16
	v_min_i32_e32 v69, 15, v69
	v_add_f32_e32 v5, v5, v53
	v_add_f32_e32 v4, v4, v54
	v_lshlrev_b32_e32 v51, 16, v17
	v_and_b32_e32 v52, 0xffff0000, v17
	v_add_u32_e32 v69, 1, v69
	v_add_f32_e32 v5, v5, v51
	v_add_f32_e32 v4, v4, v52
	v_lshlrev_b32_e32 v16, 16, v70
	v_and_b32_e32 v17, 0xffff0000, v70
	v_cvt_f32_i32_e32 v69, v69
	v_add_f32_e32 v5, v5, v16
	v_add_f32_e32 v4, v4, v17
	v_add_f32_e32 v5, v5, v13
	v_add_f32_e32 v4, v4, v14
	v_lshlrev_b32_e32 v10, 16, v68
	v_and_b32_e32 v11, 0xffff0000, v68
	v_add_f32_e32 v5, v5, v10
	v_add_f32_e32 v4, v4, v11
	v_lshlrev_b32_e32 v7, 16, v67
	v_and_b32_e32 v8, 0xffff0000, v67
	v_add_f32_e32 v5, v5, v7
	v_add_f32_e32 v67, v4, v8
	v_lshlrev_b32_e32 v4, 16, v66
	v_rcp_iflag_f32_e32 v69, v69
	v_add_f32_e32 v68, v5, v4
	v_and_b32_e32 v5, 0xffff0000, v66
	v_add_f32_e32 v66, v67, v5
	v_lshlrev_b32_e32 v67, 16, v65
	v_and_b32_e32 v65, 0xffff0000, v65
	v_add_f32_e32 v66, v66, v65
	v_add_f32_e32 v68, v68, v67
	v_fma_f32 v65, v69, v66, -v65
	v_fma_f32 v67, v69, v68, -v67
	v_cvt_pk_bf16_f32 v65, v67, v65
	v_add_u32_e32 v116, 0, v145
	s_waitcnt lgkmcnt(0)
	s_barrier
	ds_write_b32 v116, v65 offset:34816
	v_sub_f32_e32 v65, v68, v71
	v_add_u32_e32 v68, s95, v127
	v_min_i32_e32 v68, 15, v68
	v_add_u32_e32 v68, 1, v68
	v_cvt_f32_i32_e32 v68, v68
	v_cndmask_b32_e64 v59, v59, 0, s[34:35]
	v_sub_f32_e32 v66, v66, v72
	v_lshlrev_b32_e32 v67, 16, v59
	v_rcp_iflag_f32_e32 v68, v68
	v_and_b32_e32 v59, 0xffff0000, v59
	v_add_f32_e32 v65, v65, v67
	v_add_f32_e32 v66, v66, v59
	v_fma_f32 v67, v68, v65, -v67
	v_fma_f32 v59, v68, v66, -v59
	v_cvt_pk_bf16_f32 v59, v67, v59
	v_add_u32_e32 v67, s95, v128
	v_min_i32_e32 v67, 15, v67
	v_add_u32_e32 v67, 1, v67
	v_cvt_f32_i32_e32 v67, v67
	v_cndmask_b32_e64 v60, 0, v60, s[36:37]
	v_add_u32_e32 v117, 0, v146
	ds_write_b32 v117, v59 offset:34816
	v_rcp_iflag_f32_e32 v67, v67
	v_sub_f32_e32 v59, v65, v73
	v_sub_f32_e32 v65, v66, v74
	v_lshlrev_b32_e32 v66, 16, v60
	v_and_b32_e32 v60, 0xffff0000, v60
	v_add_f32_e32 v59, v59, v66
	v_add_f32_e32 v65, v65, v60
	v_fma_f32 v66, v67, v59, -v66
	v_fma_f32 v60, v67, v65, -v60
	v_cvt_pk_bf16_f32 v60, v66, v60
	v_add_u32_e32 v66, s95, v129
	v_min_i32_e32 v66, 15, v66
	v_add_u32_e32 v66, 1, v66
	v_cvt_f32_i32_e32 v66, v66
	v_cndmask_b32_e64 v61, 0, v61, s[38:39]
	v_add_u32_e32 v168, 0, v147
	ds_write_b32 v168, v60 offset:34816
	v_rcp_iflag_f32_e32 v66, v66
	v_sub_f32_e32 v59, v59, v75
	v_sub_f32_e32 v60, v65, v76
	v_lshlrev_b32_e32 v65, 16, v61
	v_and_b32_e32 v61, 0xffff0000, v61
	v_add_f32_e32 v59, v59, v65
	v_add_f32_e32 v60, v60, v61
	v_fma_f32 v65, v66, v59, -v65
	v_fma_f32 v61, v66, v60, -v61
	v_cvt_pk_bf16_f32 v61, v65, v61
	v_add_u32_e32 v65, s95, v130
	v_min_i32_e32 v65, 15, v65
	v_add_u32_e32 v65, 1, v65
	v_cvt_f32_i32_e32 v65, v65
	v_cndmask_b32_e64 v62, 0, v62, s[40:41]
	v_add_u32_e32 v169, 0, v148
	ds_write_b32 v169, v61 offset:34816
	v_rcp_iflag_f32_e32 v65, v65
	v_sub_f32_e32 v59, v59, v77
	v_lshlrev_b32_e32 v61, 16, v62
	v_sub_f32_e32 v60, v60, v78
	v_and_b32_e32 v62, 0xffff0000, v62
	v_add_f32_e32 v59, v59, v61
	v_add_f32_e32 v60, v60, v62
	v_fma_f32 v61, v65, v59, -v61
	v_cndmask_b32_e64 v63, 0, v63, s[42:43]
	v_fma_f32 v62, v65, v60, -v62
	v_cvt_pk_bf16_f32 v61, v61, v62
	v_add_u32_e32 v170, 0, v149
	ds_write_b32 v170, v61 offset:34816
	v_lshlrev_b32_e32 v61, 16, v63
	v_and_b32_e32 v62, 0xffff0000, v63
	v_add_u32_e32 v63, s95, v131
	v_min_i32_e32 v63, 15, v63
	v_add_u32_e32 v63, 1, v63
	v_cvt_f32_i32_e32 v63, v63
	v_sub_f32_e32 v59, v59, v79
	v_sub_f32_e32 v60, v60, v80
	v_add_f32_e32 v59, v59, v61
	v_rcp_iflag_f32_e32 v63, v63
	v_add_f32_e32 v60, v60, v62
	v_cndmask_b32_e64 v64, 0, v64, s[44:45]
	v_add_u32_e32 v171, 0, v150
	v_fma_f32 v61, v63, v59, -v61
	v_fma_f32 v62, v63, v60, -v62
	v_add_u32_e32 v63, s95, v132
	v_min_i32_e32 v63, 15, v63
	v_add_u32_e32 v63, 1, v63
	v_cvt_f32_i32_e32 v63, v63
	v_cvt_pk_bf16_f32 v61, v61, v62
	ds_write_b32 v171, v61 offset:34816
	v_sub_f32_e32 v59, v59, v81
	v_rcp_iflag_f32_e32 v63, v63
	v_sub_f32_e32 v60, v60, v103
	v_lshlrev_b32_e32 v61, 16, v64
	v_and_b32_e32 v62, 0xffff0000, v64
	v_add_f32_e32 v59, v59, v61
	v_add_f32_e32 v60, v60, v62
	v_fma_f32 v61, v63, v59, -v61
	v_fma_f32 v62, v63, v60, -v62
	v_cvt_pk_bf16_f32 v61, v61, v62
	v_add_u32_e32 v62, s95, v133
	v_min_i32_e32 v62, 15, v62
	v_add_u32_e32 v62, 1, v62
	v_cvt_f32_i32_e32 v62, v62
	v_cndmask_b32_e64 v58, 0, v58, s[46:47]
	v_add_u32_e32 v172, 0, v151
	ds_write_b32 v172, v61 offset:34816
	v_rcp_iflag_f32_e32 v62, v62
	v_sub_f32_e32 v59, v59, v104
	v_lshlrev_b32_e32 v61, 16, v58
	v_add_f32_e32 v59, v59, v61
	v_fma_f32 v61, v62, v59, -v61
	v_sub_f32_e32 v56, v59, v56
	v_add_u32_e32 v59, s95, v134
	v_min_i32_e32 v59, 15, v59
	v_add_u32_e32 v59, 1, v59
	v_cvt_f32_i32_e32 v59, v59
	v_sub_f32_e32 v60, v60, v105
	v_and_b32_e32 v58, 0xffff0000, v58
	v_add_f32_e32 v60, v60, v58
	v_fma_f32 v58, v62, v60, -v58
	v_rcp_iflag_f32_e32 v59, v59
	v_cndmask_b32_e64 v55, 0, v55, s[48:49]
	v_cvt_pk_bf16_f32 v58, v61, v58
	v_add_u32_e32 v173, 0, v152
	ds_write_b32 v173, v58 offset:34816
	v_lshlrev_b32_e32 v58, 16, v55
	v_add_f32_e32 v56, v56, v58
	v_fma_f32 v58, v59, v56, -v58
	v_sub_f32_e32 v53, v56, v53
	v_add_u32_e32 v56, s95, v135
	v_min_i32_e32 v56, 15, v56
	v_add_u32_e32 v56, 1, v56
	v_cvt_f32_i32_e32 v56, v56
	v_sub_f32_e32 v57, v60, v57
	v_and_b32_e32 v55, 0xffff0000, v55
	v_add_f32_e32 v57, v57, v55
	v_fma_f32 v55, v59, v57, -v55
	v_rcp_iflag_f32_e32 v56, v56
	v_cndmask_b32_e64 v50, 0, v50, s[50:51]
	v_cvt_pk_bf16_f32 v55, v58, v55
	v_add_u32_e32 v174, 0, v153
	ds_write_b32 v174, v55 offset:34816
	v_sub_f32_e32 v54, v57, v54
	v_lshlrev_b32_e32 v55, 16, v50
	v_and_b32_e32 v50, 0xffff0000, v50
	v_add_f32_e32 v54, v54, v50
	v_add_f32_e32 v53, v53, v55
	v_fma_f32 v50, v56, v54, -v50
	v_fma_f32 v55, v56, v53, -v55
	v_cvt_pk_bf16_f32 v50, v55, v50
	v_add_u32_e32 v175, 0, v154
	ds_write_b32 v175, v50 offset:34816
	v_sub_f32_e32 v50, v53, v51
	v_add_u32_e32 v53, s95, v136
	v_min_i32_e32 v53, 15, v53
	v_add_u32_e32 v53, 1, v53
	v_cvt_f32_i32_e32 v53, v53
	v_cndmask_b32_e64 v15, 0, v15, s[52:53]
	v_sub_f32_e32 v51, v54, v52
	v_lshlrev_b32_e32 v52, 16, v15
	v_rcp_iflag_f32_e32 v53, v53
	v_and_b32_e32 v15, 0xffff0000, v15
	v_add_f32_e32 v51, v51, v15
	v_add_f32_e32 v50, v50, v52
	v_fma_f32 v15, v53, v51, -v15
	v_fma_f32 v52, v53, v50, -v52
	v_cvt_pk_bf16_f32 v15, v52, v15
	v_add_u32_e32 v176, 0, v155
	ds_write_b32 v176, v15 offset:34816
	v_sub_f32_e32 v15, v50, v16
	v_add_u32_e32 v50, s95, v137
	v_min_i32_e32 v50, 15, v50
	v_add_u32_e32 v50, 1, v50
	v_cvt_f32_i32_e32 v50, v50
	v_cndmask_b32_e64 v12, 0, v12, s[54:55]
	v_sub_f32_e32 v16, v51, v17
	v_lshlrev_b32_e32 v17, 16, v12
	v_rcp_iflag_f32_e32 v50, v50
	v_and_b32_e32 v12, 0xffff0000, v12
	v_add_f32_e32 v16, v16, v12
	v_add_f32_e32 v15, v15, v17
	v_fma_f32 v12, v50, v16, -v12
	v_fma_f32 v17, v50, v15, -v17
	v_cvt_pk_bf16_f32 v12, v17, v12
	v_add_u32_e32 v177, 0, v156
	ds_write_b32 v177, v12 offset:34816
	v_sub_f32_e32 v12, v15, v13
	v_add_u32_e32 v15, s95, v138
	v_min_i32_e32 v15, 15, v15
	v_add_u32_e32 v15, 1, v15
	v_cvt_f32_i32_e32 v15, v15
	v_cndmask_b32_e64 v9, 0, v9, s[56:57]
	v_sub_f32_e32 v13, v16, v14
	v_lshlrev_b32_e32 v14, 16, v9
	v_rcp_iflag_f32_e32 v15, v15
	v_and_b32_e32 v9, 0xffff0000, v9
	v_add_f32_e32 v13, v13, v9
	v_add_f32_e32 v12, v12, v14
	v_fma_f32 v9, v15, v13, -v9
	v_fma_f32 v14, v15, v12, -v14
	v_cvt_pk_bf16_f32 v9, v14, v9
	v_add_u32_e32 v178, 0, v157
	ds_write_b32 v178, v9 offset:34816
	v_sub_f32_e32 v9, v12, v10
	v_add_u32_e32 v12, s95, v139
	v_min_i32_e32 v12, 15, v12
	v_add_u32_e32 v12, 1, v12
	v_cvt_f32_i32_e32 v12, v12
	v_cndmask_b32_e64 v6, 0, v6, s[58:59]
	v_sub_f32_e32 v10, v13, v11
	v_lshlrev_b32_e32 v11, 16, v6
	v_rcp_iflag_f32_e32 v12, v12
	v_and_b32_e32 v6, 0xffff0000, v6
	v_add_f32_e32 v10, v10, v6
	v_add_f32_e32 v9, v9, v11
	v_fma_f32 v6, v12, v10, -v6
	v_fma_f32 v11, v12, v9, -v11
	v_cvt_pk_bf16_f32 v6, v11, v6
	v_add_u32_e32 v179, 0, v158
	ds_write_b32 v179, v6 offset:34816
	v_sub_f32_e32 v6, v9, v7
	v_add_u32_e32 v9, s95, v140
	v_min_i32_e32 v9, 15, v9
	v_add_u32_e32 v9, 1, v9
	v_cvt_f32_i32_e32 v9, v9
	v_cndmask_b32_e64 v3, 0, v3, s[60:61]
	v_sub_f32_e32 v7, v10, v8
	v_lshlrev_b32_e32 v8, 16, v3
	v_rcp_iflag_f32_e32 v9, v9
	v_and_b32_e32 v3, 0xffff0000, v3
	v_add_f32_e32 v7, v7, v3
	v_add_f32_e32 v6, v6, v8
	v_fma_f32 v3, v9, v7, -v3
	v_fma_f32 v8, v9, v6, -v8
	v_cvt_pk_bf16_f32 v3, v8, v3
	v_add_u32_e32 v180, 0, v159
	ds_write_b32 v180, v3 offset:34816
	v_sub_f32_e32 v3, v6, v4
	v_add_u32_e32 v6, s95, v141
	v_min_i32_e32 v6, 15, v6
	v_add_u32_e32 v6, 1, v6
	v_cvt_f32_i32_e32 v6, v6
	v_sub_f32_e32 v4, v7, v5
	v_lshlrev_b32_e32 v5, 16, v0
	v_and_b32_e32 v0, 0xffff0000, v0
	v_rcp_iflag_f32_e32 v6, v6
	s_or_b32 s0, s94, 0x80
	v_add_f32_e32 v3, v3, v5
	v_add_f32_e32 v4, v4, v0
	s_xor_b32 s1, s95, 0xffffff7f
	s_mul_i32 s2, s0, 0x1e00
	v_fma_f32 v3, v6, v3, -v5
	v_fma_f32 v0, v6, v4, -v0
	s_mul_hi_i32 s3, s0, 0x1e00
	s_add_u32 s2, s91, s2
	v_cvt_pk_bf16_f32 v0, v3, v0
	s_addc_u32 s3, s92, s3
	v_mov_b32_e32 v3, v1
	v_add_u32_e32 v181, 0, v160
	v_cmp_lt_i32_e32 vcc, s1, v141
	v_lshl_add_u64 v[2:3], s[2:3], 0, v[2:3]
	s_mov_b64 s[2:3], 0x1720
	ds_write_b32 v181, v0 offset:34816
	v_lshl_add_u64 v[2:3], v[2:3], 0, s[2:3]
	v_cndmask_b32_e32 v0, 0, v141, vcc
	s_movk_i32 s6, 0x1e00
	v_mad_i64_i32 v[4:5], s[2:3], v0, s6, v[2:3]
	global_load_dword v0, v[4:5], off
	v_add_u32_e32 v185, v144, v143
	v_add_u32_e32 v183, v144, v161
	v_lshlrev_b32_e32 v104, 1, v90
	v_mov_b32_e32 v105, v1
	v_mov_b32_e32 v103, v1
	v_add_u32_e32 v184, v144, v163
	v_lshlrev_b32_e32 v114, 1, v98
	v_mov_b32_e32 v115, v1
	v_readlane_b32 s56, v253, 1
	s_mov_b64 s[8:9], 0
	v_readlane_b32 s58, v253, 3
	s_movk_i32 s56, 0x5ff
	s_mov_b32 s61, 0xf800000
	v_readlane_b32 s57, v253, 2
	v_readlane_b32 s59, v253, 4
	s_waitcnt vmcnt(0)
	v_cndmask_b32_e32 v182, 0, v0, vcc
	v_cmp_lt_i32_e32 vcc, s1, v85
	v_mov_b32_e32 v209, 0
	s_nop 0
	v_cndmask_b32_e32 v0, 0, v85, vcc
	v_mad_i64_i32 v[4:5], s[2:3], v0, s6, v[2:3]
	s_and_saveexec_b64 s[98:99], vcc
	global_load_dword v209, v[4:5], off
	s_mov_b64 exec, s[98:99]
	v_cmp_lt_i32_e32 vcc, s1, v91
	v_mov_b32_e32 v211, 0
	s_nop 0
	v_cndmask_b32_e32 v0, 0, v91, vcc
	v_mad_i64_i32 v[4:5], s[2:3], v0, s6, v[2:3]
	s_and_saveexec_b64 s[98:99], vcc
	global_load_dword v211, v[4:5], off
	s_mov_b64 exec, s[98:99]
	v_cmp_lt_i32_e32 vcc, s1, v93
	v_mov_b32_e32 v212, 0
	s_nop 0
	v_cndmask_b32_e32 v0, 0, v93, vcc
	v_mad_i64_i32 v[4:5], s[2:3], v0, s6, v[2:3]
	s_and_saveexec_b64 s[98:99], vcc
	global_load_dword v212, v[4:5], off
	s_mov_b64 exec, s[98:99]
	v_cmp_lt_i32_e32 vcc, s1, v95
	v_mov_b32_e32 v213, 0
	s_nop 0
	v_cndmask_b32_e32 v0, 0, v95, vcc
	v_mad_i64_i32 v[4:5], s[2:3], v0, s6, v[2:3]
	s_and_saveexec_b64 s[98:99], vcc
	global_load_dword v213, v[4:5], off
	s_mov_b64 exec, s[98:99]
	v_cmp_lt_i32_e32 vcc, s1, v97
	v_mov_b32_e32 v214, 0
	s_nop 0
	v_cndmask_b32_e32 v0, 0, v97, vcc
	v_mad_i64_i32 v[4:5], s[2:3], v0, s6, v[2:3]
	s_and_saveexec_b64 s[98:99], vcc
	global_load_dword v214, v[4:5], off
	s_mov_b64 exec, s[98:99]
	v_cmp_lt_i32_e32 vcc, s1, v99
	v_mov_b32_e32 v215, 0
	s_nop 0
	v_cndmask_b32_e32 v0, 0, v99, vcc
	v_mad_i64_i32 v[4:5], s[2:3], v0, s6, v[2:3]
	s_and_saveexec_b64 s[98:99], vcc
	global_load_dword v215, v[4:5], off
	s_mov_b64 exec, s[98:99]
	v_cmp_lt_i32_e32 vcc, s1, v101
	v_mov_b32_e32 v217, 0
	s_nop 0
	v_cndmask_b32_e32 v0, 0, v101, vcc
	v_mad_i64_i32 v[4:5], s[2:3], v0, s6, v[2:3]
	s_and_saveexec_b64 s[98:99], vcc
	global_load_dword v217, v[4:5], off
	s_mov_b64 exec, s[98:99]
	v_cmp_lt_i32_e32 vcc, s1, v119
	v_mov_b32_e32 v218, 0
	s_nop 0
	v_cndmask_b32_e32 v0, 0, v119, vcc
	v_mad_i64_i32 v[4:5], s[2:3], v0, s6, v[2:3]
	s_and_saveexec_b64 s[98:99], vcc
	global_load_dword v218, v[4:5], off
	s_mov_b64 exec, s[98:99]
	v_cmp_lt_i32_e32 vcc, s1, v120
	v_mov_b32_e32 v219, 0
	s_nop 0
	v_cndmask_b32_e32 v0, 0, v120, vcc
	v_mad_i64_i32 v[4:5], s[2:3], v0, s6, v[2:3]
	s_and_saveexec_b64 s[98:99], vcc
	global_load_dword v219, v[4:5], off
	s_mov_b64 exec, s[98:99]
	v_cmp_lt_i32_e32 vcc, s1, v121
	v_mov_b32_e32 v220, 0
	s_nop 0
	v_cndmask_b32_e32 v0, 0, v121, vcc
	v_mad_i64_i32 v[4:5], s[2:3], v0, s6, v[2:3]
	s_and_saveexec_b64 s[98:99], vcc
	global_load_dword v220, v[4:5], off
	s_mov_b64 exec, s[98:99]
	v_cmp_lt_i32_e32 vcc, s1, v122
	v_mov_b32_e32 v221, 0
	s_nop 0
	v_cndmask_b32_e32 v0, 0, v122, vcc
	v_mad_i64_i32 v[4:5], s[2:3], v0, s6, v[2:3]
	s_and_saveexec_b64 s[98:99], vcc
	global_load_dword v221, v[4:5], off
	s_mov_b64 exec, s[98:99]
	v_cmp_lt_i32_e32 vcc, s1, v123
	v_mov_b32_e32 v223, 0
	s_nop 0
	v_cndmask_b32_e32 v0, 0, v123, vcc
	v_mad_i64_i32 v[4:5], s[2:3], v0, s6, v[2:3]
	s_and_saveexec_b64 s[98:99], vcc
	global_load_dword v223, v[4:5], off
	s_mov_b64 exec, s[98:99]
	v_cmp_lt_i32_e32 vcc, s1, v124
	v_mov_b32_e32 v224, 0
	s_nop 0
	v_cndmask_b32_e32 v0, 0, v124, vcc
	v_mad_i64_i32 v[4:5], s[2:3], v0, s6, v[2:3]
	s_and_saveexec_b64 s[98:99], vcc
	global_load_dword v224, v[4:5], off
	s_mov_b64 exec, s[98:99]
	v_cmp_lt_i32_e32 vcc, s1, v125
	v_mov_b32_e32 v225, 0
	s_nop 0
	v_cndmask_b32_e32 v0, 0, v125, vcc
	v_mad_i64_i32 v[4:5], s[2:3], v0, s6, v[2:3]
	s_and_saveexec_b64 s[98:99], vcc
	global_load_dword v225, v[4:5], off
	s_mov_b64 exec, s[98:99]
	v_cmp_lt_i32_e32 vcc, s1, v126
	v_mov_b32_e32 v227, 0
	s_nop 0
	v_cndmask_b32_e32 v0, 0, v126, vcc
	v_mad_i64_i32 v[4:5], s[2:3], v0, s6, v[2:3]
	s_and_saveexec_b64 s[98:99], vcc
	global_load_dword v227, v[4:5], off
	s_mov_b64 exec, s[98:99]
	v_cmp_lt_i32_e32 vcc, s1, v83
	v_mov_b32_e32 v226, 0
	s_nop 0
	v_cndmask_b32_e32 v0, 0, v83, vcc
	v_mad_i64_i32 v[4:5], s[2:3], v0, s6, v[2:3]
	s_and_saveexec_b64 s[98:99], vcc
	global_load_dword v226, v[4:5], off
	s_mov_b64 exec, s[98:99]
	v_cmp_gt_i32_e32 vcc, s1, v83
	s_nop 1
	v_cndmask_b32_e64 v0, v127, 0, vcc
	v_mad_i64_i32 v[4:5], s[2:3], v0, s6, v[2:3]
	global_load_dword v0, v[4:5], off
	s_waitcnt vmcnt(0)
	v_cndmask_b32_e64 v222, v0, 0, vcc
	v_cmp_lt_i32_e32 vcc, s1, v128
	v_mov_b32_e32 v216, 0
	s_nop 0
	v_cndmask_b32_e32 v0, 0, v128, vcc
	v_mad_i64_i32 v[4:5], s[2:3], v0, s6, v[2:3]
	s_and_saveexec_b64 s[98:99], vcc
	global_load_dword v216, v[4:5], off
	s_mov_b64 exec, s[98:99]
	v_cmp_lt_i32_e32 vcc, s1, v129
	v_mov_b32_e32 v210, 0
	s_nop 0
	v_cndmask_b32_e32 v0, 0, v129, vcc
	v_mad_i64_i32 v[4:5], s[2:3], v0, s6, v[2:3]
	s_and_saveexec_b64 s[98:99], vcc
	global_load_dword v210, v[4:5], off
	s_mov_b64 exec, s[98:99]
	v_cmp_lt_i32_e32 vcc, s1, v130
	v_mov_b32_e32 v208, 0
	s_nop 0
	v_cndmask_b32_e32 v0, 0, v130, vcc
	v_mad_i64_i32 v[4:5], s[2:3], v0, s6, v[2:3]
	s_and_saveexec_b64 s[98:99], vcc
	global_load_dword v208, v[4:5], off
	s_mov_b64 exec, s[98:99]
	v_cmp_lt_i32_e32 vcc, s1, v131
	v_mov_b32_e32 v207, 0
	s_nop 0
	v_cndmask_b32_e32 v0, 0, v131, vcc
	v_mad_i64_i32 v[4:5], s[2:3], v0, s6, v[2:3]
	s_and_saveexec_b64 s[98:99], vcc
	global_load_dword v207, v[4:5], off
	s_mov_b64 exec, s[98:99]
	v_cmp_lt_i32_e32 vcc, s1, v132
	v_mov_b32_e32 v206, 0
	s_nop 0
	v_cndmask_b32_e32 v0, 0, v132, vcc
	v_mad_i64_i32 v[4:5], s[2:3], v0, s6, v[2:3]
	s_and_saveexec_b64 s[98:99], vcc
	global_load_dword v206, v[4:5], off
	s_mov_b64 exec, s[98:99]
	v_cmp_lt_i32_e32 vcc, s1, v133
	v_mov_b32_e32 v205, 0
	s_nop 0
	v_cndmask_b32_e32 v0, 0, v133, vcc
	v_mad_i64_i32 v[4:5], s[2:3], v0, s6, v[2:3]
	s_and_saveexec_b64 s[98:99], vcc
	global_load_dword v205, v[4:5], off
	s_mov_b64 exec, s[98:99]
	v_cmp_lt_i32_e32 vcc, s1, v134
	v_mov_b32_e32 v204, 0
	s_nop 0
	v_cndmask_b32_e32 v0, 0, v134, vcc
	v_mad_i64_i32 v[4:5], s[2:3], v0, s6, v[2:3]
	s_and_saveexec_b64 s[98:99], vcc
	global_load_dword v204, v[4:5], off
	s_mov_b64 exec, s[98:99]
	v_cmp_lt_i32_e32 vcc, s1, v135
	v_mov_b32_e32 v192, 0
	s_nop 0
	v_cndmask_b32_e32 v0, 0, v135, vcc
	v_mad_i64_i32 v[4:5], s[2:3], v0, s6, v[2:3]
	s_and_saveexec_b64 s[98:99], vcc
	global_load_dword v192, v[4:5], off
	s_mov_b64 exec, s[98:99]
	v_cmp_lt_i32_e32 vcc, s1, v136
	v_mov_b32_e32 v190, 0
	s_nop 0
	v_cndmask_b32_e32 v0, 0, v136, vcc
	v_mad_i64_i32 v[4:5], s[2:3], v0, s6, v[2:3]
	s_and_saveexec_b64 s[98:99], vcc
	global_load_dword v190, v[4:5], off
	s_mov_b64 exec, s[98:99]
	v_cmp_lt_i32_e32 vcc, s1, v137
	v_mov_b32_e32 v189, 0
	s_nop 0
	v_cndmask_b32_e32 v0, 0, v137, vcc
	v_mad_i64_i32 v[4:5], s[2:3], v0, s6, v[2:3]
	s_and_saveexec_b64 s[98:99], vcc
	global_load_dword v189, v[4:5], off
	s_mov_b64 exec, s[98:99]
	v_cmp_lt_i32_e32 vcc, s1, v138
	v_mov_b32_e32 v188, 0
	s_nop 0
	v_cndmask_b32_e32 v0, 0, v138, vcc
	v_mad_i64_i32 v[4:5], s[2:3], v0, s6, v[2:3]
	s_and_saveexec_b64 s[98:99], vcc
	global_load_dword v188, v[4:5], off
	s_mov_b64 exec, s[98:99]
	v_cmp_lt_i32_e32 vcc, s1, v139
	v_mov_b32_e32 v187, 0
	s_nop 0
	v_cndmask_b32_e32 v0, 0, v139, vcc
	v_mad_i64_i32 v[4:5], s[2:3], v0, s6, v[2:3]
	s_and_saveexec_b64 s[98:99], vcc
	global_load_dword v187, v[4:5], off
	s_mov_b64 exec, s[98:99]
	v_cmp_lt_i32_e32 vcc, s1, v140
	s_and_b32 s1, s0, 0xf80
	s_nop 0
	v_cndmask_b32_e32 v0, 0, v140, vcc
	v_mad_i64_i32 v[2:3], s[2:3], v0, s6, v[2:3]
	global_load_dword v0, v[2:3], off
	v_add_u32_e32 v2, s94, v142
	v_ashrrev_i32_e32 v3, 31, v2
	v_lshlrev_b64 v[2:3], 12, v[2:3]
	s_waitcnt lgkmcnt(0)
	s_barrier
	v_lshl_add_u64 v[2:3], s[70:71], 0, v[2:3]
	s_mov_b64 s[2:3], 0x26000b00
	ds_read_b128 v[74:77], v185 offset:34816
	ds_read_b128 v[78:81], v185 offset:34848
	ds_read_b128 v[70:73], v185 offset:34880
	ds_read_b128 v[66:69], v185 offset:34912
	ds_read_b128 v[62:65], v185 offset:34944
	ds_read_b128 v[58:61], v185 offset:34976
	ds_read_b128 v[54:57], v185 offset:35008
	ds_read_b128 v[50:53], v185 offset:35040
	v_lshl_add_u64 v[106:107], v[2:3], 0, s[2:3]
	ds_read_b128 v[2:5], v183
	ds_read_b128 v[108:111], v183 offset:32
	s_waitcnt lgkmcnt(1)
	v_mfma_f32_32x32x16_bf16 v[2:17], v[2:5], v[74:77], 0
	s_waitcnt vmcnt(0)
	v_cndmask_b32_e32 v186, 0, v0, vcc
	s_waitcnt lgkmcnt(0)
	v_mfma_f32_32x32x16_bf16 v[2:17], v[108:111], v[78:81], v[2:17]
	ds_read_b128 v[108:111], v183 offset:64
	s_waitcnt lgkmcnt(0)
	v_mfma_f32_32x32x16_bf16 v[2:17], v[108:111], v[70:73], v[2:17]
	ds_read_b128 v[108:111], v183 offset:96
	s_waitcnt lgkmcnt(0)
	v_mfma_f32_32x32x16_bf16 v[2:17], v[108:111], v[66:69], v[2:17]
	ds_read_b128 v[108:111], v183 offset:128
	s_waitcnt lgkmcnt(0)
	v_mfma_f32_32x32x16_bf16 v[2:17], v[108:111], v[62:65], v[2:17]
	ds_read_b128 v[108:111], v183 offset:160
	s_waitcnt lgkmcnt(0)
	v_mfma_f32_32x32x16_bf16 v[2:17], v[108:111], v[58:61], v[2:17]
	ds_read_b128 v[108:111], v183 offset:192
	s_waitcnt lgkmcnt(0)
	v_mfma_f32_32x32x16_bf16 v[2:17], v[108:111], v[54:57], v[2:17]
	ds_read_b128 v[108:111], v183 offset:224
	s_waitcnt lgkmcnt(0)
	v_mfma_f32_32x32x16_bf16 v[2:17], v[108:111], v[50:53], v[2:17]
	v_lshlrev_b32_e32 v108, 1, v92
	v_mov_b32_e32 v109, v1
	s_nop 9
	v_mul_f32_e32 v0, v46, v2
	v_mul_f32_e32 v2, v47, v3
	v_cvt_pk_bf16_f32 v2, v0, v2
	v_mul_f32_e32 v0, v48, v4
	v_mul_f32_e32 v3, v49, v5
	v_cvt_pk_bf16_f32 v3, v0, v3
	v_lshlrev_b32_e32 v0, 1, v88
	v_lshl_add_u64 v[4:5], v[106:107], 0, v[0:1]
	global_store_dwordx2 v[4:5], v[2:3], off
	v_mul_f32_e32 v2, v42, v6
	v_mul_f32_e32 v3, v43, v7
	v_cvt_pk_bf16_f32 v2, v2, v3
	v_mul_f32_e32 v3, v44, v8
	v_mul_f32_e32 v4, v45, v9
	v_cvt_pk_bf16_f32 v3, v3, v4
	v_lshl_add_u64 v[4:5], v[106:107], 0, v[104:105]
	global_store_dwordx2 v[4:5], v[2:3], off
	v_mul_f32_e32 v2, v38, v10
	v_mul_f32_e32 v3, v39, v11
	v_cvt_pk_bf16_f32 v2, v2, v3
	v_mul_f32_e32 v3, v40, v12
	v_mul_f32_e32 v4, v41, v13
	v_cvt_pk_bf16_f32 v3, v3, v4
	v_lshl_add_u64 v[4:5], v[106:107], 0, v[108:109]
	global_store_dwordx2 v[4:5], v[2:3], off
	v_mul_f32_e32 v2, v34, v14
	v_mul_f32_e32 v3, v35, v15
	v_cvt_pk_bf16_f32 v2, v2, v3
	v_mul_f32_e32 v3, v36, v16
	v_mul_f32_e32 v4, v37, v17
	v_cvt_pk_bf16_f32 v3, v3, v4
	v_lshl_add_u64 v[4:5], v[106:107], 0, v[102:103]
	global_store_dwordx2 v[4:5], v[2:3], off
	ds_read_b128 v[2:5], v184
	ds_read_b128 v[110:113], v184 offset:32
	s_waitcnt lgkmcnt(1)
	v_mfma_f32_32x32x16_bf16 v[2:17], v[2:5], v[74:77], 0
	ds_read_b128 v[74:77], v184 offset:64
	s_waitcnt lgkmcnt(1)
	v_mfma_f32_32x32x16_bf16 v[2:17], v[110:113], v[78:81], v[2:17]
	v_lshlrev_b32_e32 v110, 1, v94
	v_mov_b32_e32 v111, v1
	v_lshlrev_b32_e32 v112, 1, v96
	v_mov_b32_e32 v113, v1
	s_waitcnt lgkmcnt(0)
	v_mfma_f32_32x32x16_bf16 v[2:17], v[74:77], v[70:73], v[2:17]
	ds_read_b128 v[70:73], v184 offset:96
	s_waitcnt lgkmcnt(0)
	v_mfma_f32_32x32x16_bf16 v[2:17], v[70:73], v[66:69], v[2:17]
	ds_read_b128 v[66:69], v184 offset:128
	s_waitcnt lgkmcnt(0)
	v_mfma_f32_32x32x16_bf16 v[2:17], v[66:69], v[62:65], v[2:17]
	ds_read_b128 v[62:65], v184 offset:160
	v_add_u32_e32 v68, s1, v83
	v_min_i32_e32 v68, 15, v68
	v_add_u32_e32 v68, 1, v68
	v_cvt_f32_i32_e32 v68, v68
	v_lshlrev_b32_e32 v66, 16, v226
	v_and_b32_e32 v67, 0xffff0000, v226
	s_waitcnt lgkmcnt(0)
	v_mfma_f32_32x32x16_bf16 v[2:17], v[62:65], v[58:61], v[2:17]
	ds_read_b128 v[58:61], v184 offset:192
	v_lshlrev_b32_e32 v62, 16, v217
	v_and_b32_e32 v63, 0xffff0000, v217
	v_rcp_iflag_f32_e32 v68, v68
	s_waitcnt lgkmcnt(0)
	v_mfma_f32_32x32x16_bf16 v[2:17], v[58:61], v[54:57], v[2:17]
	ds_read_b128 v[54:57], v184 offset:224
	v_lshlrev_b32_e32 v58, 16, v214
	v_and_b32_e32 v59, 0xffff0000, v214
	v_lshlrev_b32_e32 v60, 16, v215
	v_and_b32_e32 v61, 0xffff0000, v215
	s_waitcnt lgkmcnt(0)
	v_mfma_f32_32x32x16_bf16 v[2:17], v[54:57], v[50:53], v[2:17]
	v_lshlrev_b32_e32 v50, 16, v209
	v_and_b32_e32 v51, 0xffff0000, v209
	v_lshlrev_b32_e32 v52, 16, v211
	v_and_b32_e32 v53, 0xffff0000, v211
	v_lshlrev_b32_e32 v54, 16, v212
	v_and_b32_e32 v55, 0xffff0000, v212
	v_lshlrev_b32_e32 v56, 16, v213
	s_nop 4
	v_mul_f32_e32 v2, v30, v2
	v_mul_f32_e32 v3, v31, v3
	v_cvt_pk_bf16_f32 v2, v2, v3
	v_mul_f32_e32 v3, v32, v4
	v_mul_f32_e32 v4, v33, v5
	v_cvt_pk_bf16_f32 v3, v3, v4
	v_lshl_add_u64 v[4:5], v[106:107], 0, v[110:111]
	global_store_dwordx2 v[4:5], v[2:3], off
	v_mul_f32_e32 v2, v26, v6
	v_mul_f32_e32 v3, v27, v7
	v_cvt_pk_bf16_f32 v2, v2, v3
	v_mul_f32_e32 v3, v28, v8
	v_mul_f32_e32 v4, v29, v9
	v_cvt_pk_bf16_f32 v3, v3, v4
	v_lshl_add_u64 v[4:5], v[106:107], 0, v[112:113]
	global_store_dwordx2 v[4:5], v[2:3], off
	v_mul_f32_e32 v2, v22, v10
	v_mul_f32_e32 v3, v23, v11
	v_cvt_pk_bf16_f32 v2, v2, v3
	v_mul_f32_e32 v3, v24, v12
	v_mul_f32_e32 v4, v25, v13
	v_cvt_pk_bf16_f32 v3, v3, v4
	v_lshl_add_u64 v[4:5], v[106:107], 0, v[114:115]
	global_store_dwordx2 v[4:5], v[2:3], off
	v_mul_f32_e32 v2, v18, v14
	v_mul_f32_e32 v3, v19, v15
	v_cvt_pk_bf16_f32 v2, v2, v3
	v_mul_f32_e32 v3, v20, v16
	v_mul_f32_e32 v4, v21, v17
	v_cvt_pk_bf16_f32 v3, v3, v4
	v_lshlrev_b32_e32 v4, 1, v100
	v_mov_b32_e32 v5, v1
	v_lshl_add_u64 v[4:5], v[106:107], 0, v[4:5]
	global_store_dwordx2 v[4:5], v[2:3], off
	v_add_f32_e32 v2, 0, v50
	v_add_f32_e32 v3, 0, v51
	v_add_f32_e32 v2, v2, v52
	v_add_f32_e32 v3, v3, v53
	v_add_f32_e32 v2, v2, v54
	v_add_f32_e32 v3, v3, v55
	v_add_f32_e32 v2, v2, v56
	v_and_b32_e32 v57, 0xffff0000, v213
	v_add_f32_e32 v3, v3, v57
	v_add_f32_e32 v2, v2, v58
	v_add_f32_e32 v3, v3, v59
	v_add_f32_e32 v2, v2, v60
	v_add_f32_e32 v3, v3, v61
	v_add_f32_e32 v2, v2, v62
	v_lshlrev_b32_e32 v16, 16, v218
	v_add_f32_e32 v3, v3, v63
	v_add_f32_e32 v2, v2, v16
	v_and_b32_e32 v17, 0xffff0000, v218
	v_lshlrev_b32_e32 v14, 16, v219
	v_add_f32_e32 v3, v3, v17
	v_add_f32_e32 v2, v2, v14
	v_and_b32_e32 v15, 0xffff0000, v219
	v_lshlrev_b32_e32 v12, 16, v220
	v_add_f32_e32 v3, v3, v15
	v_add_f32_e32 v2, v2, v12
	v_and_b32_e32 v13, 0xffff0000, v220
	v_lshlrev_b32_e32 v10, 16, v221
	v_add_f32_e32 v3, v3, v13
	v_add_f32_e32 v2, v2, v10
	v_and_b32_e32 v11, 0xffff0000, v221
	v_lshlrev_b32_e32 v8, 16, v223
	v_add_f32_e32 v3, v3, v11
	v_add_f32_e32 v2, v2, v8
	v_and_b32_e32 v9, 0xffff0000, v223
	v_lshlrev_b32_e32 v6, 16, v224
	v_add_f32_e32 v3, v3, v9
	v_add_f32_e32 v2, v2, v6
	v_and_b32_e32 v7, 0xffff0000, v224
	v_lshlrev_b32_e32 v4, 16, v225
	v_add_f32_e32 v3, v3, v7
	v_add_f32_e32 v64, v2, v4
	v_and_b32_e32 v5, 0xffff0000, v225
	v_lshlrev_b32_e32 v2, 16, v227
	v_add_f32_e32 v65, v3, v5
	v_add_f32_e32 v64, v64, v2
	v_and_b32_e32 v3, 0xffff0000, v227
	v_add_f32_e32 v65, v65, v3
	v_add_f32_e32 v64, v64, v66
	v_add_f32_e32 v65, v65, v67
	v_fma_f32 v66, v68, v64, -v66
	v_fma_f32 v67, v68, v65, -v67
	v_cvt_pk_bf16_f32 v66, v66, v67
	s_waitcnt lgkmcnt(0)
	s_barrier
	ds_write_b32 v116, v66 offset:34816
	v_add_u32_e32 v66, s1, v127
	v_min_i32_e32 v66, 15, v66
	v_add_u32_e32 v66, 1, v66
	v_cvt_f32_i32_e32 v66, v66
	v_sub_f32_e32 v50, v64, v50
	v_lshlrev_b32_e32 v64, 16, v222
	v_sub_f32_e32 v51, v65, v51
	v_rcp_iflag_f32_e32 v66, v66
	v_and_b32_e32 v65, 0xffff0000, v222
	v_add_f32_e32 v50, v50, v64
	v_add_f32_e32 v51, v51, v65
	v_fma_f32 v64, v66, v50, -v64
	v_fma_f32 v65, v66, v51, -v65
	v_cvt_pk_bf16_f32 v64, v64, v65
	ds_write_b32 v117, v64 offset:34816
	v_add_u32_e32 v64, s1, v128
	v_min_i32_e32 v64, 15, v64
	v_add_u32_e32 v64, 1, v64
	v_cvt_f32_i32_e32 v64, v64
	v_sub_f32_e32 v50, v50, v52
	v_lshlrev_b32_e32 v52, 16, v216
	v_add_f32_e32 v50, v50, v52
	v_rcp_iflag_f32_e32 v64, v64
	v_sub_f32_e32 v51, v51, v53
	v_and_b32_e32 v53, 0xffff0000, v216
	v_add_f32_e32 v51, v51, v53
	v_fma_f32 v52, v64, v50, -v52
	v_sub_f32_e32 v50, v50, v54
	v_add_u32_e32 v54, s1, v129
	v_min_i32_e32 v54, 15, v54
	v_add_u32_e32 v54, 1, v54
	v_cvt_f32_i32_e32 v54, v54
	v_fma_f32 v53, v64, v51, -v53
	v_cvt_pk_bf16_f32 v52, v52, v53
	ds_write_b32 v168, v52 offset:34816
	v_rcp_iflag_f32_e32 v54, v54
	v_sub_f32_e32 v51, v51, v55
	v_lshlrev_b32_e32 v52, 16, v210
	v_and_b32_e32 v53, 0xffff0000, v210
	v_add_f32_e32 v50, v50, v52
	v_add_f32_e32 v51, v51, v53
	v_fma_f32 v52, v54, v50, -v52
	v_fma_f32 v53, v54, v51, -v53
	v_add_u32_e32 v54, s1, v130
	v_min_i32_e32 v54, 15, v54
	v_add_u32_e32 v54, 1, v54
	v_cvt_f32_i32_e32 v54, v54
	v_cvt_pk_bf16_f32 v52, v52, v53
	ds_write_b32 v169, v52 offset:34816
	v_sub_f32_e32 v50, v50, v56
	v_rcp_iflag_f32_e32 v54, v54
	v_sub_f32_e32 v51, v51, v57
	v_lshlrev_b32_e32 v52, 16, v208
	v_and_b32_e32 v53, 0xffff0000, v208
	v_add_f32_e32 v50, v50, v52
	v_add_f32_e32 v51, v51, v53
	v_fma_f32 v52, v54, v50, -v52
	v_fma_f32 v53, v54, v51, -v53
	v_add_u32_e32 v54, s1, v131
	v_min_i32_e32 v54, 15, v54
	v_add_u32_e32 v54, 1, v54
	v_cvt_f32_i32_e32 v54, v54
	v_cvt_pk_bf16_f32 v52, v52, v53
	ds_write_b32 v170, v52 offset:34816
	v_sub_f32_e32 v50, v50, v58
	v_rcp_iflag_f32_e32 v54, v54
	v_sub_f32_e32 v51, v51, v59
	v_lshlrev_b32_e32 v52, 16, v207
	v_and_b32_e32 v53, 0xffff0000, v207
	v_add_f32_e32 v50, v50, v52
	v_add_f32_e32 v51, v51, v53
	v_fma_f32 v52, v54, v50, -v52
	v_fma_f32 v53, v54, v51, -v53
	v_add_u32_e32 v54, s1, v132
	v_min_i32_e32 v54, 15, v54
	v_add_u32_e32 v54, 1, v54
	v_cvt_f32_i32_e32 v54, v54
	v_cvt_pk_bf16_f32 v52, v52, v53
	ds_write_b32 v171, v52 offset:34816
	v_sub_f32_e32 v50, v50, v60
	v_rcp_iflag_f32_e32 v54, v54
	v_sub_f32_e32 v51, v51, v61
	v_lshlrev_b32_e32 v52, 16, v206
	v_and_b32_e32 v53, 0xffff0000, v206
	v_add_f32_e32 v50, v50, v52
	v_add_f32_e32 v51, v51, v53
	v_fma_f32 v52, v54, v50, -v52
	v_fma_f32 v53, v54, v51, -v53
	v_add_u32_e32 v54, s1, v133
	v_min_i32_e32 v54, 15, v54
	v_add_u32_e32 v54, 1, v54
	v_cvt_f32_i32_e32 v54, v54
	v_cvt_pk_bf16_f32 v52, v52, v53
	ds_write_b32 v172, v52 offset:34816
	v_sub_f32_e32 v50, v50, v62
	v_rcp_iflag_f32_e32 v54, v54
	v_lshlrev_b32_e32 v52, 16, v205
	v_sub_f32_e32 v51, v51, v63
	v_and_b32_e32 v53, 0xffff0000, v205
	v_add_f32_e32 v50, v50, v52
	v_add_f32_e32 v51, v51, v53
	v_fma_f32 v52, v54, v50, -v52
	v_fma_f32 v53, v54, v51, -v53
	v_cvt_pk_bf16_f32 v52, v52, v53
	ds_write_b32 v173, v52 offset:34816
	v_add_u32_e32 v52, s1, v134
	v_min_i32_e32 v52, 15, v52
	v_add_u32_e32 v52, 1, v52
	v_cvt_f32_i32_e32 v52, v52
	v_sub_f32_e32 v16, v50, v16
	v_lshlrev_b32_e32 v50, 16, v204
	v_sub_f32_e32 v17, v51, v17
	v_rcp_iflag_f32_e32 v52, v52
	v_and_b32_e32 v51, 0xffff0000, v204
	v_add_f32_e32 v16, v16, v50
	v_add_f32_e32 v17, v17, v51
	v_fma_f32 v50, v52, v16, -v50
	v_fma_f32 v51, v52, v17, -v51
	v_cvt_pk_bf16_f32 v50, v50, v51
	ds_write_b32 v174, v50 offset:34816
	v_add_u32_e32 v50, s1, v135
	v_min_i32_e32 v50, 15, v50
	v_add_u32_e32 v50, 1, v50
	v_cvt_f32_i32_e32 v50, v50
	v_sub_f32_e32 v14, v16, v14
	v_lshlrev_b32_e32 v16, 16, v192
	v_sub_f32_e32 v15, v17, v15
	v_rcp_iflag_f32_e32 v50, v50
	v_and_b32_e32 v17, 0xffff0000, v192
	v_add_f32_e32 v14, v14, v16
	v_add_f32_e32 v15, v15, v17
	v_fma_f32 v16, v50, v14, -v16
	v_fma_f32 v17, v50, v15, -v17
	v_cvt_pk_bf16_f32 v16, v16, v17
	ds_write_b32 v175, v16 offset:34816
	v_add_u32_e32 v16, s1, v136
	v_min_i32_e32 v16, 15, v16
	v_add_u32_e32 v16, 1, v16
	v_cvt_f32_i32_e32 v16, v16
	v_sub_f32_e32 v12, v14, v12
	v_lshlrev_b32_e32 v14, 16, v190
	v_sub_f32_e32 v13, v15, v13
	v_rcp_iflag_f32_e32 v16, v16
	v_and_b32_e32 v15, 0xffff0000, v190
	v_add_f32_e32 v12, v12, v14
	v_add_f32_e32 v13, v13, v15
	v_fma_f32 v14, v16, v12, -v14
	v_fma_f32 v15, v16, v13, -v15
	v_cvt_pk_bf16_f32 v14, v14, v15
	ds_write_b32 v176, v14 offset:34816
	v_add_u32_e32 v14, s1, v137
	v_min_i32_e32 v14, 15, v14
	v_add_u32_e32 v14, 1, v14
	v_cvt_f32_i32_e32 v14, v14
	v_sub_f32_e32 v10, v12, v10
	v_lshlrev_b32_e32 v12, 16, v189
	v_sub_f32_e32 v11, v13, v11
	v_rcp_iflag_f32_e32 v14, v14
	v_and_b32_e32 v13, 0xffff0000, v189
	v_add_f32_e32 v10, v10, v12
	v_add_f32_e32 v11, v11, v13
	v_fma_f32 v12, v14, v10, -v12
	v_fma_f32 v13, v14, v11, -v13
	v_cvt_pk_bf16_f32 v12, v12, v13
	ds_write_b32 v177, v12 offset:34816
	v_add_u32_e32 v12, s1, v138
	v_min_i32_e32 v12, 15, v12
	v_add_u32_e32 v12, 1, v12
	v_cvt_f32_i32_e32 v12, v12
	v_sub_f32_e32 v8, v10, v8
	v_lshlrev_b32_e32 v10, 16, v188
	v_sub_f32_e32 v9, v11, v9
	v_rcp_iflag_f32_e32 v12, v12
	v_and_b32_e32 v11, 0xffff0000, v188
	v_add_f32_e32 v8, v8, v10
	v_add_f32_e32 v9, v9, v11
	v_fma_f32 v10, v12, v8, -v10
	v_fma_f32 v11, v12, v9, -v11
	v_cvt_pk_bf16_f32 v10, v10, v11
	ds_write_b32 v178, v10 offset:34816
	v_add_u32_e32 v10, s1, v139
	v_min_i32_e32 v10, 15, v10
	v_add_u32_e32 v10, 1, v10
	v_cvt_f32_i32_e32 v10, v10
	v_sub_f32_e32 v6, v8, v6
	v_lshlrev_b32_e32 v8, 16, v187
	v_sub_f32_e32 v7, v9, v7
	v_rcp_iflag_f32_e32 v10, v10
	v_and_b32_e32 v9, 0xffff0000, v187
	v_add_f32_e32 v6, v6, v8
	v_add_f32_e32 v7, v7, v9
	v_fma_f32 v8, v10, v6, -v8
	v_fma_f32 v9, v10, v7, -v9
	v_cvt_pk_bf16_f32 v8, v8, v9
	ds_write_b32 v179, v8 offset:34816
	v_add_u32_e32 v8, s1, v140
	v_min_i32_e32 v8, 15, v8
	v_add_u32_e32 v8, 1, v8
	v_cvt_f32_i32_e32 v8, v8
	v_sub_f32_e32 v4, v6, v4
	v_lshlrev_b32_e32 v6, 16, v186
	v_sub_f32_e32 v5, v7, v5
	v_rcp_iflag_f32_e32 v8, v8
	v_and_b32_e32 v7, 0xffff0000, v186
	v_add_f32_e32 v4, v4, v6
	v_add_f32_e32 v5, v5, v7
	v_fma_f32 v6, v8, v4, -v6
	v_fma_f32 v7, v8, v5, -v7
	v_cvt_pk_bf16_f32 v6, v6, v7
	ds_write_b32 v180, v6 offset:34816
	v_add_u32_e32 v6, s1, v141
	v_min_i32_e32 v6, 15, v6
	v_add_u32_e32 v6, 1, v6
	v_cvt_f32_i32_e32 v6, v6
	v_sub_f32_e32 v2, v4, v2
	v_lshlrev_b32_e32 v4, 16, v182
	v_sub_f32_e32 v3, v5, v3
	v_rcp_iflag_f32_e32 v6, v6
	v_and_b32_e32 v5, 0xffff0000, v182
	v_add_f32_e32 v2, v2, v4
	v_add_f32_e32 v3, v3, v5
	v_fma_f32 v2, v6, v2, -v4
	v_fma_f32 v3, v6, v3, -v5
	v_cvt_pk_bf16_f32 v2, v2, v3
	ds_write_b32 v181, v2 offset:34816
	v_add_u32_e32 v2, s0, v142
	v_ashrrev_i32_e32 v3, 31, v2
	v_lshlrev_b64 v[2:3], 12, v[2:3]
	s_waitcnt lgkmcnt(0)
	s_barrier
	v_lshl_add_u64 v[2:3], s[70:71], 0, v[2:3]
	ds_read_b128 v[74:77], v185 offset:34816
	ds_read_b128 v[78:81], v185 offset:34848
	ds_read_b128 v[70:73], v185 offset:34880
	ds_read_b128 v[66:69], v185 offset:34912
	ds_read_b128 v[62:65], v185 offset:34944
	ds_read_b128 v[58:61], v185 offset:34976
	ds_read_b128 v[54:57], v185 offset:35008
	ds_read_b128 v[50:53], v185 offset:35040
	v_lshl_add_u64 v[106:107], v[2:3], 0, s[2:3]
	ds_read_b128 v[2:5], v183
	ds_read_b128 v[168:171], v183 offset:32
	s_waitcnt lgkmcnt(1)
	v_mfma_f32_32x32x16_bf16 v[2:17], v[2:5], v[74:77], 0
	s_waitcnt lgkmcnt(0)
	v_mfma_f32_32x32x16_bf16 v[2:17], v[168:171], v[78:81], v[2:17]
	ds_read_b128 v[168:171], v183 offset:64
	s_waitcnt lgkmcnt(0)
	v_mfma_f32_32x32x16_bf16 v[2:17], v[168:171], v[70:73], v[2:17]
	ds_read_b128 v[168:171], v183 offset:96
	s_waitcnt lgkmcnt(0)
	v_mfma_f32_32x32x16_bf16 v[2:17], v[168:171], v[66:69], v[2:17]
	ds_read_b128 v[168:171], v183 offset:128
	s_waitcnt lgkmcnt(0)
	v_mfma_f32_32x32x16_bf16 v[2:17], v[168:171], v[62:65], v[2:17]
	ds_read_b128 v[168:171], v183 offset:160
	s_waitcnt lgkmcnt(0)
	v_mfma_f32_32x32x16_bf16 v[2:17], v[168:171], v[58:61], v[2:17]
	ds_read_b128 v[168:171], v183 offset:192
	s_waitcnt lgkmcnt(0)
	v_mfma_f32_32x32x16_bf16 v[2:17], v[168:171], v[54:57], v[2:17]
	ds_read_b128 v[168:171], v183 offset:224
	s_waitcnt lgkmcnt(0)
	v_mfma_f32_32x32x16_bf16 v[2:17], v[168:171], v[50:53], v[2:17]
	s_nop 11
	v_mul_f32_e32 v2, v46, v2
	v_mul_f32_e32 v3, v47, v3
	v_cvt_pk_bf16_f32 v2, v2, v3
	v_mul_f32_e32 v3, v48, v4
	v_mul_f32_e32 v4, v49, v5
	v_cvt_pk_bf16_f32 v3, v3, v4
	v_lshl_add_u64 v[4:5], v[106:107], 0, v[0:1]
	global_store_dwordx2 v[4:5], v[2:3], off
	v_mul_f32_e32 v0, v42, v6
	v_mul_f32_e32 v2, v43, v7
	v_mul_f32_e32 v3, v45, v9
	v_cvt_pk_bf16_f32 v2, v0, v2
	v_mul_f32_e32 v0, v44, v8
	v_cvt_pk_bf16_f32 v3, v0, v3
	v_lshl_add_u64 v[4:5], v[106:107], 0, v[104:105]
	global_store_dwordx2 v[4:5], v[2:3], off
	v_mul_f32_e32 v0, v38, v10
	v_mul_f32_e32 v2, v39, v11
	v_mul_f32_e32 v3, v41, v13
	v_cvt_pk_bf16_f32 v2, v0, v2
	v_mul_f32_e32 v0, v40, v12
	v_cvt_pk_bf16_f32 v3, v0, v3
	v_lshl_add_u64 v[4:5], v[106:107], 0, v[108:109]
	global_store_dwordx2 v[4:5], v[2:3], off
	v_mul_f32_e32 v0, v34, v14
	v_mul_f32_e32 v2, v35, v15
	v_mul_f32_e32 v3, v37, v17
	v_lshl_add_u64 v[4:5], v[106:107], 0, v[102:103]
	v_cvt_pk_bf16_f32 v2, v0, v2
	v_mul_f32_e32 v0, v36, v16
	v_cvt_pk_bf16_f32 v3, v0, v3
	global_store_dwordx2 v[4:5], v[2:3], off
	ds_read_b128 v[2:5], v184
	ds_read_b128 v[34:37], v184 offset:32
	s_waitcnt lgkmcnt(1)
	v_mfma_f32_32x32x16_bf16 v[2:17], v[2:5], v[74:77], 0
	s_waitcnt lgkmcnt(0)
	v_mfma_f32_32x32x16_bf16 v[2:17], v[34:37], v[78:81], v[2:17]
	ds_read_b128 v[34:37], v184 offset:64
	s_waitcnt lgkmcnt(0)
	v_mfma_f32_32x32x16_bf16 v[2:17], v[34:37], v[70:73], v[2:17]
	ds_read_b128 v[34:37], v184 offset:96
	s_waitcnt lgkmcnt(0)
	v_mfma_f32_32x32x16_bf16 v[2:17], v[34:37], v[66:69], v[2:17]
	ds_read_b128 v[34:37], v184 offset:128
	s_waitcnt lgkmcnt(0)
	v_mfma_f32_32x32x16_bf16 v[2:17], v[34:37], v[62:65], v[2:17]
	ds_read_b128 v[34:37], v184 offset:160
	s_waitcnt lgkmcnt(0)
	v_mfma_f32_32x32x16_bf16 v[2:17], v[34:37], v[58:61], v[2:17]
	ds_read_b128 v[34:37], v184 offset:192
	s_waitcnt lgkmcnt(0)
	v_mfma_f32_32x32x16_bf16 v[2:17], v[34:37], v[54:57], v[2:17]
	ds_read_b128 v[34:37], v184 offset:224
	s_waitcnt lgkmcnt(0)
	v_mfma_f32_32x32x16_bf16 v[2:17], v[34:37], v[50:53], v[2:17]
	s_nop 11
	v_mul_f32_e32 v0, v30, v2
	v_mul_f32_e32 v2, v31, v3
	v_mul_f32_e32 v3, v33, v5
	v_cvt_pk_bf16_f32 v2, v0, v2
	v_mul_f32_e32 v0, v32, v4
	v_cvt_pk_bf16_f32 v3, v0, v3
	v_lshl_add_u64 v[4:5], v[106:107], 0, v[110:111]
	global_store_dwordx2 v[4:5], v[2:3], off
	v_mul_f32_e32 v0, v26, v6
	v_mul_f32_e32 v2, v27, v7
	v_mul_f32_e32 v3, v29, v9
	v_cvt_pk_bf16_f32 v2, v0, v2
	v_mul_f32_e32 v0, v28, v8
	v_cvt_pk_bf16_f32 v3, v0, v3
	v_lshl_add_u64 v[4:5], v[106:107], 0, v[112:113]
	global_store_dwordx2 v[4:5], v[2:3], off
	v_mul_f32_e32 v0, v22, v10
	v_mul_f32_e32 v2, v23, v11
	v_mul_f32_e32 v3, v25, v13
	v_cvt_pk_bf16_f32 v2, v0, v2
	v_mul_f32_e32 v0, v24, v12
	v_cvt_pk_bf16_f32 v3, v0, v3
	v_lshl_add_u64 v[4:5], v[106:107], 0, v[114:115]
	global_store_dwordx2 v[4:5], v[2:3], off
	v_mul_f32_e32 v0, v18, v14
	v_mul_f32_e32 v2, v19, v15
	v_mul_f32_e32 v3, v21, v17
	v_cvt_pk_bf16_f32 v2, v0, v2
	v_mul_f32_e32 v0, v20, v16
	v_cvt_pk_bf16_f32 v3, v0, v3

.LBB0_220:
	s_or_b64 exec, exec, s[52:53]
	s_waitcnt vmcnt(26)
	v_cndmask_b32_e64 v14, 0, v14, s[8:9]
	v_cndmask_b32_e32 v10, 0, v10, vcc
	v_lshlrev_b32_e32 v65, 16, v14
	v_and_b32_e32 v66, 0xffff0000, v14
	v_add_u32_e32 v14, s95, v83
	s_waitcnt vmcnt(8)
	v_cndmask_b32_e64 v0, 0, v57, s[46:47]
	v_cndmask_b32_e64 v57, 0, v56, s[28:29]
	v_cndmask_b32_e64 v11, 0, v11, s[0:1]
	v_lshlrev_b32_e32 v56, 16, v10
	v_min_i32_e32 v14, 7, v14
	v_cndmask_b32_e64 v12, 0, v12, s[2:3]
	v_add_f32_e32 v58, 0, v56
	v_and_b32_e32 v59, 0xffff0000, v10
	v_lshlrev_b32_e32 v60, 16, v11
	v_add_u32_e32 v14, 1, v14
	v_add_f32_e32 v10, 0, v59
	v_add_f32_e32 v58, v58, v60
	v_and_b32_e32 v61, 0xffff0000, v11
	v_lshlrev_b32_e32 v62, 16, v12
	v_cvt_f32_i32_e32 v14, v14
	v_cndmask_b32_e64 v13, 0, v13, s[6:7]
	v_add_f32_e32 v10, v10, v61
	v_add_f32_e32 v11, v58, v62
	v_and_b32_e32 v58, 0xffff0000, v12
	v_add_f32_e32 v10, v10, v58
	v_lshlrev_b32_e32 v63, 16, v13
	v_and_b32_e32 v64, 0xffff0000, v13
	v_cndmask_b32_e64 v15, 0, v15, s[10:11]
	v_add_f32_e32 v11, v11, v63
	v_add_f32_e32 v10, v10, v64
	v_cndmask_b32_e64 v16, 0, v16, s[12:13]
	v_add_f32_e32 v11, v11, v65
	v_add_f32_e32 v10, v10, v66
	v_lshlrev_b32_e32 v67, 16, v15
	v_and_b32_e32 v68, 0xffff0000, v15
	v_rcp_iflag_f32_e32 v14, v14
	v_cndmask_b32_e64 v17, 0, v17, s[14:15]
	v_add_f32_e32 v11, v11, v67
	v_add_f32_e32 v10, v10, v68
	v_lshlrev_b32_e32 v69, 16, v16
	v_and_b32_e32 v70, 0xffff0000, v16
	v_add_f32_e32 v12, v11, v69
	v_add_f32_e32 v13, v10, v70
	v_lshlrev_b32_e32 v10, 16, v17
	v_and_b32_e32 v11, 0xffff0000, v17
	v_add_u32_e32 v16, s95, v127
	v_add_f32_e32 v12, v12, v10
	v_add_f32_e32 v13, v13, v11
	v_min_i32_e32 v16, 7, v16
	v_fma_f32 v15, v14, v12, -v10
	v_fma_f32 v14, v14, v13, -v11
	v_add_u32_e32 v16, 1, v16
	v_cndmask_b32_e64 v50, v50, 0, s[16:17]
	v_cvt_pk_bf16_f32 v14, v15, v14
	v_add_u32_e32 v116, 0, v145
	v_cvt_f32_i32_e32 v16, v16
	s_waitcnt lgkmcnt(0)
	s_barrier
	ds_write_b32 v116, v14 offset:34816
	v_sub_f32_e32 v14, v12, v56
	v_sub_f32_e32 v15, v13, v59
	v_lshlrev_b32_e32 v12, 16, v50
	v_and_b32_e32 v13, 0xffff0000, v50
	v_add_u32_e32 v50, s95, v128
	v_min_i32_e32 v50, 7, v50
	v_add_u32_e32 v50, 1, v50
	v_rcp_iflag_f32_e32 v16, v16
	v_cvt_f32_i32_e32 v50, v50
	v_add_f32_e32 v14, v14, v12
	v_add_f32_e32 v15, v15, v13
	v_fma_f32 v17, v16, v14, -v12
	v_fma_f32 v16, v16, v15, -v13
	v_rcp_iflag_f32_e32 v50, v50
	v_cndmask_b32_e64 v51, 0, v51, s[18:19]
	v_cvt_pk_bf16_f32 v16, v17, v16
	v_add_u32_e32 v117, 0, v146
	ds_write_b32 v117, v16 offset:34816
	v_sub_f32_e32 v16, v14, v60
	v_sub_f32_e32 v17, v15, v61
	v_lshlrev_b32_e32 v14, 16, v51
	v_and_b32_e32 v15, 0xffff0000, v51
	v_add_f32_e32 v16, v16, v14
	v_add_f32_e32 v17, v17, v15
	v_fma_f32 v51, v50, v16, -v14
	v_fma_f32 v50, v50, v17, -v15
	v_cndmask_b32_e64 v52, 0, v52, s[20:21]
	v_cvt_pk_bf16_f32 v50, v51, v50
	v_add_u32_e32 v168, 0, v147
	ds_write_b32 v168, v50 offset:34816
	v_sub_f32_e32 v50, v16, v62
	v_sub_f32_e32 v51, v17, v58
	v_lshlrev_b32_e32 v16, 16, v52
	v_and_b32_e32 v17, 0xffff0000, v52
	v_add_u32_e32 v52, s95, v129
	v_min_i32_e32 v52, 7, v52
	v_add_u32_e32 v52, 1, v52
	v_cvt_f32_i32_e32 v52, v52
	v_add_f32_e32 v50, v50, v16
	v_add_f32_e32 v51, v51, v17
	v_cndmask_b32_e64 v53, 0, v53, s[22:23]
	v_rcp_iflag_f32_e32 v52, v52
	v_add_u32_e32 v169, 0, v148
	v_cndmask_b32_e64 v54, 0, v54, s[24:25]
	v_add_u32_e32 v170, 0, v149
	v_fma_f32 v56, v52, v50, -v16
	v_fma_f32 v52, v52, v51, -v17
	v_cvt_pk_bf16_f32 v52, v56, v52
	v_sub_f32_e32 v56, v51, v64
	v_and_b32_e32 v51, 0xffff0000, v53
	ds_write_b32 v169, v52 offset:34816
	v_sub_f32_e32 v52, v50, v63
	v_lshlrev_b32_e32 v50, 16, v53
	v_add_f32_e32 v53, v56, v51
	v_add_u32_e32 v56, s95, v130
	v_min_i32_e32 v56, 7, v56
	v_add_u32_e32 v56, 1, v56
	v_cvt_f32_i32_e32 v56, v56
	v_add_f32_e32 v52, v52, v50
	v_cndmask_b32_e64 v55, 0, v55, s[26:27]
	v_add_u32_e32 v171, 0, v150
	v_rcp_iflag_f32_e32 v56, v56
	v_add_u32_e32 v172, 0, v151
	v_cndmask_b32_e64 v9, 0, v9, s[50:51]
	v_add_u32_e32 v173, 0, v152
	v_fma_f32 v58, v56, v52, -v50
	v_fma_f32 v56, v56, v53, -v51
	v_cvt_pk_bf16_f32 v56, v58, v56
	ds_write_b32 v170, v56 offset:34816
	v_sub_f32_e32 v56, v52, v65
	v_sub_f32_e32 v58, v53, v66
	v_lshlrev_b32_e32 v52, 16, v54
	v_and_b32_e32 v53, 0xffff0000, v54
	v_add_f32_e32 v54, v56, v52
	v_add_f32_e32 v56, v58, v53
	v_add_u32_e32 v58, s95, v131
	v_min_i32_e32 v58, 7, v58
	v_add_u32_e32 v58, 1, v58
	v_cvt_f32_i32_e32 v58, v58
	v_add_u32_e32 v174, 0, v153
	v_cndmask_b32_e64 v8, 0, v8, s[34:35]
	v_cndmask_b32_e64 v7, 0, v7, s[36:37]
	v_rcp_iflag_f32_e32 v58, v58
	v_add_u32_e32 v175, 0, v154
	v_cndmask_b32_e64 v6, 0, v6, s[38:39]
	v_add_u32_e32 v176, 0, v155
	v_fma_f32 v59, v58, v54, -v52
	v_fma_f32 v58, v58, v56, -v53
	v_cvt_pk_bf16_f32 v58, v59, v58
	v_add_u32_e32 v59, s95, v132
	v_min_i32_e32 v59, 7, v59
	v_add_u32_e32 v59, 1, v59
	v_cvt_f32_i32_e32 v59, v59
	ds_write_b32 v171, v58 offset:34816
	v_sub_f32_e32 v58, v54, v67
	v_sub_f32_e32 v56, v56, v68
	v_rcp_iflag_f32_e32 v59, v59
	v_lshlrev_b32_e32 v54, 16, v55
	v_and_b32_e32 v55, 0xffff0000, v55
	v_add_f32_e32 v58, v58, v54
	v_add_f32_e32 v56, v56, v55
	v_fma_f32 v60, v59, v58, -v54
	v_fma_f32 v59, v59, v56, -v55
	v_cvt_pk_bf16_f32 v59, v60, v59
	v_add_u32_e32 v60, s95, v133
	v_min_i32_e32 v60, 7, v60
	v_add_u32_e32 v60, 1, v60
	v_cvt_f32_i32_e32 v60, v60
	ds_write_b32 v172, v59 offset:34816
	v_sub_f32_e32 v58, v58, v69
	v_sub_f32_e32 v59, v56, v70
	v_rcp_iflag_f32_e32 v60, v60
	v_lshlrev_b32_e32 v56, 16, v57
	v_and_b32_e32 v57, 0xffff0000, v57
	v_add_f32_e32 v58, v58, v56
	v_add_f32_e32 v59, v59, v57
	v_fma_f32 v61, v60, v58, -v56
	v_fma_f32 v60, v60, v59, -v57
	v_sub_f32_e32 v11, v59, v11
	v_add_u32_e32 v59, s95, v134
	v_min_i32_e32 v59, 7, v59
	v_add_u32_e32 v59, 1, v59
	v_cvt_f32_i32_e32 v59, v59
	v_sub_f32_e32 v10, v58, v10
	v_lshlrev_b32_e32 v58, 16, v9
	v_and_b32_e32 v9, 0xffff0000, v9
	v_rcp_iflag_f32_e32 v59, v59
	v_add_f32_e32 v11, v11, v9
	v_add_f32_e32 v10, v10, v58
	v_cvt_pk_bf16_f32 v60, v61, v60
	v_fma_f32 v9, v59, v11, -v9
	v_fma_f32 v58, v59, v10, -v58
	v_cvt_pk_bf16_f32 v9, v58, v9
	ds_write_b32 v173, v60 offset:34816
	ds_write_b32 v174, v9 offset:34816
	v_sub_f32_e32 v9, v10, v12
	v_add_u32_e32 v12, s95, v135
	v_min_i32_e32 v12, 7, v12
	v_add_u32_e32 v12, 1, v12
	v_cvt_f32_i32_e32 v12, v12
	v_sub_f32_e32 v10, v11, v13
	v_lshlrev_b32_e32 v11, 16, v8
	v_and_b32_e32 v8, 0xffff0000, v8
	v_rcp_iflag_f32_e32 v12, v12
	v_add_f32_e32 v9, v9, v11
	v_add_f32_e32 v10, v10, v8
	v_cndmask_b32_e64 v5, 0, v5, s[40:41]
	v_fma_f32 v11, v12, v9, -v11
	v_fma_f32 v8, v12, v10, -v8
	v_cvt_pk_bf16_f32 v8, v11, v8
	v_add_u32_e32 v11, s95, v136
	v_min_i32_e32 v11, 7, v11
	v_add_u32_e32 v11, 1, v11
	v_cvt_f32_i32_e32 v11, v11
	ds_write_b32 v175, v8 offset:34816
	v_sub_f32_e32 v8, v9, v14
	v_sub_f32_e32 v9, v10, v15
	v_rcp_iflag_f32_e32 v11, v11
	v_lshlrev_b32_e32 v10, 16, v7
	v_and_b32_e32 v7, 0xffff0000, v7
	v_add_f32_e32 v8, v8, v10
	v_add_f32_e32 v9, v9, v7
	v_fma_f32 v10, v11, v8, -v10
	v_fma_f32 v7, v11, v9, -v7
	v_cvt_pk_bf16_f32 v7, v10, v7
	v_add_u32_e32 v10, s95, v137
	v_min_i32_e32 v10, 7, v10
	v_add_u32_e32 v10, 1, v10
	v_cvt_f32_i32_e32 v10, v10
	ds_write_b32 v176, v7 offset:34816
	v_sub_f32_e32 v7, v8, v16
	v_sub_f32_e32 v8, v9, v17
	v_rcp_iflag_f32_e32 v10, v10
	v_lshlrev_b32_e32 v9, 16, v6
	v_and_b32_e32 v6, 0xffff0000, v6
	v_add_f32_e32 v7, v7, v9
	v_add_f32_e32 v8, v8, v6
	v_fma_f32 v9, v10, v7, -v9
	v_fma_f32 v6, v10, v8, -v6
	v_cvt_pk_bf16_f32 v6, v9, v6
	v_add_u32_e32 v9, s95, v138
	v_min_i32_e32 v9, 7, v9
	v_add_u32_e32 v9, 1, v9
	v_cvt_f32_i32_e32 v9, v9
	v_add_u32_e32 v177, 0, v156
	ds_write_b32 v177, v6 offset:34816
	v_sub_f32_e32 v6, v7, v50
	v_rcp_iflag_f32_e32 v9, v9
	v_sub_f32_e32 v7, v8, v51
	v_lshlrev_b32_e32 v8, 16, v5
	v_and_b32_e32 v5, 0xffff0000, v5
	v_add_f32_e32 v6, v6, v8
	v_add_f32_e32 v7, v7, v5
	v_fma_f32 v8, v9, v6, -v8
	v_fma_f32 v5, v9, v7, -v5
	v_cvt_pk_bf16_f32 v5, v8, v5
	v_add_u32_e32 v8, s95, v139
	v_min_i32_e32 v8, 7, v8
	v_add_u32_e32 v8, 1, v8
	v_cvt_f32_i32_e32 v8, v8
	v_cndmask_b32_e64 v4, 0, v4, s[42:43]
	v_add_u32_e32 v178, 0, v157
	ds_write_b32 v178, v5 offset:34816
	v_rcp_iflag_f32_e32 v8, v8
	v_sub_f32_e32 v5, v6, v52
	v_sub_f32_e32 v6, v7, v53
	v_lshlrev_b32_e32 v7, 16, v4
	v_and_b32_e32 v4, 0xffff0000, v4
	v_add_f32_e32 v5, v5, v7
	v_add_f32_e32 v6, v6, v4
	v_fma_f32 v7, v8, v5, -v7
	v_fma_f32 v4, v8, v6, -v4
	v_cvt_pk_bf16_f32 v4, v7, v4
	v_add_u32_e32 v7, s95, v140
	v_min_i32_e32 v7, 7, v7
	v_add_u32_e32 v7, 1, v7
	v_cvt_f32_i32_e32 v7, v7
	v_cndmask_b32_e64 v3, 0, v3, s[44:45]
	v_add_u32_e32 v179, 0, v158
	ds_write_b32 v179, v4 offset:34816
	v_rcp_iflag_f32_e32 v7, v7
	v_sub_f32_e32 v4, v5, v54
	v_sub_f32_e32 v5, v6, v55
	v_lshlrev_b32_e32 v6, 16, v3
	v_and_b32_e32 v3, 0xffff0000, v3
	v_add_f32_e32 v4, v4, v6
	v_add_f32_e32 v5, v5, v3
	v_fma_f32 v6, v7, v4, -v6
	v_fma_f32 v3, v7, v5, -v3
	v_cvt_pk_bf16_f32 v3, v6, v3
	v_add_u32_e32 v6, s95, v141
	v_min_i32_e32 v6, 7, v6
	v_add_u32_e32 v6, 1, v6
	v_cvt_f32_i32_e32 v6, v6
	v_add_u32_e32 v180, 0, v159
	ds_write_b32 v180, v3 offset:34816
	v_sub_f32_e32 v3, v4, v56
	v_rcp_iflag_f32_e32 v6, v6
	v_sub_f32_e32 v4, v5, v57
	v_lshlrev_b32_e32 v5, 16, v0
	v_and_b32_e32 v0, 0xffff0000, v0
	s_or_b32 s0, s94, 0x80
	v_add_f32_e32 v3, v3, v5
	v_add_f32_e32 v4, v4, v0
	s_xor_b32 s1, s95, 0xffffff7f
	s_mul_i32 s2, s0, 0x1e00
	v_fma_f32 v3, v6, v3, -v5
	v_fma_f32 v0, v6, v4, -v0
	s_mul_hi_i32 s3, s0, 0x1e00
	s_add_u32 s2, s91, s2
	v_cvt_pk_bf16_f32 v0, v3, v0
	s_addc_u32 s3, s92, s3
	v_mov_b32_e32 v3, v1
	v_add_u32_e32 v181, 0, v160
	v_cmp_lt_i32_e32 vcc, s1, v141
	v_lshl_add_u64 v[2:3], s[2:3], 0, v[2:3]
	s_mov_b64 s[2:3], 0x1620
	ds_write_b32 v181, v0 offset:34816
	v_lshl_add_u64 v[2:3], v[2:3], 0, s[2:3]
	v_cndmask_b32_e32 v0, 0, v141, vcc
	s_movk_i32 s6, 0x1e00
	v_mad_i64_i32 v[4:5], s[2:3], v0, s6, v[2:3]
	global_load_dword v0, v[4:5], off
	v_add_u32_e32 v185, v144, v143
	v_add_u32_e32 v183, v144, v161
	v_lshlrev_b32_e32 v104, 1, v90
	v_mov_b32_e32 v105, v1
	v_mov_b32_e32 v103, v1
	v_add_u32_e32 v184, v144, v163
	v_lshlrev_b32_e32 v114, 1, v98
	v_mov_b32_e32 v115, v1
	s_waitcnt vmcnt(0)
	v_cndmask_b32_e32 v182, 0, v0, vcc
	v_cmp_lt_i32_e32 vcc, s1, v120
	v_mov_b32_e32 v211, 0
	s_nop 0
	v_cndmask_b32_e32 v0, 0, v120, vcc
	v_mad_i64_i32 v[4:5], s[2:3], v0, s6, v[2:3]
	s_and_saveexec_b64 s[98:99], vcc
	global_load_dword v211, v[4:5], off
	s_mov_b64 exec, s[98:99]
	v_cmp_lt_i32_e32 vcc, s1, v121
	v_mov_b32_e32 v212, 0
	s_nop 0
	v_cndmask_b32_e32 v0, 0, v121, vcc
	v_mad_i64_i32 v[4:5], s[2:3], v0, s6, v[2:3]
	s_and_saveexec_b64 s[98:99], vcc
	global_load_dword v212, v[4:5], off
	s_mov_b64 exec, s[98:99]
	v_cmp_lt_i32_e32 vcc, s1, v122
	v_mov_b32_e32 v213, 0
	s_nop 0
	v_cndmask_b32_e32 v0, 0, v122, vcc
	v_mad_i64_i32 v[4:5], s[2:3], v0, s6, v[2:3]
	s_and_saveexec_b64 s[98:99], vcc
	global_load_dword v213, v[4:5], off
	s_mov_b64 exec, s[98:99]
	v_cmp_lt_i32_e32 vcc, s1, v123
	v_mov_b32_e32 v214, 0
	s_nop 0
	v_cndmask_b32_e32 v0, 0, v123, vcc
	v_mad_i64_i32 v[4:5], s[2:3], v0, s6, v[2:3]
	s_and_saveexec_b64 s[98:99], vcc
	global_load_dword v214, v[4:5], off
	s_mov_b64 exec, s[98:99]
	v_cmp_lt_i32_e32 vcc, s1, v124
	v_mov_b32_e32 v215, 0
	s_nop 0
	v_cndmask_b32_e32 v0, 0, v124, vcc
	v_mad_i64_i32 v[4:5], s[2:3], v0, s6, v[2:3]
	s_and_saveexec_b64 s[98:99], vcc
	global_load_dword v215, v[4:5], off
	s_mov_b64 exec, s[98:99]
	v_cmp_lt_i32_e32 vcc, s1, v125
	v_mov_b32_e32 v216, 0
	s_nop 0
	v_cndmask_b32_e32 v0, 0, v125, vcc
	v_mad_i64_i32 v[4:5], s[2:3], v0, s6, v[2:3]
	s_and_saveexec_b64 s[98:99], vcc
	global_load_dword v216, v[4:5], off
	s_mov_b64 exec, s[98:99]
	v_cmp_lt_i32_e32 vcc, s1, v126
	v_mov_b32_e32 v218, 0
	s_nop 0
	v_cndmask_b32_e32 v0, 0, v126, vcc
	v_mad_i64_i32 v[4:5], s[2:3], v0, s6, v[2:3]
	s_and_saveexec_b64 s[98:99], vcc
	global_load_dword v218, v[4:5], off
	s_mov_b64 exec, s[98:99]
	v_cmp_lt_i32_e32 vcc, s1, v83
	v_mov_b32_e32 v217, 0
	s_nop 0
	v_cndmask_b32_e32 v0, 0, v83, vcc
	v_mad_i64_i32 v[4:5], s[2:3], v0, s6, v[2:3]
	s_and_saveexec_b64 s[98:99], vcc
	global_load_dword v217, v[4:5], off
	s_mov_b64 exec, s[98:99]
	v_cmp_gt_i32_e32 vcc, s1, v83
	s_nop 1
	v_cndmask_b32_e64 v0, v127, 0, vcc
	v_mad_i64_i32 v[4:5], s[2:3], v0, s6, v[2:3]
	global_load_dword v0, v[4:5], off
	s_waitcnt vmcnt(0)
	v_cndmask_b32_e64 v191, v0, 0, vcc
	v_cmp_lt_i32_e32 vcc, s1, v128
	v_mov_b32_e32 v210, 0
	s_nop 0
	v_cndmask_b32_e32 v0, 0, v128, vcc
	v_mad_i64_i32 v[4:5], s[2:3], v0, s6, v[2:3]
	s_and_saveexec_b64 s[98:99], vcc
	global_load_dword v210, v[4:5], off
	s_mov_b64 exec, s[98:99]
	v_cmp_lt_i32_e32 vcc, s1, v129
	v_mov_b32_e32 v209, 0
	s_nop 0
	v_cndmask_b32_e32 v0, 0, v129, vcc
	v_mad_i64_i32 v[4:5], s[2:3], v0, s6, v[2:3]
	s_and_saveexec_b64 s[98:99], vcc
	global_load_dword v209, v[4:5], off
	s_mov_b64 exec, s[98:99]
	v_cmp_lt_i32_e32 vcc, s1, v130
	v_mov_b32_e32 v208, 0
	s_nop 0
	v_cndmask_b32_e32 v0, 0, v130, vcc
	v_mad_i64_i32 v[4:5], s[2:3], v0, s6, v[2:3]
	s_and_saveexec_b64 s[98:99], vcc
	global_load_dword v208, v[4:5], off
	s_mov_b64 exec, s[98:99]
	v_cmp_lt_i32_e32 vcc, s1, v131
	v_mov_b32_e32 v207, 0
	s_nop 0
	v_cndmask_b32_e32 v0, 0, v131, vcc
	v_mad_i64_i32 v[4:5], s[2:3], v0, s6, v[2:3]
	s_and_saveexec_b64 s[98:99], vcc
	global_load_dword v207, v[4:5], off
	s_mov_b64 exec, s[98:99]
	v_cmp_lt_i32_e32 vcc, s1, v132
	v_mov_b32_e32 v206, 0
	s_nop 0
	v_cndmask_b32_e32 v0, 0, v132, vcc
	v_mad_i64_i32 v[4:5], s[2:3], v0, s6, v[2:3]
	s_and_saveexec_b64 s[98:99], vcc
	global_load_dword v206, v[4:5], off
	s_mov_b64 exec, s[98:99]
	v_cmp_lt_i32_e32 vcc, s1, v133
	v_mov_b32_e32 v205, 0
	s_nop 0
	v_cndmask_b32_e32 v0, 0, v133, vcc
	v_mad_i64_i32 v[4:5], s[2:3], v0, s6, v[2:3]
	s_and_saveexec_b64 s[98:99], vcc
	global_load_dword v205, v[4:5], off
	s_mov_b64 exec, s[98:99]
	v_cmp_lt_i32_e32 vcc, s1, v134
	v_mov_b32_e32 v204, 0
	s_nop 0
	v_cndmask_b32_e32 v0, 0, v134, vcc
	v_mad_i64_i32 v[4:5], s[2:3], v0, s6, v[2:3]
	s_and_saveexec_b64 s[98:99], vcc
	global_load_dword v204, v[4:5], off
	s_mov_b64 exec, s[98:99]
	v_cmp_lt_i32_e32 vcc, s1, v135
	v_mov_b32_e32 v192, 0
	s_nop 0
	v_cndmask_b32_e32 v0, 0, v135, vcc
	v_mad_i64_i32 v[4:5], s[2:3], v0, s6, v[2:3]
	s_and_saveexec_b64 s[98:99], vcc
	global_load_dword v192, v[4:5], off
	s_mov_b64 exec, s[98:99]
	v_cmp_lt_i32_e32 vcc, s1, v136
	v_mov_b32_e32 v190, 0
	s_nop 0
	v_cndmask_b32_e32 v0, 0, v136, vcc
	v_mad_i64_i32 v[4:5], s[2:3], v0, s6, v[2:3]
	s_and_saveexec_b64 s[98:99], vcc
	global_load_dword v190, v[4:5], off
	s_mov_b64 exec, s[98:99]
	v_cmp_lt_i32_e32 vcc, s1, v137
	v_mov_b32_e32 v189, 0
	s_nop 0
	v_cndmask_b32_e32 v0, 0, v137, vcc
	v_mad_i64_i32 v[4:5], s[2:3], v0, s6, v[2:3]
	s_and_saveexec_b64 s[98:99], vcc
	global_load_dword v189, v[4:5], off
	s_mov_b64 exec, s[98:99]
	v_cmp_lt_i32_e32 vcc, s1, v138
	v_mov_b32_e32 v188, 0
	s_nop 0
	v_cndmask_b32_e32 v0, 0, v138, vcc
	v_mad_i64_i32 v[4:5], s[2:3], v0, s6, v[2:3]
	s_and_saveexec_b64 s[98:99], vcc
	global_load_dword v188, v[4:5], off
	s_mov_b64 exec, s[98:99]
	v_cmp_lt_i32_e32 vcc, s1, v139
	v_mov_b32_e32 v187, 0
	s_nop 0
	v_cndmask_b32_e32 v0, 0, v139, vcc
	v_mad_i64_i32 v[4:5], s[2:3], v0, s6, v[2:3]
	s_and_saveexec_b64 s[98:99], vcc
	global_load_dword v187, v[4:5], off
	s_mov_b64 exec, s[98:99]
	v_cmp_lt_i32_e32 vcc, s1, v140
	s_and_b32 s1, s0, 0xf80
	s_nop 0
	v_cndmask_b32_e32 v0, 0, v140, vcc
	v_mad_i64_i32 v[2:3], s[2:3], v0, s6, v[2:3]
	global_load_dword v0, v[2:3], off
	v_add_u32_e32 v2, s94, v142
	v_ashrrev_i32_e32 v3, 31, v2
	v_lshlrev_b64 v[2:3], 12, v[2:3]
	s_waitcnt lgkmcnt(0)
	s_barrier
	v_lshl_add_u64 v[2:3], s[70:71], 0, v[2:3]
	s_mov_b64 s[2:3], 0x26000a00
	ds_read_b128 v[74:77], v185 offset:34816
	ds_read_b128 v[78:81], v185 offset:34848
	ds_read_b128 v[70:73], v185 offset:34880
	ds_read_b128 v[66:69], v185 offset:34912
	ds_read_b128 v[62:65], v185 offset:34944
	ds_read_b128 v[58:61], v185 offset:34976
	ds_read_b128 v[54:57], v185 offset:35008
	ds_read_b128 v[50:53], v185 offset:35040
	v_lshl_add_u64 v[106:107], v[2:3], 0, s[2:3]
	ds_read_b128 v[2:5], v183
	ds_read_b128 v[108:111], v183 offset:32
	s_waitcnt lgkmcnt(1)
	v_mfma_f32_32x32x16_bf16 v[2:17], v[2:5], v[74:77], 0
	s_waitcnt vmcnt(0)
	v_cndmask_b32_e32 v186, 0, v0, vcc
	s_waitcnt lgkmcnt(0)
	v_mfma_f32_32x32x16_bf16 v[2:17], v[108:111], v[78:81], v[2:17]
	ds_read_b128 v[108:111], v183 offset:64
	s_waitcnt lgkmcnt(0)
	v_mfma_f32_32x32x16_bf16 v[2:17], v[108:111], v[70:73], v[2:17]
	ds_read_b128 v[108:111], v183 offset:96
	s_waitcnt lgkmcnt(0)
	v_mfma_f32_32x32x16_bf16 v[2:17], v[108:111], v[66:69], v[2:17]
	ds_read_b128 v[108:111], v183 offset:128
	s_waitcnt lgkmcnt(0)
	v_mfma_f32_32x32x16_bf16 v[2:17], v[108:111], v[62:65], v[2:17]
	ds_read_b128 v[108:111], v183 offset:160
	s_waitcnt lgkmcnt(0)
	v_mfma_f32_32x32x16_bf16 v[2:17], v[108:111], v[58:61], v[2:17]
	ds_read_b128 v[108:111], v183 offset:192
	s_waitcnt lgkmcnt(0)
	v_mfma_f32_32x32x16_bf16 v[2:17], v[108:111], v[54:57], v[2:17]
	ds_read_b128 v[108:111], v183 offset:224
	s_waitcnt lgkmcnt(0)
	v_mfma_f32_32x32x16_bf16 v[2:17], v[108:111], v[50:53], v[2:17]
	v_lshlrev_b32_e32 v108, 1, v92
	v_mov_b32_e32 v109, v1
	s_nop 9
	v_mul_f32_e32 v0, v46, v2
	v_mul_f32_e32 v2, v47, v3
	v_cvt_pk_bf16_f32 v2, v0, v2
	v_mul_f32_e32 v0, v48, v4
	v_mul_f32_e32 v3, v49, v5
	v_cvt_pk_bf16_f32 v3, v0, v3
	v_lshlrev_b32_e32 v0, 1, v88
	v_lshl_add_u64 v[4:5], v[106:107], 0, v[0:1]
	global_store_dwordx2 v[4:5], v[2:3], off
	v_mul_f32_e32 v2, v42, v6
	v_mul_f32_e32 v3, v43, v7
	v_cvt_pk_bf16_f32 v2, v2, v3
	v_mul_f32_e32 v3, v44, v8
	v_mul_f32_e32 v4, v45, v9
	v_cvt_pk_bf16_f32 v3, v3, v4
	v_lshl_add_u64 v[4:5], v[106:107], 0, v[104:105]
	global_store_dwordx2 v[4:5], v[2:3], off
	v_mul_f32_e32 v2, v38, v10
	v_mul_f32_e32 v3, v39, v11
	v_cvt_pk_bf16_f32 v2, v2, v3
	v_mul_f32_e32 v3, v40, v12
	v_mul_f32_e32 v4, v41, v13
	v_cvt_pk_bf16_f32 v3, v3, v4
	v_lshl_add_u64 v[4:5], v[106:107], 0, v[108:109]
	global_store_dwordx2 v[4:5], v[2:3], off
	v_mul_f32_e32 v2, v34, v14
	v_mul_f32_e32 v3, v35, v15
	v_cvt_pk_bf16_f32 v2, v2, v3
	v_mul_f32_e32 v3, v36, v16
	v_mul_f32_e32 v4, v37, v17
	v_cvt_pk_bf16_f32 v3, v3, v4
	v_lshl_add_u64 v[4:5], v[106:107], 0, v[102:103]
	global_store_dwordx2 v[4:5], v[2:3], off
	ds_read_b128 v[2:5], v184
	ds_read_b128 v[110:113], v184 offset:32
	s_waitcnt lgkmcnt(1)
	v_mfma_f32_32x32x16_bf16 v[2:17], v[2:5], v[74:77], 0
	ds_read_b128 v[74:77], v184 offset:64
	s_waitcnt lgkmcnt(1)
	v_mfma_f32_32x32x16_bf16 v[2:17], v[110:113], v[78:81], v[2:17]
	v_lshlrev_b32_e32 v110, 1, v94
	v_mov_b32_e32 v111, v1
	v_lshlrev_b32_e32 v112, 1, v96
	v_mov_b32_e32 v113, v1
	s_waitcnt lgkmcnt(0)
	v_mfma_f32_32x32x16_bf16 v[2:17], v[74:77], v[70:73], v[2:17]
	ds_read_b128 v[70:73], v184 offset:96
	s_waitcnt lgkmcnt(0)
	v_mfma_f32_32x32x16_bf16 v[2:17], v[70:73], v[66:69], v[2:17]
	ds_read_b128 v[66:69], v184 offset:128
	s_waitcnt lgkmcnt(0)
	v_mfma_f32_32x32x16_bf16 v[2:17], v[66:69], v[62:65], v[2:17]
	ds_read_b128 v[62:65], v184 offset:160
	s_waitcnt lgkmcnt(0)
	v_mfma_f32_32x32x16_bf16 v[2:17], v[62:65], v[58:61], v[2:17]
	ds_read_b128 v[58:61], v184 offset:192
	s_waitcnt lgkmcnt(0)
	v_mfma_f32_32x32x16_bf16 v[2:17], v[58:61], v[54:57], v[2:17]
	ds_read_b128 v[54:57], v184 offset:224
	s_waitcnt lgkmcnt(0)
	v_mfma_f32_32x32x16_bf16 v[2:17], v[54:57], v[50:53], v[2:17]
	v_add_u32_e32 v52, s1, v83
	v_min_i32_e32 v52, 7, v52
	v_add_u32_e32 v52, 1, v52
	v_cvt_f32_i32_e32 v52, v52
	v_lshlrev_b32_e32 v50, 16, v217
	v_and_b32_e32 v51, 0xffff0000, v217
	s_nop 5
	v_mul_f32_e32 v2, v30, v2
	v_mul_f32_e32 v3, v31, v3
	v_cvt_pk_bf16_f32 v2, v2, v3
	v_mul_f32_e32 v3, v32, v4
	v_mul_f32_e32 v4, v33, v5
	v_cvt_pk_bf16_f32 v3, v3, v4
	v_lshl_add_u64 v[4:5], v[106:107], 0, v[110:111]
	global_store_dwordx2 v[4:5], v[2:3], off
	v_mul_f32_e32 v2, v26, v6
	v_mul_f32_e32 v3, v27, v7
	v_cvt_pk_bf16_f32 v2, v2, v3
	v_mul_f32_e32 v3, v28, v8
	v_mul_f32_e32 v4, v29, v9
	v_cvt_pk_bf16_f32 v3, v3, v4
	v_lshl_add_u64 v[4:5], v[106:107], 0, v[112:113]
	global_store_dwordx2 v[4:5], v[2:3], off
	v_mul_f32_e32 v2, v22, v10
	v_mul_f32_e32 v3, v23, v11
	v_cvt_pk_bf16_f32 v2, v2, v3
	v_mul_f32_e32 v3, v24, v12
	v_mul_f32_e32 v4, v25, v13
	v_cvt_pk_bf16_f32 v3, v3, v4
	v_lshl_add_u64 v[4:5], v[106:107], 0, v[114:115]
	global_store_dwordx2 v[4:5], v[2:3], off
	v_mul_f32_e32 v2, v18, v14
	v_mul_f32_e32 v3, v19, v15
	v_cvt_pk_bf16_f32 v2, v2, v3
	v_mul_f32_e32 v3, v20, v16
	v_mul_f32_e32 v4, v21, v17
	v_cvt_pk_bf16_f32 v3, v3, v4
	v_lshlrev_b32_e32 v4, 1, v100
	v_mov_b32_e32 v5, v1
	v_lshl_add_u64 v[4:5], v[106:107], 0, v[4:5]
	global_store_dwordx2 v[4:5], v[2:3], off
	v_lshlrev_b32_e32 v2, 16, v211
	v_and_b32_e32 v4, 0xffff0000, v211
	v_add_f32_e32 v3, 0, v2
	v_add_f32_e32 v5, 0, v4
	v_lshlrev_b32_e32 v6, 16, v212
	v_and_b32_e32 v7, 0xffff0000, v212
	v_add_f32_e32 v3, v3, v6
	v_add_f32_e32 v5, v5, v7
	v_lshlrev_b32_e32 v8, 16, v213
	v_and_b32_e32 v9, 0xffff0000, v213
	v_add_f32_e32 v3, v3, v8
	v_add_f32_e32 v5, v5, v9
	v_lshlrev_b32_e32 v10, 16, v214
	v_and_b32_e32 v11, 0xffff0000, v214
	v_add_f32_e32 v3, v3, v10
	v_add_f32_e32 v5, v5, v11
	v_lshlrev_b32_e32 v12, 16, v215
	v_and_b32_e32 v13, 0xffff0000, v215
	v_add_f32_e32 v3, v3, v12
	v_add_f32_e32 v5, v5, v13
	v_lshlrev_b32_e32 v14, 16, v216
	v_and_b32_e32 v15, 0xffff0000, v216
	v_rcp_iflag_f32_e32 v52, v52
	v_add_f32_e32 v3, v3, v14
	v_add_f32_e32 v5, v5, v15
	v_lshlrev_b32_e32 v16, 16, v218
	v_and_b32_e32 v17, 0xffff0000, v218
	v_add_f32_e32 v3, v3, v16
	v_add_f32_e32 v5, v5, v17
	v_add_f32_e32 v3, v3, v50
	v_add_f32_e32 v5, v5, v51
	v_fma_f32 v53, v52, v3, -v50
	v_fma_f32 v52, v52, v5, -v51
	v_cvt_pk_bf16_f32 v52, v53, v52
	s_waitcnt lgkmcnt(0)
	s_barrier
	ds_write_b32 v116, v52 offset:34816
	v_add_u32_e32 v52, s1, v127
	v_min_i32_e32 v52, 7, v52
	v_add_u32_e32 v52, 1, v52
	v_cvt_f32_i32_e32 v52, v52
	v_sub_f32_e32 v2, v3, v2
	v_sub_f32_e32 v3, v5, v4
	v_lshlrev_b32_e32 v4, 16, v191
	v_rcp_iflag_f32_e32 v52, v52
	v_and_b32_e32 v5, 0xffff0000, v191
	v_add_f32_e32 v2, v2, v4
	v_add_f32_e32 v3, v3, v5
	v_fma_f32 v53, v52, v2, -v4
	v_fma_f32 v52, v52, v3, -v5
	v_cvt_pk_bf16_f32 v52, v53, v52
	ds_write_b32 v117, v52 offset:34816
	v_add_u32_e32 v52, s1, v128
	v_min_i32_e32 v52, 7, v52
	v_add_u32_e32 v52, 1, v52
	v_cvt_f32_i32_e32 v52, v52
	v_sub_f32_e32 v2, v2, v6
	v_sub_f32_e32 v3, v3, v7
	v_lshlrev_b32_e32 v6, 16, v210
	v_rcp_iflag_f32_e32 v52, v52
	v_and_b32_e32 v7, 0xffff0000, v210
	v_add_f32_e32 v2, v2, v6
	v_add_f32_e32 v3, v3, v7
	v_fma_f32 v53, v52, v2, -v6
	v_fma_f32 v52, v52, v3, -v7
	v_cvt_pk_bf16_f32 v52, v53, v52
	ds_write_b32 v168, v52 offset:34816
	v_add_u32_e32 v52, s1, v129
	v_min_i32_e32 v52, 7, v52
	v_add_u32_e32 v52, 1, v52
	v_cvt_f32_i32_e32 v52, v52
	v_sub_f32_e32 v2, v2, v8
	v_sub_f32_e32 v3, v3, v9
	v_lshlrev_b32_e32 v8, 16, v209
	v_rcp_iflag_f32_e32 v52, v52
	v_and_b32_e32 v9, 0xffff0000, v209
	v_add_f32_e32 v2, v2, v8
	v_add_f32_e32 v3, v3, v9
	v_fma_f32 v53, v52, v2, -v8
	v_fma_f32 v52, v52, v3, -v9
	v_cvt_pk_bf16_f32 v52, v53, v52
	ds_write_b32 v169, v52 offset:34816
	v_add_u32_e32 v52, s1, v130
	v_min_i32_e32 v52, 7, v52
	v_add_u32_e32 v52, 1, v52
	v_cvt_f32_i32_e32 v52, v52
	v_sub_f32_e32 v2, v2, v10
	v_sub_f32_e32 v3, v3, v11
	v_lshlrev_b32_e32 v10, 16, v208
	v_rcp_iflag_f32_e32 v52, v52
	v_and_b32_e32 v11, 0xffff0000, v208
	v_add_f32_e32 v2, v2, v10
	v_add_f32_e32 v3, v3, v11
	v_fma_f32 v53, v52, v2, -v10
	v_fma_f32 v52, v52, v3, -v11
	v_cvt_pk_bf16_f32 v52, v53, v52
	ds_write_b32 v170, v52 offset:34816
	v_add_u32_e32 v52, s1, v131
	v_min_i32_e32 v52, 7, v52
	v_add_u32_e32 v52, 1, v52
	v_cvt_f32_i32_e32 v52, v52
	v_sub_f32_e32 v2, v2, v12
	v_sub_f32_e32 v3, v3, v13
	v_lshlrev_b32_e32 v12, 16, v207
	v_rcp_iflag_f32_e32 v52, v52
	v_and_b32_e32 v13, 0xffff0000, v207
	v_add_f32_e32 v2, v2, v12
	v_add_f32_e32 v3, v3, v13
	v_fma_f32 v53, v52, v2, -v12
	v_fma_f32 v52, v52, v3, -v13
	v_cvt_pk_bf16_f32 v52, v53, v52
	ds_write_b32 v171, v52 offset:34816
	v_add_u32_e32 v52, s1, v132
	v_min_i32_e32 v52, 7, v52
	v_add_u32_e32 v52, 1, v52
	v_cvt_f32_i32_e32 v52, v52
	v_sub_f32_e32 v2, v2, v14
	v_sub_f32_e32 v3, v3, v15
	v_lshlrev_b32_e32 v14, 16, v206
	v_rcp_iflag_f32_e32 v52, v52
	v_and_b32_e32 v15, 0xffff0000, v206
	v_add_f32_e32 v2, v2, v14
	v_add_f32_e32 v3, v3, v15
	v_fma_f32 v53, v52, v2, -v14
	v_fma_f32 v52, v52, v3, -v15
	v_cvt_pk_bf16_f32 v52, v53, v52
	ds_write_b32 v172, v52 offset:34816
	v_add_u32_e32 v52, s1, v133
	v_min_i32_e32 v52, 7, v52
	v_add_u32_e32 v52, 1, v52
	v_cvt_f32_i32_e32 v52, v52
	v_sub_f32_e32 v2, v2, v16
	v_sub_f32_e32 v3, v3, v17
	v_lshlrev_b32_e32 v16, 16, v205
	v_rcp_iflag_f32_e32 v52, v52
	v_and_b32_e32 v17, 0xffff0000, v205
	v_add_f32_e32 v2, v2, v16
	v_add_f32_e32 v3, v3, v17
	v_fma_f32 v53, v52, v2, -v16
	v_fma_f32 v52, v52, v3, -v17
	v_cvt_pk_bf16_f32 v52, v53, v52
	ds_write_b32 v173, v52 offset:34816
	v_add_u32_e32 v52, s1, v134
	v_min_i32_e32 v52, 7, v52
	v_add_u32_e32 v52, 1, v52
	v_cvt_f32_i32_e32 v52, v52
	v_sub_f32_e32 v2, v2, v50
	v_lshlrev_b32_e32 v50, 16, v204
	v_sub_f32_e32 v3, v3, v51
	v_rcp_iflag_f32_e32 v52, v52
	v_and_b32_e32 v51, 0xffff0000, v204
	v_add_f32_e32 v2, v2, v50
	v_add_f32_e32 v3, v3, v51
	v_fma_f32 v50, v52, v2, -v50
	v_fma_f32 v51, v52, v3, -v51
	v_cvt_pk_bf16_f32 v50, v50, v51
	ds_write_b32 v174, v50 offset:34816
	v_add_u32_e32 v50, s1, v135
	v_min_i32_e32 v50, 7, v50
	v_add_u32_e32 v50, 1, v50
	v_cvt_f32_i32_e32 v50, v50
	v_sub_f32_e32 v2, v2, v4
	v_lshlrev_b32_e32 v4, 16, v192
	v_add_f32_e32 v2, v2, v4
	v_rcp_iflag_f32_e32 v50, v50
	v_sub_f32_e32 v3, v3, v5
	v_and_b32_e32 v5, 0xffff0000, v192
	v_add_f32_e32 v3, v3, v5
	v_fma_f32 v4, v50, v2, -v4
	v_sub_f32_e32 v2, v2, v6
	v_add_u32_e32 v6, s1, v136
	v_min_i32_e32 v6, 7, v6
	v_add_u32_e32 v6, 1, v6
	v_cvt_f32_i32_e32 v6, v6
	v_fma_f32 v5, v50, v3, -v5
	v_cvt_pk_bf16_f32 v4, v4, v5
	ds_write_b32 v175, v4 offset:34816
	v_rcp_iflag_f32_e32 v6, v6
	v_sub_f32_e32 v3, v3, v7
	v_lshlrev_b32_e32 v4, 16, v190
	v_and_b32_e32 v5, 0xffff0000, v190
	v_add_f32_e32 v2, v2, v4
	v_add_f32_e32 v3, v3, v5
	v_fma_f32 v4, v6, v2, -v4
	v_fma_f32 v5, v6, v3, -v5
	v_add_u32_e32 v6, s1, v137
	v_min_i32_e32 v6, 7, v6
	v_add_u32_e32 v6, 1, v6
	v_cvt_f32_i32_e32 v6, v6
	v_cvt_pk_bf16_f32 v4, v4, v5
	ds_write_b32 v176, v4 offset:34816
	v_sub_f32_e32 v2, v2, v8
	v_rcp_iflag_f32_e32 v6, v6
	v_sub_f32_e32 v3, v3, v9
	v_lshlrev_b32_e32 v4, 16, v189
	v_and_b32_e32 v5, 0xffff0000, v189
	v_add_f32_e32 v2, v2, v4
	v_add_f32_e32 v3, v3, v5
	v_fma_f32 v4, v6, v2, -v4
	v_fma_f32 v5, v6, v3, -v5
	v_add_u32_e32 v6, s1, v138
	v_min_i32_e32 v6, 7, v6
	v_add_u32_e32 v6, 1, v6
	v_cvt_f32_i32_e32 v6, v6
	v_cvt_pk_bf16_f32 v4, v4, v5
	ds_write_b32 v177, v4 offset:34816
	v_sub_f32_e32 v2, v2, v10
	v_rcp_iflag_f32_e32 v6, v6
	v_sub_f32_e32 v3, v3, v11
	v_lshlrev_b32_e32 v4, 16, v188
	v_and_b32_e32 v5, 0xffff0000, v188
	v_add_f32_e32 v2, v2, v4
	v_add_f32_e32 v3, v3, v5
	v_fma_f32 v4, v6, v2, -v4
	v_fma_f32 v5, v6, v3, -v5
	v_add_u32_e32 v6, s1, v139
	v_min_i32_e32 v6, 7, v6
	v_add_u32_e32 v6, 1, v6
	v_cvt_f32_i32_e32 v6, v6
	v_cvt_pk_bf16_f32 v4, v4, v5
	ds_write_b32 v178, v4 offset:34816
	v_sub_f32_e32 v2, v2, v12
	v_rcp_iflag_f32_e32 v6, v6
	v_sub_f32_e32 v3, v3, v13
	v_lshlrev_b32_e32 v4, 16, v187
	v_and_b32_e32 v5, 0xffff0000, v187
	v_add_f32_e32 v2, v2, v4
	v_add_f32_e32 v3, v3, v5
	v_fma_f32 v4, v6, v2, -v4
	v_fma_f32 v5, v6, v3, -v5
	v_add_u32_e32 v6, s1, v140
	v_min_i32_e32 v6, 7, v6
	v_add_u32_e32 v6, 1, v6
	v_cvt_f32_i32_e32 v6, v6
	v_cvt_pk_bf16_f32 v4, v4, v5
	ds_write_b32 v179, v4 offset:34816
	v_sub_f32_e32 v2, v2, v14
	v_rcp_iflag_f32_e32 v6, v6
	v_sub_f32_e32 v3, v3, v15
	v_lshlrev_b32_e32 v4, 16, v186
	v_and_b32_e32 v5, 0xffff0000, v186
	v_add_f32_e32 v2, v2, v4
	v_add_f32_e32 v3, v3, v5
	v_fma_f32 v4, v6, v2, -v4
	v_fma_f32 v5, v6, v3, -v5
	v_add_u32_e32 v6, s1, v141
	v_min_i32_e32 v6, 7, v6
	v_add_u32_e32 v6, 1, v6
	v_cvt_f32_i32_e32 v6, v6
	v_cvt_pk_bf16_f32 v4, v4, v5
	ds_write_b32 v180, v4 offset:34816
	v_sub_f32_e32 v2, v2, v16
	v_rcp_iflag_f32_e32 v6, v6
	v_lshlrev_b32_e32 v4, 16, v182
	v_sub_f32_e32 v3, v3, v17
	v_and_b32_e32 v5, 0xffff0000, v182
	v_add_f32_e32 v2, v2, v4
	v_add_f32_e32 v3, v3, v5
	v_fma_f32 v2, v6, v2, -v4
	v_fma_f32 v3, v6, v3, -v5
	v_cvt_pk_bf16_f32 v2, v2, v3
	ds_write_b32 v181, v2 offset:34816
	v_add_u32_e32 v2, s0, v142
	v_ashrrev_i32_e32 v3, 31, v2
	v_lshlrev_b64 v[2:3], 12, v[2:3]
	s_waitcnt lgkmcnt(0)
	s_barrier
	v_lshl_add_u64 v[2:3], s[70:71], 0, v[2:3]
	ds_read_b128 v[74:77], v185 offset:34816
	ds_read_b128 v[78:81], v185 offset:34848
	ds_read_b128 v[70:73], v185 offset:34880
	ds_read_b128 v[66:69], v185 offset:34912
	ds_read_b128 v[62:65], v185 offset:34944
	ds_read_b128 v[58:61], v185 offset:34976
	ds_read_b128 v[54:57], v185 offset:35008
	ds_read_b128 v[50:53], v185 offset:35040
	v_lshl_add_u64 v[106:107], v[2:3], 0, s[2:3]
	ds_read_b128 v[2:5], v183
	ds_read_b128 v[168:171], v183 offset:32
	s_waitcnt lgkmcnt(1)
	v_mfma_f32_32x32x16_bf16 v[2:17], v[2:5], v[74:77], 0
	s_waitcnt lgkmcnt(0)
	v_mfma_f32_32x32x16_bf16 v[2:17], v[168:171], v[78:81], v[2:17]
	ds_read_b128 v[168:171], v183 offset:64
	s_waitcnt lgkmcnt(0)
	v_mfma_f32_32x32x16_bf16 v[2:17], v[168:171], v[70:73], v[2:17]
	ds_read_b128 v[168:171], v183 offset:96
	s_waitcnt lgkmcnt(0)
	v_mfma_f32_32x32x16_bf16 v[2:17], v[168:171], v[66:69], v[2:17]
	ds_read_b128 v[168:171], v183 offset:128
	s_waitcnt lgkmcnt(0)
	v_mfma_f32_32x32x16_bf16 v[2:17], v[168:171], v[62:65], v[2:17]
	ds_read_b128 v[168:171], v183 offset:160
	s_waitcnt lgkmcnt(0)
	v_mfma_f32_32x32x16_bf16 v[2:17], v[168:171], v[58:61], v[2:17]
	ds_read_b128 v[168:171], v183 offset:192
	s_waitcnt lgkmcnt(0)
	v_mfma_f32_32x32x16_bf16 v[2:17], v[168:171], v[54:57], v[2:17]
	ds_read_b128 v[168:171], v183 offset:224
	s_waitcnt lgkmcnt(0)
	v_mfma_f32_32x32x16_bf16 v[2:17], v[168:171], v[50:53], v[2:17]
	s_nop 11
	v_mul_f32_e32 v2, v46, v2
	v_mul_f32_e32 v3, v47, v3
	v_cvt_pk_bf16_f32 v2, v2, v3
	v_mul_f32_e32 v3, v48, v4
	v_mul_f32_e32 v4, v49, v5
	v_cvt_pk_bf16_f32 v3, v3, v4
	v_lshl_add_u64 v[4:5], v[106:107], 0, v[0:1]
	global_store_dwordx2 v[4:5], v[2:3], off
	v_mul_f32_e32 v0, v42, v6
	v_mul_f32_e32 v2, v43, v7
	v_mul_f32_e32 v3, v45, v9
	v_cvt_pk_bf16_f32 v2, v0, v2
	v_mul_f32_e32 v0, v44, v8
	v_cvt_pk_bf16_f32 v3, v0, v3
	v_lshl_add_u64 v[4:5], v[106:107], 0, v[104:105]
	global_store_dwordx2 v[4:5], v[2:3], off
	v_mul_f32_e32 v0, v38, v10
	v_mul_f32_e32 v2, v39, v11
	v_mul_f32_e32 v3, v41, v13
	v_cvt_pk_bf16_f32 v2, v0, v2
	v_mul_f32_e32 v0, v40, v12
	v_cvt_pk_bf16_f32 v3, v0, v3
	v_lshl_add_u64 v[4:5], v[106:107], 0, v[108:109]
	global_store_dwordx2 v[4:5], v[2:3], off
	v_mul_f32_e32 v0, v34, v14
	v_mul_f32_e32 v2, v35, v15
	v_mul_f32_e32 v3, v37, v17
	v_lshl_add_u64 v[4:5], v[106:107], 0, v[102:103]
	v_cvt_pk_bf16_f32 v2, v0, v2
	v_mul_f32_e32 v0, v36, v16
	v_cvt_pk_bf16_f32 v3, v0, v3
	global_store_dwordx2 v[4:5], v[2:3], off
	ds_read_b128 v[2:5], v184
	ds_read_b128 v[34:37], v184 offset:32
	s_waitcnt lgkmcnt(1)
	v_mfma_f32_32x32x16_bf16 v[2:17], v[2:5], v[74:77], 0
	s_waitcnt lgkmcnt(0)
	v_mfma_f32_32x32x16_bf16 v[2:17], v[34:37], v[78:81], v[2:17]
	ds_read_b128 v[34:37], v184 offset:64
	s_waitcnt lgkmcnt(0)
	v_mfma_f32_32x32x16_bf16 v[2:17], v[34:37], v[70:73], v[2:17]
	ds_read_b128 v[34:37], v184 offset:96
	s_waitcnt lgkmcnt(0)
	v_mfma_f32_32x32x16_bf16 v[2:17], v[34:37], v[66:69], v[2:17]
	ds_read_b128 v[34:37], v184 offset:128
	s_waitcnt lgkmcnt(0)
	v_mfma_f32_32x32x16_bf16 v[2:17], v[34:37], v[62:65], v[2:17]
	ds_read_b128 v[34:37], v184 offset:160
	s_waitcnt lgkmcnt(0)
	v_mfma_f32_32x32x16_bf16 v[2:17], v[34:37], v[58:61], v[2:17]
	ds_read_b128 v[34:37], v184 offset:192
	s_waitcnt lgkmcnt(0)
	v_mfma_f32_32x32x16_bf16 v[2:17], v[34:37], v[54:57], v[2:17]
	ds_read_b128 v[34:37], v184 offset:224
	s_waitcnt lgkmcnt(0)
	v_mfma_f32_32x32x16_bf16 v[2:17], v[34:37], v[50:53], v[2:17]
	s_nop 11
	v_mul_f32_e32 v0, v30, v2
	v_mul_f32_e32 v2, v31, v3
	v_mul_f32_e32 v3, v33, v5
	v_cvt_pk_bf16_f32 v2, v0, v2
	v_mul_f32_e32 v0, v32, v4
	v_cvt_pk_bf16_f32 v3, v0, v3
	v_lshl_add_u64 v[4:5], v[106:107], 0, v[110:111]
	global_store_dwordx2 v[4:5], v[2:3], off
	v_mul_f32_e32 v0, v26, v6
	v_mul_f32_e32 v2, v27, v7
	v_mul_f32_e32 v3, v29, v9
	v_cvt_pk_bf16_f32 v2, v0, v2
	v_mul_f32_e32 v0, v28, v8
	v_cvt_pk_bf16_f32 v3, v0, v3
	v_lshl_add_u64 v[4:5], v[106:107], 0, v[112:113]
	global_store_dwordx2 v[4:5], v[2:3], off
	v_mul_f32_e32 v0, v22, v10
	v_mul_f32_e32 v2, v23, v11
	v_mul_f32_e32 v3, v25, v13
	v_cvt_pk_bf16_f32 v2, v0, v2
	v_mul_f32_e32 v0, v24, v12
	v_cvt_pk_bf16_f32 v3, v0, v3
	v_lshl_add_u64 v[4:5], v[106:107], 0, v[114:115]
	global_store_dwordx2 v[4:5], v[2:3], off
	v_mul_f32_e32 v0, v18, v14
	v_mul_f32_e32 v2, v19, v15
	v_mul_f32_e32 v3, v21, v17
	v_cvt_pk_bf16_f32 v2, v0, v2
	v_mul_f32_e32 v0, v20, v16
	v_cvt_pk_bf16_f32 v3, v0, v3

.LBB0_227:
	s_or_b64 exec, exec, s[40:41]
	v_add_u32_e32 v54, s95, v83
	v_min_i32_e32 v54, 1, v54
	v_add_u32_e32 v54, 1, v54
	v_cvt_f32_i32_e32 v54, v54
	s_waitcnt vmcnt(24)
	v_cndmask_b32_e32 v9, 0, v9, vcc
	s_waitcnt vmcnt(8)
	v_cndmask_b32_e64 v0, 0, v50, s[34:35]
	v_cndmask_b32_e64 v10, 0, v10, s[0:1]
	v_rcp_iflag_f32_e32 v54, v54
	v_lshlrev_b32_e32 v50, 16, v9
	v_and_b32_e32 v9, 0xffff0000, v9
	v_add_f32_e32 v51, 0, v50
	v_add_f32_e32 v52, 0, v9
	v_lshlrev_b32_e32 v53, 16, v10
	v_and_b32_e32 v10, 0xffff0000, v10
	v_add_f32_e32 v51, v51, v53
	v_add_f32_e32 v52, v52, v10
	v_fma_f32 v55, v54, v51, -v53
	v_fma_f32 v54, v54, v52, -v10
	v_sub_f32_e32 v9, v52, v9
	v_add_u32_e32 v52, s95, v127
	v_min_i32_e32 v52, 1, v52
	v_add_u32_e32 v52, 1, v52
	v_cvt_f32_i32_e32 v52, v52
	v_cndmask_b32_e64 v11, v11, 0, s[2:3]
	v_sub_f32_e32 v50, v51, v50
	v_lshlrev_b32_e32 v51, 16, v11
	v_rcp_iflag_f32_e32 v52, v52
	v_and_b32_e32 v11, 0xffff0000, v11
	v_cvt_pk_bf16_f32 v54, v55, v54
	v_add_u32_e32 v168, 0, v145
	v_add_f32_e32 v50, v50, v51
	v_add_f32_e32 v9, v9, v11
	s_waitcnt lgkmcnt(0)
	s_barrier
	ds_write_b32 v168, v54 offset:34816
	v_fma_f32 v54, v52, v50, -v51
	v_fma_f32 v52, v52, v9, -v11
	v_cvt_pk_bf16_f32 v52, v54, v52
	v_add_u32_e32 v169, 0, v146
	ds_write_b32 v169, v52 offset:34816
	v_add_u32_e32 v52, s95, v128
	v_min_i32_e32 v52, 1, v52
	v_add_u32_e32 v52, 1, v52
	v_cvt_f32_i32_e32 v52, v52
	v_cndmask_b32_e64 v12, 0, v12, s[6:7]
	v_sub_f32_e32 v50, v50, v53
	v_sub_f32_e32 v9, v9, v10
	v_rcp_iflag_f32_e32 v52, v52
	v_lshlrev_b32_e32 v10, 16, v12
	v_add_f32_e32 v50, v50, v10
	v_and_b32_e32 v12, 0xffff0000, v12
	v_fma_f32 v53, v52, v50, -v10
	v_sub_f32_e32 v50, v50, v51
	v_add_u32_e32 v51, s95, v129
	v_min_i32_e32 v51, 1, v51
	v_add_u32_e32 v51, 1, v51
	v_cvt_f32_i32_e32 v51, v51
	v_cndmask_b32_e64 v13, 0, v13, s[8:9]
	v_add_f32_e32 v9, v9, v12
	v_fma_f32 v52, v52, v9, -v12
	v_rcp_iflag_f32_e32 v51, v51
	v_sub_f32_e32 v9, v9, v11
	v_lshlrev_b32_e32 v11, 16, v13
	v_cvt_pk_bf16_f32 v52, v53, v52
	v_add_u32_e32 v170, 0, v147
	v_add_f32_e32 v50, v50, v11
	ds_write_b32 v170, v52 offset:34816
	v_fma_f32 v52, v51, v50, -v11
	v_sub_f32_e32 v10, v50, v10
	v_add_u32_e32 v50, s95, v130
	v_min_i32_e32 v50, 1, v50
	v_add_u32_e32 v50, 1, v50
	v_cvt_f32_i32_e32 v50, v50
	v_and_b32_e32 v13, 0xffff0000, v13
	v_cndmask_b32_e64 v14, 0, v14, s[10:11]
	v_add_f32_e32 v9, v9, v13
	v_rcp_iflag_f32_e32 v50, v50
	v_fma_f32 v51, v51, v9, -v13
	v_sub_f32_e32 v9, v9, v12
	v_lshlrev_b32_e32 v12, 16, v14
	v_and_b32_e32 v14, 0xffff0000, v14
	v_cndmask_b32_e64 v15, 0, v15, s[12:13]
	v_cvt_pk_bf16_f32 v51, v52, v51
	v_add_u32_e32 v171, 0, v148
	v_add_f32_e32 v10, v10, v12
	v_add_f32_e32 v9, v9, v14
	ds_write_b32 v171, v51 offset:34816
	v_fma_f32 v51, v50, v10, -v12
	v_fma_f32 v50, v50, v9, -v14
	v_sub_f32_e32 v10, v10, v11
	v_sub_f32_e32 v9, v9, v13
	v_lshlrev_b32_e32 v11, 16, v15
	v_and_b32_e32 v13, 0xffff0000, v15
	v_add_u32_e32 v15, s95, v131
	v_min_i32_e32 v15, 1, v15
	v_add_u32_e32 v15, 1, v15
	v_cvt_f32_i32_e32 v15, v15
	v_cvt_pk_bf16_f32 v50, v51, v50
	v_add_u32_e32 v172, 0, v149
	v_add_f32_e32 v10, v10, v11
	v_rcp_iflag_f32_e32 v15, v15
	v_add_f32_e32 v9, v9, v13
	ds_write_b32 v172, v50 offset:34816
	v_add_u32_e32 v173, 0, v150
	v_fma_f32 v50, v15, v10, -v11
	v_fma_f32 v15, v15, v9, -v13
	v_cvt_pk_bf16_f32 v15, v50, v15
	ds_write_b32 v173, v15 offset:34816
	v_add_u32_e32 v15, s95, v132
	v_min_i32_e32 v15, 1, v15
	v_add_u32_e32 v15, 1, v15
	v_cvt_f32_i32_e32 v15, v15
	v_cndmask_b32_e64 v16, 0, v16, s[14:15]
	v_sub_f32_e32 v10, v10, v12
	v_sub_f32_e32 v9, v9, v14
	v_rcp_iflag_f32_e32 v15, v15
	v_lshlrev_b32_e32 v12, 16, v16
	v_and_b32_e32 v14, 0xffff0000, v16
	v_add_f32_e32 v10, v10, v12
	v_add_f32_e32 v9, v9, v14
	v_fma_f32 v16, v15, v10, -v12
	v_fma_f32 v15, v15, v9, -v14
	v_cvt_pk_bf16_f32 v15, v16, v15
	v_add_u32_e32 v174, 0, v151
	ds_write_b32 v174, v15 offset:34816
	v_add_u32_e32 v15, s95, v133
	v_min_i32_e32 v15, 1, v15
	v_add_u32_e32 v15, 1, v15
	v_cvt_f32_i32_e32 v15, v15
	v_cndmask_b32_e64 v17, 0, v17, s[16:17]
	v_sub_f32_e32 v10, v10, v11
	v_sub_f32_e32 v9, v9, v13
	v_rcp_iflag_f32_e32 v15, v15
	v_lshlrev_b32_e32 v11, 16, v17
	v_and_b32_e32 v13, 0xffff0000, v17
	v_add_f32_e32 v10, v10, v11
	v_add_f32_e32 v9, v9, v13
	v_fma_f32 v16, v15, v10, -v11
	v_fma_f32 v15, v15, v9, -v13
	v_sub_f32_e32 v9, v9, v14
	v_add_u32_e32 v14, s95, v134
	v_min_i32_e32 v14, 1, v14
	v_add_u32_e32 v14, 1, v14
	v_cvt_f32_i32_e32 v14, v14
	v_cndmask_b32_e64 v8, 0, v8, s[18:19]
	v_sub_f32_e32 v10, v10, v12
	v_lshlrev_b32_e32 v12, 16, v8
	v_rcp_iflag_f32_e32 v14, v14
	v_and_b32_e32 v8, 0xffff0000, v8
	v_cvt_pk_bf16_f32 v15, v16, v15
	v_add_u32_e32 v175, 0, v152
	v_add_f32_e32 v10, v10, v12
	v_add_f32_e32 v9, v9, v8
	ds_write_b32 v175, v15 offset:34816
	v_fma_f32 v15, v14, v10, -v12
	v_fma_f32 v14, v14, v9, -v8
	v_sub_f32_e32 v9, v9, v13
	v_add_u32_e32 v13, s95, v135
	v_min_i32_e32 v13, 1, v13
	v_add_u32_e32 v13, 1, v13
	v_cvt_f32_i32_e32 v13, v13
	v_cndmask_b32_e64 v7, 0, v7, s[20:21]
	v_sub_f32_e32 v10, v10, v11
	v_lshlrev_b32_e32 v11, 16, v7
	v_rcp_iflag_f32_e32 v13, v13
	v_cvt_pk_bf16_f32 v14, v15, v14
	v_add_u32_e32 v176, 0, v153
	v_add_f32_e32 v10, v10, v11
	ds_write_b32 v176, v14 offset:34816
	v_fma_f32 v14, v13, v10, -v11
	v_sub_f32_e32 v10, v10, v12
	v_add_u32_e32 v12, s95, v136
	v_min_i32_e32 v12, 1, v12
	v_add_u32_e32 v12, 1, v12
	v_cvt_f32_i32_e32 v12, v12
	v_and_b32_e32 v7, 0xffff0000, v7
	v_cndmask_b32_e64 v6, 0, v6, s[22:23]
	v_add_f32_e32 v9, v9, v7
	v_rcp_iflag_f32_e32 v12, v12
	v_fma_f32 v13, v13, v9, -v7
	v_sub_f32_e32 v8, v9, v8
	v_lshlrev_b32_e32 v9, 16, v6
	v_cvt_pk_bf16_f32 v13, v14, v13
	v_add_u32_e32 v177, 0, v154
	v_add_f32_e32 v10, v10, v9
	ds_write_b32 v177, v13 offset:34816
	v_fma_f32 v13, v12, v10, -v9
	v_sub_f32_e32 v10, v10, v11
	v_add_u32_e32 v11, s95, v137
	v_min_i32_e32 v11, 1, v11
	v_add_u32_e32 v11, 1, v11
	v_cvt_f32_i32_e32 v11, v11
	v_and_b32_e32 v6, 0xffff0000, v6
	v_cndmask_b32_e64 v5, 0, v5, s[24:25]
	v_add_f32_e32 v8, v8, v6
	v_rcp_iflag_f32_e32 v11, v11
	v_fma_f32 v12, v12, v8, -v6
	v_sub_f32_e32 v7, v8, v7
	v_lshlrev_b32_e32 v8, 16, v5
	v_cvt_pk_bf16_f32 v12, v13, v12
	v_add_u32_e32 v178, 0, v155
	v_add_f32_e32 v10, v10, v8
	ds_write_b32 v178, v12 offset:34816
	v_fma_f32 v12, v11, v10, -v8
	v_sub_f32_e32 v9, v10, v9
	v_add_u32_e32 v10, s95, v138
	v_min_i32_e32 v10, 1, v10
	v_add_u32_e32 v10, 1, v10
	v_cvt_f32_i32_e32 v10, v10
	v_and_b32_e32 v5, 0xffff0000, v5
	v_cndmask_b32_e64 v4, 0, v4, s[26:27]
	v_add_f32_e32 v7, v7, v5
	v_rcp_iflag_f32_e32 v10, v10
	v_fma_f32 v11, v11, v7, -v5
	v_sub_f32_e32 v6, v7, v6
	v_lshlrev_b32_e32 v7, 16, v4
	v_cvt_pk_bf16_f32 v11, v12, v11
	v_add_u32_e32 v179, 0, v156
	v_add_f32_e32 v9, v9, v7
	ds_write_b32 v179, v11 offset:34816
	v_fma_f32 v11, v10, v9, -v7
	v_sub_f32_e32 v8, v9, v8
	v_add_u32_e32 v9, s95, v139
	v_min_i32_e32 v9, 1, v9
	v_add_u32_e32 v9, 1, v9
	v_cvt_f32_i32_e32 v9, v9
	v_and_b32_e32 v4, 0xffff0000, v4
	v_cndmask_b32_e64 v3, 0, v3, s[28:29]
	v_add_f32_e32 v6, v6, v4
	v_rcp_iflag_f32_e32 v9, v9
	v_fma_f32 v10, v10, v6, -v4
	v_sub_f32_e32 v5, v6, v5
	v_lshlrev_b32_e32 v6, 16, v3
	v_cvt_pk_bf16_f32 v10, v11, v10
	v_add_u32_e32 v180, 0, v157
	v_add_f32_e32 v8, v8, v6
	ds_write_b32 v180, v10 offset:34816
	v_fma_f32 v10, v9, v8, -v6
	v_sub_f32_e32 v7, v8, v7
	v_add_u32_e32 v8, s95, v140
	v_min_i32_e32 v8, 1, v8
	v_add_u32_e32 v8, 1, v8
	v_cvt_f32_i32_e32 v8, v8
	v_and_b32_e32 v3, 0xffff0000, v3
	v_cndmask_b32_e64 v2, 0, v2, s[38:39]
	v_add_f32_e32 v5, v5, v3
	v_rcp_iflag_f32_e32 v8, v8
	v_fma_f32 v9, v9, v5, -v3
	v_sub_f32_e32 v4, v5, v4
	v_lshlrev_b32_e32 v5, 16, v2
	v_and_b32_e32 v2, 0xffff0000, v2
	v_add_f32_e32 v7, v7, v5
	v_add_f32_e32 v4, v4, v2
	v_fma_f32 v5, v8, v7, -v5
	v_fma_f32 v2, v8, v4, -v2
	v_cvt_pk_bf16_f32 v2, v5, v2
	v_add_u32_e32 v5, s95, v141
	v_min_i32_e32 v5, 1, v5
	v_add_u32_e32 v5, 1, v5
	v_cvt_f32_i32_e32 v5, v5
	v_add_u32_e32 v181, 0, v158
	v_add_u32_e32 v182, 0, v159
	s_or_b32 s0, s94, 0x80
	v_rcp_iflag_f32_e32 v5, v5
	v_cvt_pk_bf16_f32 v9, v10, v9
	ds_write_b32 v181, v9 offset:34816
	ds_write_b32 v182, v2 offset:34816
	v_sub_f32_e32 v2, v7, v6
	v_sub_f32_e32 v3, v4, v3
	v_lshlrev_b32_e32 v4, 16, v0
	v_and_b32_e32 v0, 0xffff0000, v0
	s_xor_b32 s1, s95, 0xffffff7f
	s_mul_i32 s2, s0, 0x1e00
	v_add_f32_e32 v2, v2, v4
	v_add_f32_e32 v3, v3, v0
	s_mul_hi_i32 s3, s0, 0x1e00
	s_add_u32 s2, s91, s2
	v_fma_f32 v2, v5, v2, -v4
	v_fma_f32 v0, v5, v3, -v0
	s_addc_u32 s3, s92, s3
	v_mov_b32_e32 v105, v1
	v_cvt_pk_bf16_f32 v0, v2, v0
	v_add_u32_e32 v183, 0, v160
	v_cmp_lt_i32_e32 vcc, s1, v141
	v_lshl_add_u64 v[2:3], s[2:3], 0, v[104:105]
	s_mov_b64 s[2:3], 0x1420
	ds_write_b32 v183, v0 offset:34816
	v_lshl_add_u64 v[2:3], v[2:3], 0, s[2:3]
	v_cndmask_b32_e32 v0, 0, v141, vcc
	s_movk_i32 s6, 0x1e00
	v_mad_i64_i32 v[4:5], s[2:3], v0, s6, v[2:3]
	global_load_dword v0, v[4:5], off
	v_add_u32_e32 v186, v144, v143
	v_add_u32_e32 v185, v144, v161
	v_mov_b32_e32 v103, v1
	v_add_u32_e32 v184, v144, v163
	v_lshlrev_b32_e32 v116, 1, v98
	v_mov_b32_e32 v117, v1
	s_mov_b64 s[36:37], 0
	s_waitcnt vmcnt(0)
	v_cndmask_b32_e32 v105, 0, v0, vcc
	v_cmp_lt_i32_e32 vcc, s1, v126
	v_mov_b32_e32 v212, 0
	s_nop 0
	v_cndmask_b32_e32 v0, 0, v126, vcc
	v_mad_i64_i32 v[4:5], s[2:3], v0, s6, v[2:3]
	s_and_saveexec_b64 s[98:99], vcc
	global_load_dword v212, v[4:5], off
	s_mov_b64 exec, s[98:99]
	v_cmp_lt_i32_e32 vcc, s1, v83
	v_mov_b32_e32 v213, 0
	s_nop 0
	v_cndmask_b32_e32 v0, 0, v83, vcc
	v_mad_i64_i32 v[4:5], s[2:3], v0, s6, v[2:3]
	s_and_saveexec_b64 s[98:99], vcc
	global_load_dword v213, v[4:5], off
	s_mov_b64 exec, s[98:99]
	v_cmp_gt_i32_e32 vcc, s1, v83
	s_nop 1
	v_cndmask_b32_e64 v0, v127, 0, vcc
	v_mad_i64_i32 v[4:5], s[2:3], v0, s6, v[2:3]
	global_load_dword v0, v[4:5], off
	s_waitcnt vmcnt(0)
	v_cndmask_b32_e64 v191, v0, 0, vcc
	v_cmp_lt_i32_e32 vcc, s1, v128
	v_mov_b32_e32 v211, 0
	s_nop 0
	v_cndmask_b32_e32 v0, 0, v128, vcc
	v_mad_i64_i32 v[4:5], s[2:3], v0, s6, v[2:3]
	s_and_saveexec_b64 s[98:99], vcc
	global_load_dword v211, v[4:5], off
	s_mov_b64 exec, s[98:99]
	v_cmp_lt_i32_e32 vcc, s1, v129
	v_mov_b32_e32 v210, 0
	s_nop 0
	v_cndmask_b32_e32 v0, 0, v129, vcc
	v_mad_i64_i32 v[4:5], s[2:3], v0, s6, v[2:3]
	s_and_saveexec_b64 s[98:99], vcc
	global_load_dword v210, v[4:5], off
	s_mov_b64 exec, s[98:99]
	v_cmp_lt_i32_e32 vcc, s1, v130
	v_mov_b32_e32 v209, 0
	s_nop 0
	v_cndmask_b32_e32 v0, 0, v130, vcc
	v_mad_i64_i32 v[4:5], s[2:3], v0, s6, v[2:3]
	s_and_saveexec_b64 s[98:99], vcc
	global_load_dword v209, v[4:5], off
	s_mov_b64 exec, s[98:99]
	v_cmp_lt_i32_e32 vcc, s1, v131
	v_mov_b32_e32 v208, 0
	s_nop 0
	v_cndmask_b32_e32 v0, 0, v131, vcc
	v_mad_i64_i32 v[4:5], s[2:3], v0, s6, v[2:3]
	s_and_saveexec_b64 s[98:99], vcc
	global_load_dword v208, v[4:5], off
	s_mov_b64 exec, s[98:99]
	v_cmp_lt_i32_e32 vcc, s1, v132
	v_mov_b32_e32 v207, 0
	s_nop 0
	v_cndmask_b32_e32 v0, 0, v132, vcc
	v_mad_i64_i32 v[4:5], s[2:3], v0, s6, v[2:3]
	s_and_saveexec_b64 s[98:99], vcc
	global_load_dword v207, v[4:5], off
	s_mov_b64 exec, s[98:99]
	v_cmp_lt_i32_e32 vcc, s1, v133
	v_mov_b32_e32 v206, 0
	s_nop 0
	v_cndmask_b32_e32 v0, 0, v133, vcc
	v_mad_i64_i32 v[4:5], s[2:3], v0, s6, v[2:3]
	s_and_saveexec_b64 s[98:99], vcc
	global_load_dword v206, v[4:5], off
	s_mov_b64 exec, s[98:99]
	v_cmp_lt_i32_e32 vcc, s1, v134
	v_mov_b32_e32 v205, 0
	s_nop 0
	v_cndmask_b32_e32 v0, 0, v134, vcc
	v_mad_i64_i32 v[4:5], s[2:3], v0, s6, v[2:3]
	s_and_saveexec_b64 s[98:99], vcc
	global_load_dword v205, v[4:5], off
	s_mov_b64 exec, s[98:99]
	v_cmp_lt_i32_e32 vcc, s1, v135
	v_mov_b32_e32 v204, 0
	s_nop 0
	v_cndmask_b32_e32 v0, 0, v135, vcc
	v_mad_i64_i32 v[4:5], s[2:3], v0, s6, v[2:3]
	s_and_saveexec_b64 s[98:99], vcc
	global_load_dword v204, v[4:5], off
	s_mov_b64 exec, s[98:99]
	v_cmp_lt_i32_e32 vcc, s1, v136
	v_mov_b32_e32 v192, 0
	s_nop 0
	v_cndmask_b32_e32 v0, 0, v136, vcc
	v_mad_i64_i32 v[4:5], s[2:3], v0, s6, v[2:3]
	s_and_saveexec_b64 s[98:99], vcc
	global_load_dword v192, v[4:5], off
	s_mov_b64 exec, s[98:99]
	v_cmp_lt_i32_e32 vcc, s1, v137
	v_mov_b32_e32 v190, 0
	s_nop 0
	v_cndmask_b32_e32 v0, 0, v137, vcc
	v_mad_i64_i32 v[4:5], s[2:3], v0, s6, v[2:3]
	s_and_saveexec_b64 s[98:99], vcc
	global_load_dword v190, v[4:5], off
	s_mov_b64 exec, s[98:99]
	v_cmp_lt_i32_e32 vcc, s1, v138
	v_mov_b32_e32 v189, 0
	s_nop 0
	v_cndmask_b32_e32 v0, 0, v138, vcc
	v_mad_i64_i32 v[4:5], s[2:3], v0, s6, v[2:3]
	s_and_saveexec_b64 s[98:99], vcc
	global_load_dword v189, v[4:5], off
	s_mov_b64 exec, s[98:99]
	v_cmp_lt_i32_e32 vcc, s1, v139
	v_mov_b32_e32 v188, 0
	s_nop 0
	v_cndmask_b32_e32 v0, 0, v139, vcc
	v_mad_i64_i32 v[4:5], s[2:3], v0, s6, v[2:3]
	s_and_saveexec_b64 s[98:99], vcc
	global_load_dword v188, v[4:5], off
	s_mov_b64 exec, s[98:99]
	v_cmp_lt_i32_e32 vcc, s1, v140
	s_and_b32 s1, s0, 0xf80
	s_nop 0
	v_cndmask_b32_e32 v0, 0, v140, vcc
	v_mad_i64_i32 v[2:3], s[2:3], v0, s6, v[2:3]
	global_load_dword v0, v[2:3], off
	v_add_u32_e32 v2, s94, v142
	v_ashrrev_i32_e32 v3, 31, v2
	v_lshlrev_b64 v[2:3], 12, v[2:3]
	s_waitcnt lgkmcnt(0)
	s_barrier
	v_lshl_add_u64 v[2:3], s[70:71], 0, v[2:3]
	s_mov_b64 s[2:3], 0x26000800
	ds_read_b128 v[74:77], v186 offset:34816
	ds_read_b128 v[78:81], v186 offset:34848
	ds_read_b128 v[70:73], v186 offset:34880
	ds_read_b128 v[66:69], v186 offset:34912
	ds_read_b128 v[62:65], v186 offset:34944
	ds_read_b128 v[58:61], v186 offset:34976
	ds_read_b128 v[54:57], v186 offset:35008
	ds_read_b128 v[50:53], v186 offset:35040
	v_lshl_add_u64 v[106:107], v[2:3], 0, s[2:3]
	ds_read_b128 v[2:5], v185
	ds_read_b128 v[108:111], v185 offset:32
	s_waitcnt lgkmcnt(1)
	v_mfma_f32_32x32x16_bf16 v[2:17], v[2:5], v[74:77], 0
	s_waitcnt vmcnt(0)
	v_cndmask_b32_e32 v187, 0, v0, vcc
	s_waitcnt lgkmcnt(0)
	v_mfma_f32_32x32x16_bf16 v[2:17], v[108:111], v[78:81], v[2:17]
	ds_read_b128 v[108:111], v185 offset:64
	s_waitcnt lgkmcnt(0)
	v_mfma_f32_32x32x16_bf16 v[2:17], v[108:111], v[70:73], v[2:17]
	ds_read_b128 v[108:111], v185 offset:96
	s_waitcnt lgkmcnt(0)
	v_mfma_f32_32x32x16_bf16 v[2:17], v[108:111], v[66:69], v[2:17]
	ds_read_b128 v[108:111], v185 offset:128
	s_waitcnt lgkmcnt(0)
	v_mfma_f32_32x32x16_bf16 v[2:17], v[108:111], v[62:65], v[2:17]
	ds_read_b128 v[108:111], v185 offset:160
	s_waitcnt lgkmcnt(0)
	v_mfma_f32_32x32x16_bf16 v[2:17], v[108:111], v[58:61], v[2:17]
	ds_read_b128 v[108:111], v185 offset:192
	s_waitcnt lgkmcnt(0)
	v_mfma_f32_32x32x16_bf16 v[2:17], v[108:111], v[54:57], v[2:17]
	ds_read_b128 v[108:111], v185 offset:224
	s_waitcnt lgkmcnt(0)
	v_mfma_f32_32x32x16_bf16 v[2:17], v[108:111], v[50:53], v[2:17]
	v_lshlrev_b32_e32 v108, 1, v90
	v_mov_b32_e32 v109, v1
	v_lshlrev_b32_e32 v110, 1, v92
	v_mov_b32_e32 v111, v1
	s_nop 7
	v_mul_f32_e32 v0, v46, v2
	v_mul_f32_e32 v2, v47, v3
	v_cvt_pk_bf16_f32 v2, v0, v2
	v_mul_f32_e32 v0, v48, v4
	v_mul_f32_e32 v3, v49, v5
	v_cvt_pk_bf16_f32 v3, v0, v3
	v_lshlrev_b32_e32 v0, 1, v88
	v_lshl_add_u64 v[4:5], v[106:107], 0, v[0:1]
	global_store_dwordx2 v[4:5], v[2:3], off
	v_mul_f32_e32 v2, v42, v6
	v_mul_f32_e32 v3, v43, v7
	v_cvt_pk_bf16_f32 v2, v2, v3
	v_mul_f32_e32 v3, v44, v8
	v_mul_f32_e32 v4, v45, v9
	v_cvt_pk_bf16_f32 v3, v3, v4
	v_lshl_add_u64 v[4:5], v[106:107], 0, v[108:109]
	global_store_dwordx2 v[4:5], v[2:3], off
	v_mul_f32_e32 v2, v38, v10
	v_mul_f32_e32 v3, v39, v11
	v_cvt_pk_bf16_f32 v2, v2, v3
	v_mul_f32_e32 v3, v40, v12
	v_mul_f32_e32 v4, v41, v13
	v_cvt_pk_bf16_f32 v3, v3, v4
	v_lshl_add_u64 v[4:5], v[106:107], 0, v[110:111]
	global_store_dwordx2 v[4:5], v[2:3], off
	v_mul_f32_e32 v2, v34, v14
	v_mul_f32_e32 v3, v35, v15
	v_cvt_pk_bf16_f32 v2, v2, v3
	v_mul_f32_e32 v3, v36, v16
	v_mul_f32_e32 v4, v37, v17
	v_cvt_pk_bf16_f32 v3, v3, v4
	v_lshl_add_u64 v[4:5], v[106:107], 0, v[102:103]
	global_store_dwordx2 v[4:5], v[2:3], off
	ds_read_b128 v[2:5], v184
	ds_read_b128 v[112:115], v184 offset:32
	s_waitcnt lgkmcnt(1)
	v_mfma_f32_32x32x16_bf16 v[2:17], v[2:5], v[74:77], 0
	ds_read_b128 v[74:77], v184 offset:64
	s_waitcnt lgkmcnt(1)
	v_mfma_f32_32x32x16_bf16 v[2:17], v[112:115], v[78:81], v[2:17]
	v_lshlrev_b32_e32 v112, 1, v94
	v_mov_b32_e32 v113, v1
	v_lshlrev_b32_e32 v114, 1, v96
	v_mov_b32_e32 v115, v1
	s_waitcnt lgkmcnt(0)
	v_mfma_f32_32x32x16_bf16 v[2:17], v[74:77], v[70:73], v[2:17]
	ds_read_b128 v[70:73], v184 offset:96
	s_waitcnt lgkmcnt(0)
	v_mfma_f32_32x32x16_bf16 v[2:17], v[70:73], v[66:69], v[2:17]
	ds_read_b128 v[66:69], v184 offset:128
	s_waitcnt lgkmcnt(0)
	v_mfma_f32_32x32x16_bf16 v[2:17], v[66:69], v[62:65], v[2:17]
	ds_read_b128 v[62:65], v184 offset:160
	s_waitcnt lgkmcnt(0)
	v_mfma_f32_32x32x16_bf16 v[2:17], v[62:65], v[58:61], v[2:17]
	ds_read_b128 v[58:61], v184 offset:192
	s_waitcnt lgkmcnt(0)
	v_mfma_f32_32x32x16_bf16 v[2:17], v[58:61], v[54:57], v[2:17]
	ds_read_b128 v[54:57], v184 offset:224
	s_waitcnt lgkmcnt(0)
	v_mfma_f32_32x32x16_bf16 v[2:17], v[54:57], v[50:53], v[2:17]
	s_nop 11
	v_mul_f32_e32 v2, v30, v2
	v_mul_f32_e32 v3, v31, v3
	v_cvt_pk_bf16_f32 v2, v2, v3
	v_mul_f32_e32 v3, v32, v4
	v_mul_f32_e32 v4, v33, v5
	v_cvt_pk_bf16_f32 v3, v3, v4
	v_lshl_add_u64 v[4:5], v[106:107], 0, v[112:113]
	global_store_dwordx2 v[4:5], v[2:3], off
	v_mul_f32_e32 v2, v26, v6
	v_mul_f32_e32 v3, v27, v7
	v_cvt_pk_bf16_f32 v2, v2, v3
	v_mul_f32_e32 v3, v28, v8
	v_mul_f32_e32 v4, v29, v9
	v_cvt_pk_bf16_f32 v3, v3, v4
	v_lshl_add_u64 v[4:5], v[106:107], 0, v[114:115]
	v_add_u32_e32 v8, s1, v83
	global_store_dwordx2 v[4:5], v[2:3], off
	v_mul_f32_e32 v2, v22, v10
	v_mul_f32_e32 v3, v23, v11
	v_min_i32_e32 v8, 1, v8
	v_cvt_pk_bf16_f32 v2, v2, v3
	v_mul_f32_e32 v3, v24, v12
	v_mul_f32_e32 v4, v25, v13
	v_add_u32_e32 v8, 1, v8
	v_cvt_pk_bf16_f32 v3, v3, v4
	v_lshl_add_u64 v[4:5], v[106:107], 0, v[116:117]
	v_cvt_f32_i32_e32 v8, v8
	global_store_dwordx2 v[4:5], v[2:3], off
	v_mul_f32_e32 v2, v18, v14
	v_mul_f32_e32 v3, v19, v15
	v_cvt_pk_bf16_f32 v2, v2, v3
	v_mul_f32_e32 v3, v20, v16
	v_mul_f32_e32 v4, v21, v17
	v_cvt_pk_bf16_f32 v3, v3, v4
	v_lshlrev_b32_e32 v4, 1, v100
	v_mov_b32_e32 v5, v1
	v_lshl_add_u64 v[4:5], v[106:107], 0, v[4:5]
	v_rcp_iflag_f32_e32 v8, v8
	global_store_dwordx2 v[4:5], v[2:3], off
	v_lshlrev_b32_e32 v2, 16, v212
	v_and_b32_e32 v3, 0xffff0000, v212
	v_add_f32_e32 v4, 0, v2
	v_add_f32_e32 v5, 0, v3
	v_lshlrev_b32_e32 v6, 16, v213
	v_and_b32_e32 v7, 0xffff0000, v213
	v_add_f32_e32 v4, v4, v6
	v_add_f32_e32 v5, v5, v7
	v_fma_f32 v9, v8, v4, -v6
	v_fma_f32 v8, v8, v5, -v7
	v_cvt_pk_bf16_f32 v8, v9, v8
	s_waitcnt lgkmcnt(0)
	s_barrier
	ds_write_b32 v168, v8 offset:34816
	v_add_u32_e32 v8, s1, v127
	v_min_i32_e32 v8, 1, v8
	v_add_u32_e32 v8, 1, v8
	v_cvt_f32_i32_e32 v8, v8
	v_sub_f32_e32 v2, v4, v2
	v_sub_f32_e32 v3, v5, v3
	v_lshlrev_b32_e32 v4, 16, v191
	v_rcp_iflag_f32_e32 v8, v8
	v_and_b32_e32 v5, 0xffff0000, v191
	v_add_f32_e32 v2, v2, v4
	v_add_f32_e32 v3, v3, v5
	v_fma_f32 v9, v8, v2, -v4
	v_fma_f32 v8, v8, v3, -v5
	v_cvt_pk_bf16_f32 v8, v9, v8
	ds_write_b32 v169, v8 offset:34816
	v_add_u32_e32 v8, s1, v128
	v_min_i32_e32 v8, 1, v8
	v_add_u32_e32 v8, 1, v8
	v_cvt_f32_i32_e32 v8, v8
	v_sub_f32_e32 v2, v2, v6
	v_sub_f32_e32 v3, v3, v7
	v_lshlrev_b32_e32 v6, 16, v211
	v_rcp_iflag_f32_e32 v8, v8
	v_and_b32_e32 v7, 0xffff0000, v211
	v_add_f32_e32 v2, v2, v6
	v_add_f32_e32 v3, v3, v7
	v_fma_f32 v9, v8, v2, -v6
	v_fma_f32 v8, v8, v3, -v7
	v_cvt_pk_bf16_f32 v8, v9, v8
	ds_write_b32 v170, v8 offset:34816
	v_add_u32_e32 v8, s1, v129
	v_min_i32_e32 v8, 1, v8
	v_add_u32_e32 v8, 1, v8
	v_cvt_f32_i32_e32 v8, v8
	v_sub_f32_e32 v2, v2, v4
	v_sub_f32_e32 v3, v3, v5
	v_lshlrev_b32_e32 v4, 16, v210
	v_rcp_iflag_f32_e32 v8, v8
	v_and_b32_e32 v5, 0xffff0000, v210
	v_add_f32_e32 v2, v2, v4
	v_add_f32_e32 v3, v3, v5
	v_fma_f32 v9, v8, v2, -v4
	v_fma_f32 v8, v8, v3, -v5
	v_cvt_pk_bf16_f32 v8, v9, v8
	ds_write_b32 v171, v8 offset:34816
	v_add_u32_e32 v8, s1, v130
	v_min_i32_e32 v8, 1, v8
	v_add_u32_e32 v8, 1, v8
	v_cvt_f32_i32_e32 v8, v8
	v_sub_f32_e32 v2, v2, v6
	v_sub_f32_e32 v3, v3, v7
	v_lshlrev_b32_e32 v6, 16, v209
	v_rcp_iflag_f32_e32 v8, v8
	v_and_b32_e32 v7, 0xffff0000, v209
	v_add_f32_e32 v2, v2, v6
	v_add_f32_e32 v3, v3, v7
	v_fma_f32 v9, v8, v2, -v6
	v_fma_f32 v8, v8, v3, -v7
	v_cvt_pk_bf16_f32 v8, v9, v8
	ds_write_b32 v172, v8 offset:34816
	v_add_u32_e32 v8, s1, v131
	v_min_i32_e32 v8, 1, v8
	v_add_u32_e32 v8, 1, v8
	v_cvt_f32_i32_e32 v8, v8
	v_sub_f32_e32 v2, v2, v4
	v_sub_f32_e32 v3, v3, v5
	v_lshlrev_b32_e32 v4, 16, v208
	v_rcp_iflag_f32_e32 v8, v8
	v_and_b32_e32 v5, 0xffff0000, v208
	v_add_f32_e32 v2, v2, v4
	v_add_f32_e32 v3, v3, v5
	v_fma_f32 v9, v8, v2, -v4
	v_fma_f32 v8, v8, v3, -v5
	v_cvt_pk_bf16_f32 v8, v9, v8
	ds_write_b32 v173, v8 offset:34816
	v_add_u32_e32 v8, s1, v132
	v_min_i32_e32 v8, 1, v8
	v_add_u32_e32 v8, 1, v8
	v_cvt_f32_i32_e32 v8, v8
	v_sub_f32_e32 v2, v2, v6
	v_sub_f32_e32 v3, v3, v7
	v_lshlrev_b32_e32 v6, 16, v207
	v_rcp_iflag_f32_e32 v8, v8
	v_and_b32_e32 v7, 0xffff0000, v207
	v_add_f32_e32 v2, v2, v6
	v_add_f32_e32 v3, v3, v7
	v_fma_f32 v9, v8, v2, -v6
	v_fma_f32 v8, v8, v3, -v7
	v_cvt_pk_bf16_f32 v8, v9, v8
	ds_write_b32 v174, v8 offset:34816
	v_add_u32_e32 v8, s1, v133
	v_min_i32_e32 v8, 1, v8
	v_add_u32_e32 v8, 1, v8
	v_cvt_f32_i32_e32 v8, v8
	v_sub_f32_e32 v2, v2, v4
	v_sub_f32_e32 v3, v3, v5
	v_lshlrev_b32_e32 v4, 16, v206
	v_rcp_iflag_f32_e32 v8, v8
	v_and_b32_e32 v5, 0xffff0000, v206
	v_add_f32_e32 v2, v2, v4
	v_add_f32_e32 v3, v3, v5
	v_fma_f32 v9, v8, v2, -v4
	v_fma_f32 v8, v8, v3, -v5
	v_cvt_pk_bf16_f32 v8, v9, v8
	ds_write_b32 v175, v8 offset:34816
	v_add_u32_e32 v8, s1, v134
	v_min_i32_e32 v8, 1, v8
	v_add_u32_e32 v8, 1, v8
	v_cvt_f32_i32_e32 v8, v8
	v_sub_f32_e32 v2, v2, v6
	v_sub_f32_e32 v3, v3, v7
	v_lshlrev_b32_e32 v6, 16, v205
	v_rcp_iflag_f32_e32 v8, v8
	v_and_b32_e32 v7, 0xffff0000, v205
	v_add_f32_e32 v2, v2, v6
	v_add_f32_e32 v3, v3, v7
	v_fma_f32 v9, v8, v2, -v6
	v_fma_f32 v8, v8, v3, -v7
	v_cvt_pk_bf16_f32 v8, v9, v8
	ds_write_b32 v176, v8 offset:34816
	v_add_u32_e32 v8, s1, v135
	v_min_i32_e32 v8, 1, v8
	v_add_u32_e32 v8, 1, v8
	v_cvt_f32_i32_e32 v8, v8
	v_sub_f32_e32 v2, v2, v4
	v_sub_f32_e32 v3, v3, v5
	v_lshlrev_b32_e32 v4, 16, v204
	v_rcp_iflag_f32_e32 v8, v8
	v_and_b32_e32 v5, 0xffff0000, v204
	v_add_f32_e32 v2, v2, v4
	v_add_f32_e32 v3, v3, v5
	v_fma_f32 v9, v8, v2, -v4
	v_fma_f32 v8, v8, v3, -v5
	v_cvt_pk_bf16_f32 v8, v9, v8
	ds_write_b32 v177, v8 offset:34816
	v_add_u32_e32 v8, s1, v136
	v_min_i32_e32 v8, 1, v8
	v_add_u32_e32 v8, 1, v8
	v_cvt_f32_i32_e32 v8, v8
	v_sub_f32_e32 v2, v2, v6
	v_sub_f32_e32 v3, v3, v7
	v_lshlrev_b32_e32 v6, 16, v192
	v_rcp_iflag_f32_e32 v8, v8
	v_and_b32_e32 v7, 0xffff0000, v192
	v_add_f32_e32 v2, v2, v6
	v_add_f32_e32 v3, v3, v7
	v_fma_f32 v9, v8, v2, -v6
	v_fma_f32 v8, v8, v3, -v7
	v_cvt_pk_bf16_f32 v8, v9, v8
	ds_write_b32 v178, v8 offset:34816
	v_add_u32_e32 v8, s1, v137
	v_min_i32_e32 v8, 1, v8
	v_add_u32_e32 v8, 1, v8
	v_cvt_f32_i32_e32 v8, v8
	v_sub_f32_e32 v2, v2, v4
	v_sub_f32_e32 v3, v3, v5
	v_lshlrev_b32_e32 v4, 16, v190
	v_rcp_iflag_f32_e32 v8, v8
	v_and_b32_e32 v5, 0xffff0000, v190
	v_add_f32_e32 v2, v2, v4
	v_add_f32_e32 v3, v3, v5
	v_fma_f32 v9, v8, v2, -v4
	v_fma_f32 v8, v8, v3, -v5
	v_cvt_pk_bf16_f32 v8, v9, v8
	ds_write_b32 v179, v8 offset:34816
	v_add_u32_e32 v8, s1, v138
	v_min_i32_e32 v8, 1, v8
	v_add_u32_e32 v8, 1, v8
	v_cvt_f32_i32_e32 v8, v8
	v_sub_f32_e32 v2, v2, v6
	v_sub_f32_e32 v3, v3, v7
	v_lshlrev_b32_e32 v6, 16, v189
	v_rcp_iflag_f32_e32 v8, v8
	v_and_b32_e32 v7, 0xffff0000, v189
	v_add_f32_e32 v2, v2, v6
	v_add_f32_e32 v3, v3, v7
	v_fma_f32 v9, v8, v2, -v6
	v_fma_f32 v8, v8, v3, -v7
	v_cvt_pk_bf16_f32 v8, v9, v8
	ds_write_b32 v180, v8 offset:34816
	v_add_u32_e32 v8, s1, v139
	v_min_i32_e32 v8, 1, v8
	v_add_u32_e32 v8, 1, v8
	v_cvt_f32_i32_e32 v8, v8
	v_sub_f32_e32 v2, v2, v4
	v_sub_f32_e32 v3, v3, v5
	v_lshlrev_b32_e32 v4, 16, v188
	v_rcp_iflag_f32_e32 v8, v8
	v_and_b32_e32 v5, 0xffff0000, v188
	v_add_f32_e32 v2, v2, v4
	v_add_f32_e32 v3, v3, v5
	v_fma_f32 v9, v8, v2, -v4
	v_fma_f32 v8, v8, v3, -v5
	v_cvt_pk_bf16_f32 v8, v9, v8
	ds_write_b32 v181, v8 offset:34816
	v_add_u32_e32 v8, s1, v140
	v_min_i32_e32 v8, 1, v8
	v_add_u32_e32 v8, 1, v8
	v_cvt_f32_i32_e32 v8, v8
	v_sub_f32_e32 v2, v2, v6
	v_lshlrev_b32_e32 v6, 16, v187
	v_sub_f32_e32 v3, v3, v7
	v_rcp_iflag_f32_e32 v8, v8
	v_and_b32_e32 v7, 0xffff0000, v187
	v_add_f32_e32 v2, v2, v6
	v_add_f32_e32 v3, v3, v7
	v_fma_f32 v6, v8, v2, -v6
	v_fma_f32 v7, v8, v3, -v7
	v_cvt_pk_bf16_f32 v6, v6, v7
	ds_write_b32 v182, v6 offset:34816
	v_add_u32_e32 v6, s1, v141
	v_min_i32_e32 v6, 1, v6
	v_add_u32_e32 v6, 1, v6
	v_cvt_f32_i32_e32 v6, v6
	v_sub_f32_e32 v2, v2, v4
	v_lshlrev_b32_e32 v4, 16, v105
	v_sub_f32_e32 v3, v3, v5
	v_rcp_iflag_f32_e32 v6, v6
	v_and_b32_e32 v5, 0xffff0000, v105
	v_add_f32_e32 v2, v2, v4
	v_add_f32_e32 v3, v3, v5
	v_fma_f32 v2, v6, v2, -v4
	v_fma_f32 v3, v6, v3, -v5
	v_cvt_pk_bf16_f32 v2, v2, v3
	ds_write_b32 v183, v2 offset:34816
	v_add_u32_e32 v2, s0, v142
	v_ashrrev_i32_e32 v3, 31, v2
	v_lshlrev_b64 v[2:3], 12, v[2:3]
	s_waitcnt lgkmcnt(0)
	s_barrier
	v_lshl_add_u64 v[2:3], s[70:71], 0, v[2:3]
	ds_read_b128 v[74:77], v186 offset:34816
	ds_read_b128 v[78:81], v186 offset:34848
	ds_read_b128 v[70:73], v186 offset:34880
	ds_read_b128 v[66:69], v186 offset:34912
	ds_read_b128 v[62:65], v186 offset:34944
	ds_read_b128 v[58:61], v186 offset:34976
	ds_read_b128 v[54:57], v186 offset:35008
	ds_read_b128 v[50:53], v186 offset:35040
	v_lshl_add_u64 v[106:107], v[2:3], 0, s[2:3]
	ds_read_b128 v[2:5], v185
	ds_read_b128 v[168:171], v185 offset:32
	s_waitcnt lgkmcnt(1)
	v_mfma_f32_32x32x16_bf16 v[2:17], v[2:5], v[74:77], 0
	s_waitcnt lgkmcnt(0)
	v_mfma_f32_32x32x16_bf16 v[2:17], v[168:171], v[78:81], v[2:17]
	ds_read_b128 v[168:171], v185 offset:64
	s_waitcnt lgkmcnt(0)
	v_mfma_f32_32x32x16_bf16 v[2:17], v[168:171], v[70:73], v[2:17]
	ds_read_b128 v[168:171], v185 offset:96
	s_waitcnt lgkmcnt(0)
	v_mfma_f32_32x32x16_bf16 v[2:17], v[168:171], v[66:69], v[2:17]
	ds_read_b128 v[168:171], v185 offset:128
	s_waitcnt lgkmcnt(0)
	v_mfma_f32_32x32x16_bf16 v[2:17], v[168:171], v[62:65], v[2:17]
	ds_read_b128 v[168:171], v185 offset:160
	s_waitcnt lgkmcnt(0)
	v_mfma_f32_32x32x16_bf16 v[2:17], v[168:171], v[58:61], v[2:17]
	ds_read_b128 v[168:171], v185 offset:192
	s_waitcnt lgkmcnt(0)
	v_mfma_f32_32x32x16_bf16 v[2:17], v[168:171], v[54:57], v[2:17]
	ds_read_b128 v[168:171], v185 offset:224
	s_waitcnt lgkmcnt(0)
	v_mfma_f32_32x32x16_bf16 v[2:17], v[168:171], v[50:53], v[2:17]
	s_nop 11
	v_mul_f32_e32 v2, v46, v2
	v_mul_f32_e32 v3, v47, v3
	v_cvt_pk_bf16_f32 v2, v2, v3
	v_mul_f32_e32 v3, v48, v4
	v_mul_f32_e32 v4, v49, v5
	v_cvt_pk_bf16_f32 v3, v3, v4
	v_lshl_add_u64 v[4:5], v[106:107], 0, v[0:1]
	global_store_dwordx2 v[4:5], v[2:3], off
	v_mul_f32_e32 v0, v42, v6
	v_mul_f32_e32 v2, v43, v7
	v_mul_f32_e32 v3, v45, v9
	v_cvt_pk_bf16_f32 v2, v0, v2
	v_mul_f32_e32 v0, v44, v8
	v_cvt_pk_bf16_f32 v3, v0, v3
	v_lshl_add_u64 v[4:5], v[106:107], 0, v[108:109]
	global_store_dwordx2 v[4:5], v[2:3], off
	v_mul_f32_e32 v0, v38, v10
	v_mul_f32_e32 v2, v39, v11
	v_mul_f32_e32 v3, v41, v13
	v_cvt_pk_bf16_f32 v2, v0, v2
	v_mul_f32_e32 v0, v40, v12
	v_cvt_pk_bf16_f32 v3, v0, v3
	v_lshl_add_u64 v[4:5], v[106:107], 0, v[110:111]
	global_store_dwordx2 v[4:5], v[2:3], off
	v_mul_f32_e32 v0, v34, v14
	v_mul_f32_e32 v2, v35, v15
	v_mul_f32_e32 v3, v37, v17
	v_lshl_add_u64 v[4:5], v[106:107], 0, v[102:103]
	v_cvt_pk_bf16_f32 v2, v0, v2
	v_mul_f32_e32 v0, v36, v16
	v_cvt_pk_bf16_f32 v3, v0, v3
	global_store_dwordx2 v[4:5], v[2:3], off
	ds_read_b128 v[2:5], v184
	ds_read_b128 v[34:37], v184 offset:32
	s_waitcnt lgkmcnt(1)
	v_mfma_f32_32x32x16_bf16 v[2:17], v[2:5], v[74:77], 0
	s_waitcnt lgkmcnt(0)
	v_mfma_f32_32x32x16_bf16 v[2:17], v[34:37], v[78:81], v[2:17]
	ds_read_b128 v[34:37], v184 offset:64
	s_waitcnt lgkmcnt(0)
	v_mfma_f32_32x32x16_bf16 v[2:17], v[34:37], v[70:73], v[2:17]
	ds_read_b128 v[34:37], v184 offset:96
	s_waitcnt lgkmcnt(0)
	v_mfma_f32_32x32x16_bf16 v[2:17], v[34:37], v[66:69], v[2:17]
	ds_read_b128 v[34:37], v184 offset:128
	s_waitcnt lgkmcnt(0)
	v_mfma_f32_32x32x16_bf16 v[2:17], v[34:37], v[62:65], v[2:17]
	ds_read_b128 v[34:37], v184 offset:160
	s_waitcnt lgkmcnt(0)
	v_mfma_f32_32x32x16_bf16 v[2:17], v[34:37], v[58:61], v[2:17]
	ds_read_b128 v[34:37], v184 offset:192
	s_waitcnt lgkmcnt(0)
	v_mfma_f32_32x32x16_bf16 v[2:17], v[34:37], v[54:57], v[2:17]
	ds_read_b128 v[34:37], v184 offset:224
	s_waitcnt lgkmcnt(0)
	v_mfma_f32_32x32x16_bf16 v[2:17], v[34:37], v[50:53], v[2:17]
	s_nop 11
	v_mul_f32_e32 v0, v30, v2
	v_mul_f32_e32 v2, v31, v3
	v_mul_f32_e32 v3, v33, v5
	v_cvt_pk_bf16_f32 v2, v0, v2
	v_mul_f32_e32 v0, v32, v4
	v_cvt_pk_bf16_f32 v3, v0, v3
	v_lshl_add_u64 v[4:5], v[106:107], 0, v[112:113]
	global_store_dwordx2 v[4:5], v[2:3], off
	v_mul_f32_e32 v0, v26, v6
	v_mul_f32_e32 v2, v27, v7
	v_mul_f32_e32 v3, v29, v9
	v_cvt_pk_bf16_f32 v2, v0, v2
	v_mul_f32_e32 v0, v28, v8
	v_cvt_pk_bf16_f32 v3, v0, v3
	v_lshl_add_u64 v[4:5], v[106:107], 0, v[114:115]
	global_store_dwordx2 v[4:5], v[2:3], off
	v_mul_f32_e32 v0, v22, v10
	v_mul_f32_e32 v2, v23, v11
	v_mul_f32_e32 v3, v25, v13
	v_cvt_pk_bf16_f32 v2, v0, v2
	v_mul_f32_e32 v0, v24, v12
	v_cvt_pk_bf16_f32 v3, v0, v3
	v_lshl_add_u64 v[4:5], v[106:107], 0, v[116:117]
	global_store_dwordx2 v[4:5], v[2:3], off
	v_mul_f32_e32 v0, v18, v14
	v_mul_f32_e32 v2, v19, v15
	v_mul_f32_e32 v3, v21, v17
	v_cvt_pk_bf16_f32 v2, v0, v2
	v_mul_f32_e32 v0, v20, v16
	v_cvt_pk_bf16_f32 v3, v0, v3

.LBB0_324:
	s_or_b64 exec, exec, s[42:43]
	v_lshl_or_b32 v18, s44, 7, v155
	v_or_b32_e32 v144, s34, v18
	s_movk_i32 s37, 0x1e00
	v_mad_u64_u32 v[18:19], s[42:43], v144, s37, v[132:133]
	v_mad_i32_i24 v19, s35, v199, v19
	global_load_dwordx2 v[142:143], v[18:19], off
	global_load_dwordx2 v[140:141], v[18:19], off offset:16
	global_load_dwordx2 v[138:139], v[18:19], off offset:32
	global_load_dwordx2 v[136:137], v[18:19], off offset:48
	s_waitcnt lgkmcnt(0)
	s_barrier
	v_add_u32_e32 v196, 0x19800, v222
	ds_read_b32 v163, v156
	ds_read_b128 v[18:21], v196
	v_add_u32_e32 v191, 0x11000, v241
	ds_read_b128 v[34:37], v191
	ds_read_b128 v[38:41], v196 offset:32
	ds_read_b128 v[90:93], v191 offset:32
	ds_read_b128 v[200:203], v196 offset:64
	ds_read_b128 v[106:109], v191 offset:64
	ds_read_b128 v[94:97], v191 offset:96
	ds_read_b128 v[102:105], v191 offset:128
	ds_read_b128 v[86:89], v191 offset:160
	ds_read_b128 v[98:101], v191 offset:192
	ds_read_b128 v[82:85], v191 offset:224
	v_mov_b32_e32 v145, s35
	s_waitcnt lgkmcnt(9)
	v_mfma_f32_32x32x16_bf16 v[18:33], v[18:21], v[34:37], 0
	s_waitcnt lgkmcnt(7)
	v_mfma_f32_32x32x16_bf16 v[18:33], v[38:41], v[90:93], v[18:33]
	ds_read_b128 v[38:41], v196 offset:96
	s_waitcnt lgkmcnt(6)
	v_mfma_f32_32x32x16_bf16 v[18:33], v[200:203], v[106:109], v[18:33]
	ds_read_b128 v[200:203], v196 offset:128
	s_waitcnt lgkmcnt(1)
	v_mfma_f32_32x32x16_bf16 v[18:33], v[38:41], v[94:97], v[18:33]
	ds_read_b128 v[38:41], v196 offset:160
	s_waitcnt lgkmcnt(1)
	v_mfma_f32_32x32x16_bf16 v[18:33], v[200:203], v[102:105], v[18:33]
	ds_read_b128 v[200:203], v196 offset:192
	s_waitcnt lgkmcnt(1)
	v_mfma_f32_32x32x16_bf16 v[18:33], v[38:41], v[86:89], v[18:33]
	ds_read_b128 v[38:41], v196 offset:224
	s_waitcnt lgkmcnt(1)
	v_mfma_f32_32x32x16_bf16 v[18:33], v[200:203], v[98:101], v[18:33]
	s_waitcnt lgkmcnt(0)
	v_mfma_f32_32x32x16_bf16 v[18:33], v[38:41], v[82:85], v[18:33]
	ds_read_b32 v38, v157
	s_waitcnt lgkmcnt(0)
	s_nop 9
	v_pk_mul_f32 v[32:33], v[38:39], v[32:33] op_sel_hi:[0,1]
	v_pk_mul_f32 v[30:31], v[38:39], v[30:31] op_sel_hi:[0,1]
	v_pk_mul_f32 v[28:29], v[38:39], v[28:29] op_sel_hi:[0,1]
	v_pk_mul_f32 v[26:27], v[38:39], v[26:27] op_sel_hi:[0,1]
	v_pk_mul_f32 v[24:25], v[38:39], v[24:25] op_sel_hi:[0,1]
	v_pk_mul_f32 v[22:23], v[38:39], v[22:23] op_sel_hi:[0,1]
	v_pk_mul_f32 v[20:21], v[38:39], v[20:21] op_sel_hi:[0,1]
	v_pk_mul_f32 v[18:19], v[38:39], v[18:19] op_sel_hi:[0,1]
	s_mov_b64 s[42:43], exec
	v_readlane_b32 s44, v254, 20
	v_readlane_b32 s45, v254, 21
	s_and_b64 s[44:45], s[42:43], s[44:45]
	s_mov_b64 exec, s[44:45]
	s_cbranch_execz .LBB0_328
	s_mov_b32 s37, 0
	s_mov_b64 s[44:45], 0
	v_mov_b32_e32 v82, v217
	v_mov_b32_e32 v83, v216
	v_mov_b32_e32 v84, v215
	v_mov_b32_e32 v85, v158
.LBB0_326:
	ds_read_b128 v[34:37], v84
	ds_read_b128 v[38:41], v191
	ds_read_b128 v[86:89], v84 offset:32
	ds_read_b128 v[90:93], v191 offset:32
	ds_read_b128 v[102:105], v84 offset:64
	ds_read_b128 v[106:109], v191 offset:64
	ds_read_b128 v[200:203], v84 offset:96
	ds_read_b128 v[98:101], v191 offset:96
	s_add_i32 vcc_lo, s37, 0
	s_add_i32 vcc_lo, vcc_lo, 0x1e600
	s_add_i32 s37, s37, 4
	v_mov_b32_e32 v94, vcc_lo
	s_waitcnt lgkmcnt(6)
	v_mfma_f32_32x32x16_bf16 v[34:49], v[34:37], v[38:41], 0
	s_waitcnt lgkmcnt(4)
	v_mfma_f32_32x32x16_bf16 v[34:49], v[86:89], v[90:93], v[34:49]
	ds_read_b128 v[86:89], v84 offset:128
	ds_read_b128 v[90:93], v191 offset:128
	s_waitcnt lgkmcnt(4)
	v_mfma_f32_32x32x16_bf16 v[34:49], v[102:105], v[106:109], v[34:49]
	ds_read_b128 v[102:105], v84 offset:160
	ds_read_b128 v[106:109], v191 offset:160
	s_waitcnt lgkmcnt(4)
	v_mfma_f32_32x32x16_bf16 v[34:49], v[200:203], v[98:101], v[34:49]
	ds_read_b128 v[200:203], v84 offset:192
	ds_read_b128 v[98:101], v191 offset:192
	s_waitcnt lgkmcnt(4)
	v_mfma_f32_32x32x16_bf16 v[34:49], v[86:89], v[90:93], v[34:49]
	ds_read_b128 v[86:89], v84 offset:224
	ds_read_b128 v[90:93], v191 offset:224
	s_waitcnt lgkmcnt(4)
	v_mfma_f32_32x32x16_bf16 v[34:49], v[102:105], v[106:109], v[34:49]
	s_waitcnt lgkmcnt(2)
	v_mfma_f32_32x32x16_bf16 v[34:49], v[200:203], v[98:101], v[34:49]
	s_waitcnt lgkmcnt(0)
	v_mfma_f32_32x32x16_bf16 v[34:49], v[86:89], v[90:93], v[34:49]
	ds_read_b32 v90, v94
	v_add_u32_e32 v91, 0x1e400, v85
	ds_read_b128 v[86:89], v91
	ds_read_b128 v[102:105], v91 offset:32
	ds_read_b128 v[200:203], v91 offset:64
	ds_read_b128 v[106:109], v91 offset:96
	ds_read_b64_tr_b16 v[98:99], v82
	ds_read_b64_tr_b16 v[100:101], v82 offset:2176
	ds_read_b64_tr_b16 v[94:95], v83 offset:4352
	ds_read_b64_tr_b16 v[96:97], v83 offset:6528
	v_cmp_eq_u32_e32 vcc, s37, v214
	v_add_u32_e32 v84, 0x2200, v84
	v_add_u32_e32 v85, 0x80, v85
	s_or_b64 s[44:45], vcc, s[44:45]
	v_add_u32_e32 v82, 0x2200, v82
	v_add_u32_e32 v83, 0x2200, v83
	s_waitcnt lgkmcnt(8)
	v_sub_f32_e32 v90, v163, v90
	v_exp_f32_e32 v92, v90
	s_waitcnt lgkmcnt(7)
	v_mul_f32_e32 v93, v92, v86
	v_mul_f32_e32 v34, v34, v93
	v_mul_f32_e32 v93, v92, v87
	v_mul_f32_e32 v35, v35, v93
	v_mul_f32_e32 v93, v92, v88
	v_mul_f32_e32 v36, v36, v93
	v_mul_f32_e32 v93, v92, v89
	v_mul_f32_e32 v37, v37, v93
	s_waitcnt lgkmcnt(6)
	v_mul_f32_e32 v93, v92, v102
	v_mul_f32_e32 v38, v38, v93
	v_mul_f32_e32 v93, v92, v103
	v_mul_f32_e32 v39, v39, v93
	v_mul_f32_e32 v93, v92, v104
	v_mul_f32_e32 v40, v40, v93
	v_mul_f32_e32 v93, v92, v105
	v_mul_f32_e32 v41, v41, v93
	s_waitcnt lgkmcnt(5)
	v_mul_f32_e32 v93, v92, v200
	v_mul_f32_e32 v42, v42, v93
	v_mul_f32_e32 v93, v92, v201
	v_mul_f32_e32 v43, v43, v93
	v_mul_f32_e32 v93, v92, v202
	v_mul_f32_e32 v44, v44, v93
	v_mul_f32_e32 v93, v92, v203
	v_mul_f32_e32 v45, v45, v93
	s_waitcnt lgkmcnt(4)
	v_mul_f32_e32 v93, v92, v106
	v_mul_f32_e32 v46, v46, v93
	v_mul_f32_e32 v93, v92, v107
	v_mul_f32_e32 v47, v47, v93
	v_mul_f32_e32 v93, v92, v108
	v_mul_f32_e32 v48, v48, v93
	v_mul_f32_e32 v93, v92, v109
	v_mul_f32_e32 v49, v49, v93
	v_cvt_pk_bf16_f32 v34, v34, v35
	v_cvt_pk_bf16_f32 v35, v36, v37
	v_cvt_pk_bf16_f32 v36, v38, v39
	v_cvt_pk_bf16_f32 v37, v40, v41
	v_cvt_pk_bf16_f32 v38, v42, v43
	v_cvt_pk_bf16_f32 v39, v44, v45
	v_cvt_pk_bf16_f32 v40, v46, v47
	v_cvt_pk_bf16_f32 v41, v48, v49
	s_waitcnt lgkmcnt(2)
	v_mfma_f32_32x32x16_bf16 v[18:33], v[98:101], v[34:37], v[18:33]
	s_waitcnt lgkmcnt(0)
	v_mfma_f32_32x32x16_bf16 v[18:33], v[94:97], v[38:41], v[18:33]
	s_andn2_b64 exec, exec, s[44:45]
	s_cbranch_execnz .LBB0_326
	s_or_b64 exec, exec, s[44:45]
	ds_read_b128 v[34:37], v191
	ds_read_b128 v[90:93], v191 offset:32
	ds_read_b128 v[106:109], v191 offset:64
	ds_read_b128 v[94:97], v191 offset:96
	ds_read_b128 v[102:105], v191 offset:128
	ds_read_b128 v[86:89], v191 offset:160
	ds_read_b128 v[98:101], v191 offset:192
	ds_read_b128 v[82:85], v191 offset:224
.LBB0_328:
	s_or_b64 exec, exec, s[42:43]
	ds_read_b128 v[38:41], v241 offset:34816
	ds_read_b128 v[164:167], v241 offset:34848
	ds_read_b128 v[200:203], v241 offset:34880
	s_waitcnt lgkmcnt(2)
	v_mfma_f32_32x32x16_bf16 v[34:49], v[38:41], v[34:37], 0
	s_waitcnt lgkmcnt(1)
	v_mfma_f32_32x32x16_bf16 v[34:49], v[164:167], v[90:93], v[34:49]
	ds_read_b128 v[90:93], v241 offset:34912
	ds_read_b128 v[164:167], v241 offset:34944
	s_waitcnt lgkmcnt(2)
	v_mfma_f32_32x32x16_bf16 v[34:49], v[200:203], v[106:109], v[34:49]
	ds_read_b128 v[200:203], v241 offset:34976
	s_waitcnt lgkmcnt(2)
	v_mfma_f32_32x32x16_bf16 v[34:49], v[90:93], v[94:97], v[34:49]
	ds_read_b128 v[90:93], v241 offset:35008
	s_waitcnt lgkmcnt(2)
	v_mfma_f32_32x32x16_bf16 v[34:49], v[164:167], v[102:105], v[34:49]
	ds_read_b128 v[164:167], v241 offset:35040
	s_waitcnt lgkmcnt(2)
	v_mfma_f32_32x32x16_bf16 v[34:49], v[200:203], v[86:89], v[34:49]
	s_waitcnt lgkmcnt(1)
	v_mfma_f32_32x32x16_bf16 v[34:49], v[90:93], v[98:101], v[34:49]
	s_waitcnt lgkmcnt(0)
	v_mfma_f32_32x32x16_bf16 v[34:49], v[164:167], v[82:85], v[34:49]
	v_mov_b32_e32 v82, v163
	s_mov_b64 s[42:43], exec
	v_readlane_b32 s44, v254, 62
	v_readlane_b32 s45, v254, 63
	s_and_b64 s[44:45], s[42:43], s[44:45]
	s_mov_b64 exec, s[44:45]
	ds_read_b32 v82, v160
	s_mov_b64 exec, s[42:43]
	ds_read_b32 v83, v161
	v_mov_b32_e32 v85, v163
	s_and_saveexec_b64 s[42:43], s[38:39]
	ds_read_b32 v85, v168
	s_mov_b64 exec, s[42:43]
	ds_read_b32 v86, v169
	v_mov_b32_e32 v84, v163
	s_mov_b64 s[42:43], exec
	v_readlane_b32 s44, v255, 6
	v_readlane_b32 s45, v255, 7
	s_and_b64 s[44:45], s[42:43], s[44:45]
	s_mov_b64 exec, s[44:45]
	ds_read_b32 v84, v170
	s_mov_b64 exec, s[42:43]
	ds_read_b32 v87, v171
	v_mov_b32_e32 v89, v163
	s_mov_b64 s[42:43], exec
	v_readlane_b32 s44, v255, 12
	v_readlane_b32 s45, v255, 13
	s_and_b64 s[44:45], s[42:43], s[44:45]
	s_mov_b64 exec, s[44:45]
	ds_read_b32 v89, v172
	s_mov_b64 exec, s[42:43]
	ds_read_b32 v88, v173
	v_mov_b32_e32 v90, v163
	s_and_saveexec_b64 s[42:43], s[56:57]
	ds_read_b32 v90, v174
	s_mov_b64 exec, s[42:43]
	ds_read_b32 v91, v175
	v_mov_b32_e32 v93, v163
	s_and_saveexec_b64 s[42:43], s[62:63]
	ds_read_b32 v93, v176
	s_mov_b64 exec, s[42:43]
	ds_read_b32 v92, v177
	v_mov_b32_e32 v94, v163
	s_and_saveexec_b64 s[42:43], s[68:69]
	ds_read_b32 v94, v178
	s_mov_b64 exec, s[42:43]
	ds_read_b32 v96, v179
	v_mov_b32_e32 v98, v163
	s_and_saveexec_b64 s[42:43], s[74:75]
	ds_read_b32 v98, v180
	s_mov_b64 exec, s[42:43]
	ds_read_b32 v97, v181
	v_mov_b32_e32 v99, v163
	s_and_saveexec_b64 s[42:43], s[80:81]
	ds_read_b32 v99, v182
	s_mov_b64 exec, s[42:43]
	ds_read_b32 v100, v183
	v_mov_b32_e32 v102, v163
	s_and_saveexec_b64 s[42:43], s[86:87]
	ds_read_b32 v102, v184
	s_mov_b64 exec, s[42:43]
	ds_read_b32 v101, v185
	v_mov_b32_e32 v103, v163
	s_and_saveexec_b64 s[42:43], s[92:93]
	ds_read_b32 v103, v186
	s_mov_b64 exec, s[42:43]
	ds_read_b32 v104, v187
	v_mov_b32_e32 v106, v163
	s_and_saveexec_b64 s[42:43], s[2:3]
	ds_read_b32 v106, v188
	s_mov_b64 exec, s[42:43]
	ds_read_b32 v105, v189
	v_mov_b32_e32 v107, v163
	s_and_saveexec_b64 s[42:43], s[0:1]
	ds_read_b32 v107, v204
	s_mov_b64 exec, s[42:43]
	ds_read_b32 v108, v205
	v_mov_b32_e32 v109, v163
	s_and_saveexec_b64 s[42:43], s[14:15]
	ds_read_b32 v109, v206
	s_mov_b64 exec, s[42:43]
	ds_read_b32 v191, v207
	v_mov_b32_e32 v193, v163
	s_and_saveexec_b64 s[42:43], s[22:23]
	ds_read_b32 v193, v208
	s_mov_b64 exec, s[42:43]
	ds_read_b32 v164, v209
	v_mov_b32_e32 v95, v163
	s_and_saveexec_b64 s[42:43], s[28:29]
	ds_read_b32 v95, v210
	s_mov_b64 exec, s[42:43]
	s_waitcnt lgkmcnt(0)
	v_sub_f32_e32 v82, v163, v82
	v_sub_f32_e32 v85, v163, v85
	v_sub_f32_e32 v84, v163, v84
	v_sub_f32_e32 v89, v163, v89
	v_sub_f32_e32 v90, v163, v90
	v_sub_f32_e32 v93, v163, v93
	v_sub_f32_e32 v94, v163, v94
	v_sub_f32_e32 v98, v163, v98
	v_sub_f32_e32 v99, v163, v99
	v_sub_f32_e32 v102, v163, v102
	v_sub_f32_e32 v103, v163, v103
	v_sub_f32_e32 v106, v163, v106
	v_sub_f32_e32 v107, v163, v107
	v_sub_f32_e32 v109, v163, v109
	v_sub_f32_e32 v193, v163, v193
	v_sub_f32_e32 v95, v163, v95
	v_exp_f32_e32 v106, v106
	v_readlane_b32 s42, v255, 10
	v_readlane_b32 s43, v255, 11
	v_exp_f32_e32 v163, v193
	v_mul_f32_e32 v45, v45, v106
	s_waitcnt lgkmcnt(3)
	v_mul_f32_e32 v45, v105, v45
	v_cndmask_b32_e64 v45, v45, 0, s[96:97]
	v_add_f32_e32 v105, v243, v45
	v_cndmask_b32_e64 v105, v45, v105, s[4:5]
	v_exp_f32_e32 v45, v103
	v_exp_f32_e32 v109, v109
	v_exp_f32_e32 v107, v107
	v_mul_f32_e32 v48, v48, v163
	v_mul_f32_e32 v44, v44, v45
	v_mul_f32_e32 v44, v104, v44
	v_cndmask_b32_e64 v44, v44, 0, s[90:91]
	v_add_f32_e32 v45, v243, v44
	v_cndmask_b32_e64 v103, v44, v45, s[94:95]
	v_exp_f32_e32 v44, v102
	v_mul_f32_e32 v47, v47, v109
	v_mul_f32_e32 v46, v46, v107
	s_waitcnt lgkmcnt(0)
	v_mul_f32_e32 v48, v164, v48
	v_mul_f32_e32 v43, v43, v44
	v_mul_f32_e32 v43, v101, v43
	v_cndmask_b32_e64 v43, v43, 0, s[84:85]
	v_add_f32_e32 v44, v243, v43
	v_cndmask_b32_e64 v101, v43, v44, s[88:89]
	v_exp_f32_e32 v43, v99
	v_mul_f32_e32 v47, v191, v47
	v_mul_f32_e32 v46, v108, v46
	v_cndmask_b32_e64 v48, v48, 0, s[20:21]
	v_mul_f32_e32 v42, v42, v43
	v_mul_f32_e32 v42, v100, v42
	v_cndmask_b32_e64 v42, v42, 0, s[78:79]
	v_add_f32_e32 v43, v243, v42
	v_cndmask_b32_e64 v99, v42, v43, s[82:83]
	v_exp_f32_e32 v42, v98
	ds_read_b32 v43, v211
	v_cndmask_b32_e64 v47, v47, 0, s[10:11]
	v_cndmask_b32_e64 v46, v46, 0, s[6:7]
	v_mul_f32_e32 v41, v41, v42
	v_mul_f32_e32 v41, v97, v41
	v_cndmask_b32_e64 v41, v41, 0, s[72:73]
	v_add_f32_e32 v42, v243, v41
	v_cndmask_b32_e64 v41, v41, v42, s[76:77]
	v_exp_f32_e32 v42, v94
	v_add_f32_e32 v163, v243, v48
	v_add_f32_e32 v109, v243, v47
	v_add_f32_e32 v107, v243, v46
	v_mul_f32_e32 v40, v40, v42
	v_mul_f32_e32 v40, v96, v40
	v_cndmask_b32_e64 v40, v40, 0, s[66:67]
	v_add_f32_e32 v42, v243, v40
	v_cndmask_b32_e64 v40, v40, v42, s[70:71]
	v_exp_f32_e32 v42, v93
	v_readlane_b32 s37, v253, 48
	v_cndmask_b32_e64 v48, v48, v163, s[24:25]
	v_cndmask_b32_e64 v47, v47, v109, s[18:19]
	v_mul_f32_e32 v39, v39, v42
	v_mul_f32_e32 v39, v92, v39
	v_cndmask_b32_e64 v39, v39, 0, s[60:61]
	v_add_f32_e32 v42, v243, v39
	v_cndmask_b32_e64 v39, v39, v42, s[64:65]
	v_exp_f32_e32 v42, v90
	v_cndmask_b32_e64 v46, v46, v107, s[12:13]
	v_cvt_pk_bf16_f32 v45, v40, v41
	s_andn2_b64 vcc, exec, s[40:41]
	v_mul_f32_e32 v38, v38, v42
	v_mul_f32_e32 v38, v91, v38
	v_cndmask_b32_e64 v38, v38, 0, s[54:55]
	v_add_f32_e32 v42, v243, v38
	v_cndmask_b32_e64 v38, v38, v42, s[58:59]
	v_exp_f32_e32 v42, v89
	v_cvt_pk_bf16_f32 v44, v38, v39
	v_add_u32_e32 v38, 0, v159
	v_mul_f32_e32 v37, v37, v42
	v_mul_f32_e32 v37, v88, v37
	v_cndmask_b32_e64 v37, v37, 0, s[42:43]
	v_readlane_b32 s42, v255, 14
	v_add_f32_e32 v42, v243, v37
	v_readlane_b32 s43, v255, 15
	s_nop 1
	v_cndmask_b32_e64 v37, v37, v42, s[42:43]
	v_exp_f32_e32 v42, v84
	v_readlane_b32 s42, v255, 4
	v_readlane_b32 s43, v255, 5
	v_mul_f32_e32 v36, v36, v42
	v_mul_f32_e32 v36, v87, v36
	v_cndmask_b32_e64 v36, v36, 0, s[42:43]
	v_readlane_b32 s42, v255, 8
	v_add_f32_e32 v42, v243, v36
	v_readlane_b32 s43, v255, 9
	s_nop 1
	v_cndmask_b32_e64 v36, v36, v42, s[42:43]
	v_exp_f32_e32 v42, v85
	v_readlane_b32 s42, v255, 2
	v_readlane_b32 s43, v255, 3
	v_mul_f32_e32 v35, v35, v42
	v_mul_f32_e32 v35, v86, v35
	v_cndmask_b32_e64 v35, 0, v35, s[38:39]
	v_add_f32_e32 v42, v243, v35
	v_cndmask_b32_e64 v35, v35, v42, s[42:43]
	v_exp_f32_e32 v42, v82
	v_readlane_b32 s42, v254, 60
	v_readlane_b32 s43, v254, 61
	v_mov_b32_e32 v82, s37
	v_mul_f32_e32 v34, v34, v42
	v_mul_f32_e32 v34, v83, v34
	v_cndmask_b32_e64 v34, v34, 0, s[42:43]
	v_readlane_b32 s42, v255, 0
	v_add_f32_e32 v42, v243, v34
	v_readlane_b32 s43, v255, 1
	s_nop 1
	v_cndmask_b32_e64 v34, v34, v42, s[42:43]
	v_exp_f32_e32 v42, v95
	s_nop 0
	v_mul_f32_e32 v42, v49, v42
	s_waitcnt lgkmcnt(0)
	v_mul_f32_e32 v42, v43, v42
	v_cndmask_b32_e64 v42, v42, 0, s[26:27]
	v_add_f32_e32 v43, v243, v42
	v_cndmask_b32_e64 v49, v42, v43, s[16:17]
	v_cvt_pk_bf16_f32 v43, v36, v37
	v_cvt_pk_bf16_f32 v36, v46, v47
	v_cvt_pk_bf16_f32 v37, v48, v49
	ds_read_b64_tr_b16 v[46:47], v38
	ds_read_b64_tr_b16 v[48:49], v38 offset:2176
	ds_read_b64_tr_b16 v[38:39], v223
	ds_read_b64_tr_b16 v[40:41], v223 offset:2176
	ds_read_b32 v82, v82
	v_cvt_pk_bf16_f32 v42, v34, v35
	v_cvt_pk_bf16_f32 v34, v99, v101
	v_cvt_pk_bf16_f32 v35, v103, v105
	s_waitcnt lgkmcnt(0)
	v_pk_mul_f32 v[16:17], v[16:17], v[82:83] op_sel_hi:[1,0]
	v_pk_mul_f32 v[14:15], v[14:15], v[82:83] op_sel_hi:[1,0]
	v_pk_mul_f32 v[12:13], v[12:13], v[82:83] op_sel_hi:[1,0]
	v_pk_mul_f32 v[10:11], v[10:11], v[82:83] op_sel_hi:[1,0]
	v_pk_mul_f32 v[8:9], v[8:9], v[82:83] op_sel_hi:[1,0]
	v_pk_mul_f32 v[6:7], v[6:7], v[82:83] op_sel_hi:[1,0]
	v_pk_mul_f32 v[4:5], v[4:5], v[82:83] op_sel_hi:[1,0]
	v_pk_mul_f32 v[2:3], v[2:3], v[82:83] op_sel_hi:[1,0]
	ds_read_b64_tr_b16 v[82:83], v224 offset:128
	ds_read_b64_tr_b16 v[84:85], v224 offset:2304
	ds_read_b64_tr_b16 v[86:87], v225 offset:34816
	ds_read_b64_tr_b16 v[88:89], v225 offset:36992
	ds_read_b64_tr_b16 v[90:91], v226 offset:128
	ds_read_b64_tr_b16 v[92:93], v226 offset:2304
	ds_read_b64_tr_b16 v[98:99], v227 offset:34816
	ds_read_b64_tr_b16 v[100:101], v227 offset:36992
	ds_read_b64_tr_b16 v[94:95], v228 offset:128
	ds_read_b64_tr_b16 v[96:97], v228 offset:2304
	ds_read_b64_tr_b16 v[102:103], v229 offset:34816
	ds_read_b64_tr_b16 v[104:105], v229 offset:36992
	s_waitcnt lgkmcnt(8)
	v_mfma_f32_32x32x16_bf16 v[2:17], v[82:85], v[86:89], v[2:17]
	ds_read_b64_tr_b16 v[82:83], v230 offset:128
	ds_read_b64_tr_b16 v[84:85], v230 offset:2304
	ds_read_b64_tr_b16 v[86:87], v231 offset:34816
	ds_read_b64_tr_b16 v[88:89], v231 offset:36992
	s_waitcnt lgkmcnt(8)
	v_mfma_f32_32x32x16_bf16 v[2:17], v[90:93], v[98:101], v[2:17]
	ds_read_b64_tr_b16 v[90:91], v232 offset:128
	ds_read_b64_tr_b16 v[92:93], v232 offset:2304
	ds_read_b64_tr_b16 v[98:99], v233 offset:34816
	ds_read_b64_tr_b16 v[100:101], v233 offset:36992
	s_waitcnt lgkmcnt(8)
	v_mfma_f32_32x32x16_bf16 v[2:17], v[94:97], v[102:105], v[2:17]
	ds_read_b64_tr_b16 v[94:95], v234 offset:128
	ds_read_b64_tr_b16 v[96:97], v234 offset:2304
	ds_read_b64_tr_b16 v[102:103], v235 offset:34816
	ds_read_b64_tr_b16 v[104:105], v235 offset:36992
	s_waitcnt lgkmcnt(8)
	v_mfma_f32_32x32x16_bf16 v[2:17], v[82:85], v[86:89], v[2:17]
	ds_read_b64_tr_b16 v[82:83], v236 offset:128
	ds_read_b64_tr_b16 v[84:85], v236 offset:2304
	ds_read_b64_tr_b16 v[86:87], v237 offset:34816
	ds_read_b64_tr_b16 v[88:89], v237 offset:36992
	s_waitcnt lgkmcnt(8)
	v_mfma_f32_32x32x16_bf16 v[2:17], v[90:93], v[98:101], v[2:17]
	ds_read_b64_tr_b16 v[90:91], v238 offset:128
	ds_read_b64_tr_b16 v[92:93], v238 offset:2304
	ds_read_b64_tr_b16 v[98:99], v239 offset:34816
	ds_read_b64_tr_b16 v[100:101], v239 offset:36992
	s_waitcnt lgkmcnt(8)
	v_mfma_f32_32x32x16_bf16 v[2:17], v[94:97], v[102:105], v[2:17]
	s_waitcnt lgkmcnt(4)
	v_mfma_f32_32x32x16_bf16 v[2:17], v[82:85], v[86:89], v[2:17]
	s_waitcnt lgkmcnt(0)
	s_barrier
	v_mfma_f32_32x32x16_bf16 v[18:33], v[46:49], v[42:45], v[18:33]
	s_waitcnt lgkmcnt(0)
	v_mfma_f32_32x32x16_bf16 v[2:17], v[90:93], v[98:101], v[2:17]
	v_mfma_f32_32x32x16_bf16 v[18:33], v[38:41], v[34:37], v[18:33]
	s_cbranch_vccnz .LBB0_314
	v_readlane_b32 s40, v254, 14
	v_readlane_b32 s41, v254, 15
	s_mov_b32 s43, s41
	s_lshl_b32 s42, s33, 7
	v_lshl_add_u64 v[34:35], s[42:43], 0, v[112:113]
	s_movk_i32 s37, 0x1e00
	v_mad_u64_u32 v[36:37], s[40:41], v34, s37, v[124:125]
	v_mad_i32_i24 v37, v35, s37, v37
	v_add_co_u32_e32 v34, vcc, 0xffffb000, v36
	s_movk_i32 s37, 0x2000
	s_nop 0
	v_addc_co_u32_e32 v35, vcc, -1, v37, vcc
	v_add_co_u32_e32 v38, vcc, 0xffffd000, v36
	s_lshl_b32 s42, s33, 17
	s_nop 0
	v_addc_co_u32_e32 v39, vcc, -1, v37, vcc
	v_add_co_u32_e32 v40, vcc, 0xfffff000, v36
	s_nop 1
	v_addc_co_u32_e32 v41, vcc, -1, v37, vcc
	v_add_co_u32_e32 v42, vcc, s37, v36
	s_movk_i32 s37, 0x4000
	s_nop 0
	v_addc_co_u32_e32 v43, vcc, 0, v37, vcc
	v_add_co_u32_e32 v44, vcc, s37, v36
	s_movk_i32 s37, 0x6000
	s_nop 0
	v_addc_co_u32_e32 v45, vcc, 0, v37, vcc
	v_add_co_u32_e32 v46, vcc, s37, v36
	s_mov_b32 s37, 0x8000
	s_nop 0
	v_addc_co_u32_e32 v47, vcc, 0, v37, vcc
	v_add_co_u32_e32 v48, vcc, s37, v36
	s_mov_b32 s37, 0x9000
	s_nop 0
	v_addc_co_u32_e32 v49, vcc, 0, v37, vcc
	v_add_co_u32_e32 v50, vcc, s37, v36
	s_mov_b32 s37, s43
	s_nop 0
	v_addc_co_u32_e32 v51, vcc, 0, v37, vcc
	global_load_dword v190, v[34:35], off offset:-512
	global_load_dword v192, v[38:39], off offset:-1024
	global_load_dword v252, v[40:41], off offset:-1536
	global_load_dword v0, v[42:43], off offset:1536
	global_load_dword v123, v[44:45], off offset:1024
	global_load_dword v246, v[46:47], off offset:512
	global_load_dword v247, v[48:49], off
	global_load_dword v248, v[50:51], off offset:3584
	v_add_co_u32_e32 v34, vcc, 0xb000, v36
	v_lshl_add_u64 v[40:41], v[126:127], 0, s[42:43]
	s_nop 0
	v_addc_co_u32_e32 v35, vcc, 0, v37, vcc
	v_add_co_u32_e32 v38, vcc, 0xd000, v36
	v_writelane_b32 v254, s36, 14
	s_nop 0
	v_addc_co_u32_e32 v39, vcc, 0, v37, vcc
	global_load_dword v249, v[34:35], off offset:3072
	global_load_dword v250, v[38:39], off offset:2560
	global_load_dwordx4 v[50:53], v[40:41], off
	v_add_co_u32_e32 v34, vcc, 0x4000, v40
	v_writelane_b32 v254, s37, 15
	s_nop 0
	v_addc_co_u32_e32 v35, vcc, 0, v41, vcc
	v_add_co_u32_e32 v38, vcc, 0x8000, v40
	s_nop 1
	v_addc_co_u32_e32 v39, vcc, 0, v41, vcc
	global_load_dwordx4 v[54:57], v[34:35], off
	global_load_dwordx4 v[58:61], v[38:39], off
	v_add_co_u32_e32 v34, vcc, 0xc000, v40
	s_nop 1
	v_addc_co_u32_e32 v35, vcc, 0, v41, vcc
	v_add_co_u32_e32 v38, vcc, 0x10000, v40
	s_nop 1
	v_addc_co_u32_e32 v39, vcc, 0, v41, vcc
	global_load_dwordx4 v[62:65], v[34:35], off
	global_load_dwordx4 v[66:69], v[38:39], off
	v_add_co_u32_e32 v34, vcc, 0x14000, v40
	s_nop 1
	v_addc_co_u32_e32 v35, vcc, 0, v41, vcc
	v_add_co_u32_e32 v38, vcc, 0x18000, v40
	s_nop 1
	v_addc_co_u32_e32 v39, vcc, 0, v41, vcc
	global_load_dwordx4 v[70:73], v[34:35], off
	global_load_dwordx4 v[74:77], v[38:39], off
	v_add_co_u32_e32 v34, vcc, 0x1c000, v40
	s_nop 1
	v_addc_co_u32_e32 v35, vcc, 0, v41, vcc
	global_load_dword v251, v[36:37], off offset:2048
	global_load_dwordx4 v[78:81], v[34:35], off
	s_branch .LBB0_314

.LBB0_521:
	s_xor_b32 s10, s16, s14
	s_lshl_b32 s8, s10, 8
	s_lshl_b32 s7, s16, 9
	s_and_b32 s11, s8, 0x100
	s_or_b32 s62, s11, s7
	v_lshl_add_u64 v[134:135], v[122:123], 0, s[62:63]
	v_mad_u64_u32 v[2:3], s[8:9], v134, s59, v[124:125]
	v_mov_b32_e32 v0, v3
	v_mad_u64_u32 v[4:5], s[8:9], v135, s59, v[0:1]
	v_mov_b32_e32 v3, v4
	global_load_dwordx4 v[66:69], v[2:3], off
	global_load_dwordx4 v[70:73], v[2:3], off offset:32
	global_load_dwordx4 v[74:77], v[2:3], off offset:64
	global_load_dwordx4 v[78:81], v[2:3], off offset:96
	global_load_dwordx4 v[82:85], v[2:3], off offset:128
	global_load_dwordx4 v[86:89], v[2:3], off offset:160
	s_waitcnt lgkmcnt(0)
	s_barrier
	global_load_dwordx4 v[90:93], v[126:127], off
	global_load_dwordx4 v[94:97], v[126:127], off offset:128
	v_mov_b32_e32 v2, v1
	v_mov_b32_e32 v3, v1
	v_mov_b32_e32 v0, v1
	s_waitcnt vmcnt(16)
	v_mov_b64_e32 v[100:101], v[2:3]
	v_mov_b64_e32 v[98:99], v[0:1]
	global_load_dwordx4 v[98:101], v[128:129], off
	global_load_dwordx4 v[220:223], v[132:133], off
	global_load_dwordx4 v[224:227], v[132:133], off offset:128
	global_load_dwordx4 v[228:231], v[130:131], off
	s_mov_b64 s[24:25], 0x20000
	v_lshl_add_u64 v[136:137], v[132:133], 0, s[24:25]
	v_lshl_add_u64 v[138:139], v[130:131], 0, s[30:31]
	global_load_dwordx4 v[242:245], v[136:137], off
	global_load_dwordx4 v[246:249], v[136:137], off offset:128
	global_load_dwordx4 v[164:167], v[138:139], off
	v_lshl_add_u64 v[136:137], v[136:137], 0, s[24:25]
	v_lshl_add_u64 v[138:139], v[138:139], 0, s[30:31]
	v_add_u32_e32 v0, 0, v112
	s_waitcnt vmcnt(3)
	ds_write_b128 v0, v[90:93]
	v_add_u32_e32 v0, 0, v113
	s_nop 0
	ds_write_b128 v0, v[94:97] offset:13312
	s_and_saveexec_b64 s[8:9], s[0:1]
	v_add_u32_e32 v0, 0, v115
	ds_write_b128 v0, v[98:101] offset:128
	s_or_b64 exec, exec, s[8:9]
	ds_write_b128 v112, v[220:223] offset:22528
	ds_write_b128 v113, v[224:227] offset:35840
	ds_write_b128 v115, v[228:231] offset:22656
	global_load_dwordx4 v[90:93], v[136:137], off
	global_load_dwordx4 v[94:97], v[136:137], off offset:128
	global_load_dwordx4 v[98:101], v[138:139], off
	v_lshl_add_u64 v[136:137], v[136:137], 0, s[24:25]
	v_lshl_add_u64 v[138:139], v[138:139], 0, s[30:31]
	s_add_i32 s8, s15, s11
	s_lshr_b32 s8, s8, 6
	v_mov_b32_e32 v14, v1
	v_mov_b32_e32 v15, v1
	s_waitcnt lgkmcnt(0)
	s_barrier
	s_sub_i32 s18, 0, s8
	s_and_b32 s8, s10, 1
	v_mov_b32_e32 v0, v1
	v_mov_b32_e32 v2, v1
	v_mov_b32_e32 v3, v1
	v_mov_b32_e32 v4, v1
	v_mov_b32_e32 v5, v1
	v_mov_b32_e32 v6, v1
	v_mov_b32_e32 v7, v1
	v_mov_b32_e32 v8, v1
	v_mov_b32_e32 v9, v1
	v_mov_b32_e32 v10, v1
	v_mov_b32_e32 v11, v1
	v_mov_b32_e32 v12, v1
	v_mov_b32_e32 v13, v1
	v_mov_b64_e32 v[32:33], v[14:15]
	s_add_i32 s7, s62, 0x100
	s_lshl_b32 s8, s8, 8
	v_mov_b64_e32 v[30:31], v[12:13]
	v_mov_b64_e32 v[28:29], v[10:11]
	v_mov_b64_e32 v[26:27], v[8:9]
	v_mov_b64_e32 v[24:25], v[6:7]
	v_mov_b64_e32 v[22:23], v[4:5]
	v_mov_b64_e32 v[20:21], v[2:3]
	v_mov_b64_e32 v[18:19], v[0:1]
	v_mov_b64_e32 v[16:17], v[14:15]
	s_lshr_b32 s7, s7, 6
	s_mov_b32 s19, 1
	s_sub_i32 s20, 0, s8
	v_subrev_u32_e32 v121, s11, v114
	v_mov_b32_e32 v144, 0xf149f2ca
	v_mov_b32_e32 v143, 0
	s_nop 0
	s_nop 0
	s_mov_b32 s21, s17
	v_mov_b64_e32 v[14:15], v[12:13]
	v_mov_b64_e32 v[12:13], v[10:11]
	v_mov_b64_e32 v[10:11], v[8:9]
	v_mov_b64_e32 v[8:9], v[6:7]
	v_mov_b64_e32 v[6:7], v[4:5]
	v_mov_b64_e32 v[4:5], v[2:3]
	v_mov_b64_e32 v[2:3], v[0:1]
	v_mov_b32_e32 v203, 0xf149f2ca
	v_mov_b32_e32 v146, 0
	v_mov_b32_e32 v147, 0
	v_mov_b32_e32 v148, 0
	v_mov_b32_e32 v149, 0
	v_mov_b32_e32 v150, 0
	v_mov_b32_e32 v151, 0
	v_mov_b32_e32 v152, 0
	v_mov_b32_e32 v153, 0
	v_mov_b32_e32 v154, 0
	v_mov_b32_e32 v155, 0
	v_mov_b32_e32 v156, 0
	v_mov_b32_e32 v157, 0
	v_mov_b32_e32 v158, 0
	v_mov_b32_e32 v159, 0
	v_mov_b32_e32 v160, 0
	v_mov_b32_e32 v161, 0
	v_mov_b32_e32 v169, v142
	v_add_u32_e32 v250, 22528, v142
	v_add_u32_e32 v251, 45056, v142
	s_mov_b64 s[34:35], 0x20000
	s_add_i32 s36, s7, -4
	s_add_i32 s37, s7, -3
	v_readfirstlane_b32 s38, v109
	s_nop 3
	s_lshl_b32 s38, s38, 5
	s_or_b32 s38, s38, 31
	s_cmp_eq_u32 s36, 0
	s_cselect_b64 s[10:11], -1, 0
	s_branch .Lat_first
.Lat_head0:
	ds_read_b128 v[170:173], v140
	ds_read_b128 v[174:177], v140 offset:32
	ds_read_b128 v[178:181], v140 offset:64
	ds_read_b128 v[182:185], v140 offset:96
	ds_read_b128 v[186:189], v140 offset:128
	ds_read_b128 v[190:193], v140 offset:160
	ds_read_b128 v[204:207], v141
	ds_read_b128 v[208:211], v141 offset:32
	global_load_dwordx4 v[220:223], v[136:137], off
	global_load_dwordx4 v[224:227], v[136:137], off offset:128
	global_load_dwordx4 v[228:231], v[138:139], off
	s_waitcnt lgkmcnt(7)
	v_mfma_f32_32x32x16_bf16 v[50:65], v[170:173], v[66:69], v[146:161]
	ds_read_b128 v[170:173], v141 offset:64
	s_waitcnt lgkmcnt(7)
	v_mfma_f32_32x32x16_bf16 v[50:65], v[174:177], v[70:73], v[50:65]
	ds_read_b128 v[174:177], v141 offset:96
	s_waitcnt lgkmcnt(7)
	v_mfma_f32_32x32x16_bf16 v[50:65], v[178:181], v[74:77], v[50:65]
	ds_read_b128 v[178:181], v141 offset:128
	s_waitcnt lgkmcnt(7)
	v_mfma_f32_32x32x16_bf16 v[50:65], v[182:185], v[78:81], v[50:65]
	ds_read_b128 v[182:185], v141 offset:160
	s_waitcnt lgkmcnt(7)
	v_mfma_f32_32x32x16_bf16 v[50:65], v[186:189], v[82:85], v[50:65]
	s_waitcnt lgkmcnt(6)
	v_mfma_f32_32x32x16_bf16 v[50:65], v[190:193], v[86:89], v[50:65]
	ds_read_b64_tr_b16 v[186:187], v169 offset:13312
	ds_read_b64_tr_b16 v[188:189], v169 offset:14464
	ds_read_b64_tr_b16 v[190:191], v169 offset:13376
	ds_read_b64_tr_b16 v[192:193], v169 offset:14528
	s_waitcnt lgkmcnt(9)
	v_mfma_f32_32x32x16_bf16 v[34:49], v[204:207], v[66:69], v[146:161]
	ds_read_b64_tr_b16 v[204:205], v169 offset:15616
	ds_read_b64_tr_b16 v[206:207], v169 offset:16768
	s_waitcnt lgkmcnt(10)
	v_mfma_f32_32x32x16_bf16 v[34:49], v[208:211], v[70:73], v[34:49]
	ds_read_b64_tr_b16 v[208:209], v169 offset:15680
	ds_read_b64_tr_b16 v[210:211], v169 offset:16832
	s_nop 5
	v_exp_f32_e32 v50, v50
	v_exp_f32_e32 v51, v51
	v_exp_f32_e32 v52, v52
	v_exp_f32_e32 v53, v53
	s_waitcnt lgkmcnt(11)
	v_mfma_f32_32x32x16_bf16 v[34:49], v[170:173], v[74:77], v[34:49]
	v_exp_f32_e32 v54, v54
	v_exp_f32_e32 v55, v55
	v_exp_f32_e32 v56, v56
	v_exp_f32_e32 v57, v57
	v_cvt_pk_bf16_f32 v212, v50, v51
	v_cvt_pk_bf16_f32 v213, v52, v53
	v_cvt_pk_bf16_f32 v214, v54, v55
	v_cvt_pk_bf16_f32 v215, v56, v57
	s_waitcnt lgkmcnt(10)
	v_mfma_f32_32x32x16_bf16 v[34:49], v[174:177], v[78:81], v[34:49]
	v_add_f32_e32 v163, v50, v52
	v_add_f32_e32 v237, v51, v53
	s_waitcnt lgkmcnt(6)
	v_mfma_f32_32x32x16_bf16 v[18:33], v[186:189], v[212:215], v[18:33]
	v_exp_f32_e32 v58, v58
	v_exp_f32_e32 v59, v59
	v_exp_f32_e32 v60, v60
	s_waitcnt lgkmcnt(4)
	v_mfma_f32_32x32x16_bf16 v[2:17], v[190:193], v[212:215], v[2:17]
	v_exp_f32_e32 v61, v61
	v_exp_f32_e32 v62, v62
	v_exp_f32_e32 v63, v63
	v_mfma_f32_32x32x16_bf16 v[34:49], v[178:181], v[82:85], v[34:49]
	v_exp_f32_e32 v64, v64
	v_exp_f32_e32 v65, v65
	v_add_f32_e32 v163, v163, v54
	v_add_f32_e32 v237, v237, v55
	v_mfma_f32_32x32x16_bf16 v[34:49], v[182:185], v[86:89], v[34:49]
	v_cvt_pk_bf16_f32 v216, v58, v59
	v_cvt_pk_bf16_f32 v217, v60, v61
	v_cvt_pk_bf16_f32 v218, v62, v63
	v_cvt_pk_bf16_f32 v219, v64, v65
	v_add_f32_e32 v163, v163, v56
	v_add_f32_e32 v237, v237, v57
	v_add_f32_e32 v163, v163, v58
	v_add_f32_e32 v237, v237, v59
	s_waitcnt lgkmcnt(2)
	v_mfma_f32_32x32x16_bf16 v[18:33], v[204:207], v[216:219], v[18:33]
	v_add_f32_e32 v163, v163, v60
	v_add_f32_e32 v237, v237, v61
	v_add_f32_e32 v163, v163, v62
	s_waitcnt lgkmcnt(0)
	v_mfma_f32_32x32x16_bf16 v[2:17], v[208:211], v[216:219], v[2:17]
	v_add_f32_e32 v237, v237, v63
	v_add_f32_e32 v163, v163, v64
	v_add_f32_e32 v237, v237, v65
	s_barrier
	ds_read_b64_tr_b16 v[170:171], v169 offset:17920
	ds_read_b64_tr_b16 v[172:173], v169 offset:19072
	ds_read_b64_tr_b16 v[174:175], v169 offset:17984
	ds_read_b64_tr_b16 v[176:177], v169 offset:19136
	ds_read_b64_tr_b16 v[178:179], v169 offset:20224
	ds_read_b64_tr_b16 v[180:181], v169 offset:21376
	ds_read_b64_tr_b16 v[182:183], v169 offset:20288
	ds_read_b64_tr_b16 v[184:185], v169 offset:21440
	s_waitcnt vmcnt(6)
	ds_write_b128 v112, v[242:245] offset:45056
	ds_write_b128 v113, v[246:249] offset:58368
	ds_write_b128 v115, v[164:167] offset:45184
	v_exp_f32_e32 v34, v34
	v_exp_f32_e32 v35, v35
	v_exp_f32_e32 v36, v36
	v_exp_f32_e32 v37, v37
	v_exp_f32_e32 v38, v38
	v_exp_f32_e32 v39, v39
	v_exp_f32_e32 v40, v40
	v_exp_f32_e32 v41, v41
	v_cvt_pk_bf16_f32 v212, v34, v35
	v_cvt_pk_bf16_f32 v213, v36, v37
	v_cvt_pk_bf16_f32 v214, v38, v39
	v_cvt_pk_bf16_f32 v215, v40, v41
	v_exp_f32_e32 v42, v42
	v_exp_f32_e32 v43, v43
	s_waitcnt lgkmcnt(9)
	v_mfma_f32_32x32x16_bf16 v[18:33], v[170:173], v[212:215], v[18:33]
	s_waitcnt lgkmcnt(7)
	v_mfma_f32_32x32x16_bf16 v[2:17], v[174:177], v[212:215], v[2:17]
	v_exp_f32_e32 v44, v44
	v_add_f32_e32 v163, v163, v34
	v_exp_f32_e32 v45, v45
	v_add_f32_e32 v237, v237, v35
	v_exp_f32_e32 v46, v46
	v_add_f32_e32 v163, v163, v36
	v_exp_f32_e32 v47, v47
	v_add_f32_e32 v237, v237, v37
	v_exp_f32_e32 v48, v48
	v_add_f32_e32 v163, v163, v38
	v_exp_f32_e32 v49, v49
	v_add_f32_e32 v237, v237, v39
	v_add_f32_e32 v163, v163, v40
	v_add_f32_e32 v237, v237, v41
	v_cvt_pk_bf16_f32 v216, v42, v43
	v_cvt_pk_bf16_f32 v217, v44, v45
	v_cvt_pk_bf16_f32 v218, v46, v47
	v_cvt_pk_bf16_f32 v219, v48, v49
	v_add_f32_e32 v163, v163, v42
	v_add_f32_e32 v237, v237, v43
	s_waitcnt lgkmcnt(5)
	v_mfma_f32_32x32x16_bf16 v[18:33], v[178:181], v[216:219], v[18:33]
	s_waitcnt lgkmcnt(3)
	v_mfma_f32_32x32x16_bf16 v[2:17], v[182:185], v[216:219], v[2:17]
	v_add_f32_e32 v163, v163, v44
	v_add_f32_e32 v237, v237, v45
	v_add_f32_e32 v163, v163, v46
	v_add_f32_e32 v237, v237, v47
	v_add_f32_e32 v163, v163, v48
	v_add_f32_e32 v237, v237, v49
	v_add_f32_e32 v163, v163, v237
	v_cmp_lt_f32_e32 vcc, 0x45800000, v163
	v_add_f32_e32 v143, v143, v163
	s_cbranch_vccnz .Lat_postf0
.Lat_postdonef0:
.Lat_tail0:
	s_add_i32 s19, s19, 1
	s_add_i32 s21, s21, 64
	v_lshl_add_u64 v[138:139], v[138:139], 0, s[30:31]
	v_lshl_add_u64 v[136:137], v[136:137], 0, s[34:35]
	s_cmp_le_u32 s19, s36
	s_cbranch_scc0 .Lat_bandctl1
.Lat_head1:
	ds_read_b128 v[170:173], v140 offset:22528
	ds_read_b128 v[174:177], v140 offset:22560
	ds_read_b128 v[178:181], v140 offset:22592
	ds_read_b128 v[182:185], v140 offset:22624
	ds_read_b128 v[186:189], v140 offset:22656
	ds_read_b128 v[190:193], v140 offset:22688
	ds_read_b128 v[204:207], v141 offset:22528
	ds_read_b128 v[208:211], v141 offset:22560
	global_load_dwordx4 v[242:245], v[136:137], off
	global_load_dwordx4 v[246:249], v[136:137], off offset:128
	global_load_dwordx4 v[164:167], v[138:139], off
	s_waitcnt lgkmcnt(7)
	v_mfma_f32_32x32x16_bf16 v[50:65], v[170:173], v[66:69], v[146:161]
	ds_read_b128 v[170:173], v141 offset:22592
	s_waitcnt lgkmcnt(7)
	v_mfma_f32_32x32x16_bf16 v[50:65], v[174:177], v[70:73], v[50:65]
	ds_read_b128 v[174:177], v141 offset:22624
	s_waitcnt lgkmcnt(7)
	v_mfma_f32_32x32x16_bf16 v[50:65], v[178:181], v[74:77], v[50:65]
	ds_read_b128 v[178:181], v141 offset:22656
	s_waitcnt lgkmcnt(7)
	v_mfma_f32_32x32x16_bf16 v[50:65], v[182:185], v[78:81], v[50:65]
	ds_read_b128 v[182:185], v141 offset:22688
	s_waitcnt lgkmcnt(7)
	v_mfma_f32_32x32x16_bf16 v[50:65], v[186:189], v[82:85], v[50:65]
	s_waitcnt lgkmcnt(6)
	v_mfma_f32_32x32x16_bf16 v[50:65], v[190:193], v[86:89], v[50:65]
	ds_read_b64_tr_b16 v[186:187], v250 offset:13312
	ds_read_b64_tr_b16 v[188:189], v250 offset:14464
	ds_read_b64_tr_b16 v[190:191], v250 offset:13376
	ds_read_b64_tr_b16 v[192:193], v250 offset:14528
	s_waitcnt lgkmcnt(9)
	v_mfma_f32_32x32x16_bf16 v[34:49], v[204:207], v[66:69], v[146:161]
	ds_read_b64_tr_b16 v[204:205], v250 offset:15616
	ds_read_b64_tr_b16 v[206:207], v250 offset:16768
	s_waitcnt lgkmcnt(10)
	v_mfma_f32_32x32x16_bf16 v[34:49], v[208:211], v[70:73], v[34:49]
	ds_read_b64_tr_b16 v[208:209], v250 offset:15680
	ds_read_b64_tr_b16 v[210:211], v250 offset:16832
	s_nop 5
	v_exp_f32_e32 v50, v50
	v_exp_f32_e32 v51, v51
	v_exp_f32_e32 v52, v52
	v_exp_f32_e32 v53, v53
	s_waitcnt lgkmcnt(11)
	v_mfma_f32_32x32x16_bf16 v[34:49], v[170:173], v[74:77], v[34:49]
	v_exp_f32_e32 v54, v54
	v_exp_f32_e32 v55, v55
	v_exp_f32_e32 v56, v56
	v_exp_f32_e32 v57, v57
	v_cvt_pk_bf16_f32 v212, v50, v51
	v_cvt_pk_bf16_f32 v213, v52, v53
	v_cvt_pk_bf16_f32 v214, v54, v55
	v_cvt_pk_bf16_f32 v215, v56, v57
	s_waitcnt lgkmcnt(10)
	v_mfma_f32_32x32x16_bf16 v[34:49], v[174:177], v[78:81], v[34:49]
	v_add_f32_e32 v163, v50, v52
	v_add_f32_e32 v237, v51, v53
	s_waitcnt lgkmcnt(6)
	v_mfma_f32_32x32x16_bf16 v[18:33], v[186:189], v[212:215], v[18:33]
	v_exp_f32_e32 v58, v58
	v_exp_f32_e32 v59, v59
	v_exp_f32_e32 v60, v60
	s_waitcnt lgkmcnt(4)
	v_mfma_f32_32x32x16_bf16 v[2:17], v[190:193], v[212:215], v[2:17]
	v_exp_f32_e32 v61, v61
	v_exp_f32_e32 v62, v62
	v_exp_f32_e32 v63, v63
	v_mfma_f32_32x32x16_bf16 v[34:49], v[178:181], v[82:85], v[34:49]
	v_exp_f32_e32 v64, v64
	v_exp_f32_e32 v65, v65
	v_add_f32_e32 v163, v163, v54
	v_add_f32_e32 v237, v237, v55
	v_mfma_f32_32x32x16_bf16 v[34:49], v[182:185], v[86:89], v[34:49]
	v_cvt_pk_bf16_f32 v216, v58, v59
	v_cvt_pk_bf16_f32 v217, v60, v61
	v_cvt_pk_bf16_f32 v218, v62, v63
	v_cvt_pk_bf16_f32 v219, v64, v65
	v_add_f32_e32 v163, v163, v56
	v_add_f32_e32 v237, v237, v57
	v_add_f32_e32 v163, v163, v58
	v_add_f32_e32 v237, v237, v59
	s_waitcnt lgkmcnt(2)
	v_mfma_f32_32x32x16_bf16 v[18:33], v[204:207], v[216:219], v[18:33]
	v_add_f32_e32 v163, v163, v60
	v_add_f32_e32 v237, v237, v61
	v_add_f32_e32 v163, v163, v62
	s_waitcnt lgkmcnt(0)
	v_mfma_f32_32x32x16_bf16 v[2:17], v[208:211], v[216:219], v[2:17]
	v_add_f32_e32 v237, v237, v63
	v_add_f32_e32 v163, v163, v64
	v_add_f32_e32 v237, v237, v65
	s_barrier
	ds_read_b64_tr_b16 v[170:171], v250 offset:17920
	ds_read_b64_tr_b16 v[172:173], v250 offset:19072
	ds_read_b64_tr_b16 v[174:175], v250 offset:17984
	ds_read_b64_tr_b16 v[176:177], v250 offset:19136
	ds_read_b64_tr_b16 v[178:179], v250 offset:20224
	ds_read_b64_tr_b16 v[180:181], v250 offset:21376
	ds_read_b64_tr_b16 v[182:183], v250 offset:20288
	ds_read_b64_tr_b16 v[184:185], v250 offset:21440
	s_waitcnt vmcnt(6)
	ds_write_b128 v112, v[90:93]
	ds_write_b128 v113, v[94:97] offset:13312
	ds_write_b128 v115, v[98:101] offset:128
	v_exp_f32_e32 v34, v34
	v_exp_f32_e32 v35, v35
	v_exp_f32_e32 v36, v36
	v_exp_f32_e32 v37, v37
	v_exp_f32_e32 v38, v38
	v_exp_f32_e32 v39, v39
	v_exp_f32_e32 v40, v40
	v_exp_f32_e32 v41, v41
	v_cvt_pk_bf16_f32 v212, v34, v35
	v_cvt_pk_bf16_f32 v213, v36, v37
	v_cvt_pk_bf16_f32 v214, v38, v39
	v_cvt_pk_bf16_f32 v215, v40, v41
	v_exp_f32_e32 v42, v42
	v_exp_f32_e32 v43, v43
	s_waitcnt lgkmcnt(9)
	v_mfma_f32_32x32x16_bf16 v[18:33], v[170:173], v[212:215], v[18:33]
	s_waitcnt lgkmcnt(7)
	v_mfma_f32_32x32x16_bf16 v[2:17], v[174:177], v[212:215], v[2:17]
	v_exp_f32_e32 v44, v44
	v_add_f32_e32 v163, v163, v34
	v_exp_f32_e32 v45, v45
	v_add_f32_e32 v237, v237, v35
	v_exp_f32_e32 v46, v46
	v_add_f32_e32 v163, v163, v36
	v_exp_f32_e32 v47, v47
	v_add_f32_e32 v237, v237, v37
	v_exp_f32_e32 v48, v48
	v_add_f32_e32 v163, v163, v38
	v_exp_f32_e32 v49, v49
	v_add_f32_e32 v237, v237, v39
	v_add_f32_e32 v163, v163, v40
	v_add_f32_e32 v237, v237, v41
	v_cvt_pk_bf16_f32 v216, v42, v43
	v_cvt_pk_bf16_f32 v217, v44, v45
	v_cvt_pk_bf16_f32 v218, v46, v47
	v_cvt_pk_bf16_f32 v219, v48, v49
	v_add_f32_e32 v163, v163, v42
	v_add_f32_e32 v237, v237, v43
	s_waitcnt lgkmcnt(5)
	v_mfma_f32_32x32x16_bf16 v[18:33], v[178:181], v[216:219], v[18:33]
	s_waitcnt lgkmcnt(3)
	v_mfma_f32_32x32x16_bf16 v[2:17], v[182:185], v[216:219], v[2:17]
	v_add_f32_e32 v163, v163, v44
	v_add_f32_e32 v237, v237, v45
	v_add_f32_e32 v163, v163, v46
	v_add_f32_e32 v237, v237, v47
	v_add_f32_e32 v163, v163, v48
	v_add_f32_e32 v237, v237, v49
	v_add_f32_e32 v163, v163, v237
	v_cmp_lt_f32_e32 vcc, 0x45800000, v163
	v_add_f32_e32 v143, v143, v163
	s_cbranch_vccnz .Lat_postf1

.Lat_head2:
	ds_read_b128 v[170:173], v140 offset:45056
	ds_read_b128 v[174:177], v140 offset:45088
	ds_read_b128 v[178:181], v140 offset:45120
	ds_read_b128 v[182:185], v140 offset:45152
	ds_read_b128 v[186:189], v140 offset:45184
	ds_read_b128 v[190:193], v140 offset:45216
	ds_read_b128 v[204:207], v141 offset:45056
	ds_read_b128 v[208:211], v141 offset:45088
	global_load_dwordx4 v[90:93], v[136:137], off
	global_load_dwordx4 v[94:97], v[136:137], off offset:128
	global_load_dwordx4 v[98:101], v[138:139], off
	s_waitcnt lgkmcnt(7)
	v_mfma_f32_32x32x16_bf16 v[50:65], v[170:173], v[66:69], v[146:161]
	ds_read_b128 v[170:173], v141 offset:45120
	s_waitcnt lgkmcnt(7)
	v_mfma_f32_32x32x16_bf16 v[50:65], v[174:177], v[70:73], v[50:65]
	ds_read_b128 v[174:177], v141 offset:45152
	s_waitcnt lgkmcnt(7)
	v_mfma_f32_32x32x16_bf16 v[50:65], v[178:181], v[74:77], v[50:65]
	ds_read_b128 v[178:181], v141 offset:45184
	s_waitcnt lgkmcnt(7)
	v_mfma_f32_32x32x16_bf16 v[50:65], v[182:185], v[78:81], v[50:65]
	ds_read_b128 v[182:185], v141 offset:45216
	s_waitcnt lgkmcnt(7)
	v_mfma_f32_32x32x16_bf16 v[50:65], v[186:189], v[82:85], v[50:65]
	s_waitcnt lgkmcnt(6)
	v_mfma_f32_32x32x16_bf16 v[50:65], v[190:193], v[86:89], v[50:65]
	ds_read_b64_tr_b16 v[186:187], v251 offset:13312
	ds_read_b64_tr_b16 v[188:189], v251 offset:14464
	ds_read_b64_tr_b16 v[190:191], v251 offset:13376
	ds_read_b64_tr_b16 v[192:193], v251 offset:14528
	s_waitcnt lgkmcnt(9)
	v_mfma_f32_32x32x16_bf16 v[34:49], v[204:207], v[66:69], v[146:161]
	ds_read_b64_tr_b16 v[204:205], v251 offset:15616
	ds_read_b64_tr_b16 v[206:207], v251 offset:16768
	s_waitcnt lgkmcnt(10)
	v_mfma_f32_32x32x16_bf16 v[34:49], v[208:211], v[70:73], v[34:49]
	ds_read_b64_tr_b16 v[208:209], v251 offset:15680
	ds_read_b64_tr_b16 v[210:211], v251 offset:16832
	s_nop 5
	v_exp_f32_e32 v50, v50
	v_exp_f32_e32 v51, v51
	v_exp_f32_e32 v52, v52
	v_exp_f32_e32 v53, v53
	s_waitcnt lgkmcnt(11)
	v_mfma_f32_32x32x16_bf16 v[34:49], v[170:173], v[74:77], v[34:49]
	v_exp_f32_e32 v54, v54
	v_exp_f32_e32 v55, v55
	v_exp_f32_e32 v56, v56
	v_exp_f32_e32 v57, v57
	v_cvt_pk_bf16_f32 v212, v50, v51
	v_cvt_pk_bf16_f32 v213, v52, v53
	v_cvt_pk_bf16_f32 v214, v54, v55
	v_cvt_pk_bf16_f32 v215, v56, v57
	s_waitcnt lgkmcnt(10)
	v_mfma_f32_32x32x16_bf16 v[34:49], v[174:177], v[78:81], v[34:49]
	v_add_f32_e32 v163, v50, v52
	v_add_f32_e32 v237, v51, v53
	s_waitcnt lgkmcnt(6)
	v_mfma_f32_32x32x16_bf16 v[18:33], v[186:189], v[212:215], v[18:33]
	v_exp_f32_e32 v58, v58
	v_exp_f32_e32 v59, v59
	v_exp_f32_e32 v60, v60
	s_waitcnt lgkmcnt(4)
	v_mfma_f32_32x32x16_bf16 v[2:17], v[190:193], v[212:215], v[2:17]
	v_exp_f32_e32 v61, v61
	v_exp_f32_e32 v62, v62
	v_exp_f32_e32 v63, v63
	v_mfma_f32_32x32x16_bf16 v[34:49], v[178:181], v[82:85], v[34:49]
	v_exp_f32_e32 v64, v64
	v_exp_f32_e32 v65, v65
	v_add_f32_e32 v163, v163, v54
	v_add_f32_e32 v237, v237, v55
	v_mfma_f32_32x32x16_bf16 v[34:49], v[182:185], v[86:89], v[34:49]
	v_cvt_pk_bf16_f32 v216, v58, v59
	v_cvt_pk_bf16_f32 v217, v60, v61
	v_cvt_pk_bf16_f32 v218, v62, v63
	v_cvt_pk_bf16_f32 v219, v64, v65
	v_add_f32_e32 v163, v163, v56
	v_add_f32_e32 v237, v237, v57
	v_add_f32_e32 v163, v163, v58
	v_add_f32_e32 v237, v237, v59
	s_waitcnt lgkmcnt(2)
	v_mfma_f32_32x32x16_bf16 v[18:33], v[204:207], v[216:219], v[18:33]
	v_add_f32_e32 v163, v163, v60
	v_add_f32_e32 v237, v237, v61
	v_add_f32_e32 v163, v163, v62
	s_waitcnt lgkmcnt(0)
	v_mfma_f32_32x32x16_bf16 v[2:17], v[208:211], v[216:219], v[2:17]
	v_add_f32_e32 v237, v237, v63
	v_add_f32_e32 v163, v163, v64
	v_add_f32_e32 v237, v237, v65
	s_barrier
	ds_read_b64_tr_b16 v[170:171], v251 offset:17920
	ds_read_b64_tr_b16 v[172:173], v251 offset:19072
	ds_read_b64_tr_b16 v[174:175], v251 offset:17984
	ds_read_b64_tr_b16 v[176:177], v251 offset:19136
	ds_read_b64_tr_b16 v[178:179], v251 offset:20224
	ds_read_b64_tr_b16 v[180:181], v251 offset:21376
	ds_read_b64_tr_b16 v[182:183], v251 offset:20288
	ds_read_b64_tr_b16 v[184:185], v251 offset:21440
	s_waitcnt vmcnt(6)
	ds_write_b128 v112, v[220:223] offset:22528
	ds_write_b128 v113, v[224:227] offset:35840
	ds_write_b128 v115, v[228:231] offset:22656
	v_exp_f32_e32 v34, v34
	v_exp_f32_e32 v35, v35
	v_exp_f32_e32 v36, v36
	v_exp_f32_e32 v37, v37
	v_exp_f32_e32 v38, v38
	v_exp_f32_e32 v39, v39
	v_exp_f32_e32 v40, v40
	v_exp_f32_e32 v41, v41
	v_cvt_pk_bf16_f32 v212, v34, v35
	v_cvt_pk_bf16_f32 v213, v36, v37
	v_cvt_pk_bf16_f32 v214, v38, v39
	v_cvt_pk_bf16_f32 v215, v40, v41
	v_exp_f32_e32 v42, v42
	v_exp_f32_e32 v43, v43
	s_waitcnt lgkmcnt(9)
	v_mfma_f32_32x32x16_bf16 v[18:33], v[170:173], v[212:215], v[18:33]
	s_waitcnt lgkmcnt(7)
	v_mfma_f32_32x32x16_bf16 v[2:17], v[174:177], v[212:215], v[2:17]
	v_exp_f32_e32 v44, v44
	v_add_f32_e32 v163, v163, v34
	v_exp_f32_e32 v45, v45
	v_add_f32_e32 v237, v237, v35
	v_exp_f32_e32 v46, v46
	v_add_f32_e32 v163, v163, v36
	v_exp_f32_e32 v47, v47
	v_add_f32_e32 v237, v237, v37
	v_exp_f32_e32 v48, v48
	v_add_f32_e32 v163, v163, v38
	v_exp_f32_e32 v49, v49
	v_add_f32_e32 v237, v237, v39
	v_add_f32_e32 v163, v163, v40
	v_add_f32_e32 v237, v237, v41
	v_cvt_pk_bf16_f32 v216, v42, v43
	v_cvt_pk_bf16_f32 v217, v44, v45
	v_cvt_pk_bf16_f32 v218, v46, v47
	v_cvt_pk_bf16_f32 v219, v48, v49
	v_add_f32_e32 v163, v163, v42
	v_add_f32_e32 v237, v237, v43
	s_waitcnt lgkmcnt(5)
	v_mfma_f32_32x32x16_bf16 v[18:33], v[178:181], v[216:219], v[18:33]
	s_waitcnt lgkmcnt(3)
	v_mfma_f32_32x32x16_bf16 v[2:17], v[182:185], v[216:219], v[2:17]
	v_add_f32_e32 v163, v163, v44
	v_add_f32_e32 v237, v237, v45
	v_add_f32_e32 v163, v163, v46
	v_add_f32_e32 v237, v237, v47
	v_add_f32_e32 v163, v163, v48
	v_add_f32_e32 v237, v237, v49
	v_add_f32_e32 v163, v163, v237
	v_cmp_lt_f32_e32 vcc, 0x45800000, v163
	v_add_f32_e32 v143, v143, v163
	s_cbranch_vccnz .Lat_postf2
.Lat_postdonef2:
.Lat_tail2:
	s_add_i32 s19, s19, 1
	s_add_i32 s21, s21, 64
	v_lshl_add_u64 v[138:139], v[138:139], 0, s[30:31]
	v_lshl_add_u64 v[136:137], v[136:137], 0, s[34:35]
	s_cmp_le_u32 s19, s36
	s_cbranch_scc0 .Lat_bandctl0
	s_branch .Lat_head0
.Lat_first:
	ds_read_b128 v[170:173], v140
	ds_read_b128 v[174:177], v140 offset:32
	ds_read_b128 v[178:181], v140 offset:64
	ds_read_b128 v[182:185], v140 offset:96
	ds_read_b128 v[186:189], v140 offset:128
	ds_read_b128 v[190:193], v140 offset:160
	ds_read_b128 v[204:207], v141
	ds_read_b128 v[208:211], v141 offset:32
	s_add_i32 s23, s19, 3
	s_cmp_ge_u32 s23, s7
	s_cbranch_scc1 .Lat_noissue_x0
	global_load_dwordx4 v[220:223], v[136:137], off
	global_load_dwordx4 v[224:227], v[136:137], off offset:128
	global_load_dwordx4 v[228:231], v[138:139], off
.Lat_noissue_x0:
	s_waitcnt lgkmcnt(7)
	v_mfma_f32_32x32x16_bf16 v[50:65], v[170:173], v[66:69], v[146:161]
	ds_read_b128 v[170:173], v141 offset:64
	s_waitcnt lgkmcnt(7)
	v_mfma_f32_32x32x16_bf16 v[50:65], v[174:177], v[70:73], v[50:65]
	ds_read_b128 v[174:177], v141 offset:96
	s_waitcnt lgkmcnt(7)
	v_mfma_f32_32x32x16_bf16 v[50:65], v[178:181], v[74:77], v[50:65]
	ds_read_b128 v[178:181], v141 offset:128
	s_waitcnt lgkmcnt(7)
	v_mfma_f32_32x32x16_bf16 v[50:65], v[182:185], v[78:81], v[50:65]
	ds_read_b128 v[182:185], v141 offset:160
	s_waitcnt lgkmcnt(7)
	v_mfma_f32_32x32x16_bf16 v[50:65], v[186:189], v[82:85], v[50:65]
	s_waitcnt lgkmcnt(6)
	v_mfma_f32_32x32x16_bf16 v[50:65], v[190:193], v[86:89], v[50:65]
	ds_read_b64_tr_b16 v[186:187], v169 offset:13312
	ds_read_b64_tr_b16 v[188:189], v169 offset:14464
	ds_read_b64_tr_b16 v[190:191], v169 offset:13376
	ds_read_b64_tr_b16 v[192:193], v169 offset:14528
	s_nop 7
	s_nop 1
	s_andn2_b64 vcc, exec, s[10:11]
	s_cbranch_vccnz .Lat_xnomaskA0
	v_add_u32_e32 v0, s21, v121
	v_mov_b32_e32 v145, v0
	v_add_u32_e32 v168, 1, v0
	v_cmp_le_i32_e64 vcc, v145, v102
	v_add_u32_e32 v252, 2, v0
	v_cmp_le_i32_e64 s[28:29], v168, v102
	v_cndmask_b32_e64 v50, v203, v50, vcc
	v_add_u32_e32 v145, 3, v0
	v_cmp_le_i32_e64 vcc, v252, v102
	v_cndmask_b32_e64 v51, v203, v51, s[28:29]
	v_add_u32_e32 v168, 8, v0
	v_cmp_le_i32_e64 s[28:29], v145, v102
	v_cndmask_b32_e64 v52, v203, v52, vcc
	v_add_u32_e32 v252, 9, v0
	v_cmp_le_i32_e64 vcc, v168, v102
	v_cndmask_b32_e64 v53, v203, v53, s[28:29]
	v_add_u32_e32 v145, 10, v0
	v_cmp_le_i32_e64 s[28:29], v252, v102
	v_cndmask_b32_e64 v54, v203, v54, vcc
	v_add_u32_e32 v168, 11, v0
	v_cmp_le_i32_e64 vcc, v145, v102
	v_cndmask_b32_e64 v55, v203, v55, s[28:29]
	v_add_u32_e32 v252, 16, v0
	v_cmp_le_i32_e64 s[28:29], v168, v102
	v_cndmask_b32_e64 v56, v203, v56, vcc
	v_add_u32_e32 v145, 17, v0
	v_cmp_le_i32_e64 vcc, v252, v102
	v_cndmask_b32_e64 v57, v203, v57, s[28:29]
	v_add_u32_e32 v168, 18, v0
	v_cmp_le_i32_e64 s[28:29], v145, v102
	v_cndmask_b32_e64 v58, v203, v58, vcc
	v_add_u32_e32 v252, 19, v0
	v_cmp_le_i32_e64 vcc, v168, v102
	v_cndmask_b32_e64 v59, v203, v59, s[28:29]
	v_add_u32_e32 v145, 24, v0
	v_cmp_le_i32_e64 s[28:29], v252, v102
	v_cndmask_b32_e64 v60, v203, v60, vcc
	v_add_u32_e32 v168, 25, v0
	v_cmp_le_i32_e64 vcc, v145, v102
	v_cndmask_b32_e64 v61, v203, v61, s[28:29]
	v_add_u32_e32 v252, 26, v0
	v_cmp_le_i32_e64 s[28:29], v168, v102
	v_cndmask_b32_e64 v62, v203, v62, vcc
	v_add_u32_e32 v145, 27, v0
	v_cmp_le_i32_e64 vcc, v252, v102
	v_cndmask_b32_e64 v63, v203, v63, s[28:29]
	v_cmp_le_i32_e64 s[28:29], v145, v102
	v_cndmask_b32_e64 v64, v203, v64, vcc
	s_nop 1
	v_cndmask_b32_e64 v65, v203, v65, s[28:29]

.Lat_bandctl0:
	s_add_i32 s12, s20, s21
	s_cmp_le_i32 s12, s38
	s_cbranch_scc0 .Lat_bskip0
	ds_read_b128 v[170:173], v140
	ds_read_b128 v[174:177], v140 offset:32
	ds_read_b128 v[178:181], v140 offset:64
	ds_read_b128 v[182:185], v140 offset:96
	ds_read_b128 v[186:189], v140 offset:128
	ds_read_b128 v[190:193], v140 offset:160
	ds_read_b128 v[204:207], v141
	ds_read_b128 v[208:211], v141 offset:32
	s_waitcnt lgkmcnt(7)
	v_mfma_f32_32x32x16_bf16 v[50:65], v[170:173], v[66:69], v[146:161]
	ds_read_b128 v[170:173], v141 offset:64
	s_waitcnt lgkmcnt(7)
	v_mfma_f32_32x32x16_bf16 v[50:65], v[174:177], v[70:73], v[50:65]
	ds_read_b128 v[174:177], v141 offset:96
	s_waitcnt lgkmcnt(7)
	v_mfma_f32_32x32x16_bf16 v[50:65], v[178:181], v[74:77], v[50:65]
	ds_read_b128 v[178:181], v141 offset:128
	s_waitcnt lgkmcnt(7)
	v_mfma_f32_32x32x16_bf16 v[50:65], v[182:185], v[78:81], v[50:65]
	ds_read_b128 v[182:185], v141 offset:160
	s_waitcnt lgkmcnt(7)
	v_mfma_f32_32x32x16_bf16 v[50:65], v[186:189], v[82:85], v[50:65]
	s_waitcnt lgkmcnt(6)
	v_mfma_f32_32x32x16_bf16 v[50:65], v[190:193], v[86:89], v[50:65]
	ds_read_b64_tr_b16 v[186:187], v169 offset:13312
	ds_read_b64_tr_b16 v[188:189], v169 offset:14464
	ds_read_b64_tr_b16 v[190:191], v169 offset:13376
	ds_read_b64_tr_b16 v[192:193], v169 offset:14528
	s_waitcnt lgkmcnt(9)
	v_mfma_f32_32x32x16_bf16 v[34:49], v[204:207], v[66:69], v[146:161]
	ds_read_b64_tr_b16 v[204:205], v169 offset:15616
	ds_read_b64_tr_b16 v[206:207], v169 offset:16768
	s_waitcnt lgkmcnt(10)
	v_mfma_f32_32x32x16_bf16 v[34:49], v[208:211], v[70:73], v[34:49]
	ds_read_b64_tr_b16 v[208:209], v169 offset:15680
	ds_read_b64_tr_b16 v[210:211], v169 offset:16832
	s_nop 5
	v_add_u32_e32 v0, s21, v121
	v_mov_b32_e32 v145, v0
	v_add_u32_e32 v168, 1, v0
	v_cmp_le_i32_e64 vcc, v145, v102
	v_add_u32_e32 v252, 2, v0
	v_cmp_le_i32_e64 s[28:29], v168, v102
	v_cndmask_b32_e64 v50, v203, v50, vcc
	v_add_u32_e32 v145, 3, v0
	v_cmp_le_i32_e64 vcc, v252, v102
	v_cndmask_b32_e64 v51, v203, v51, s[28:29]
	v_add_u32_e32 v168, 8, v0
	v_cmp_le_i32_e64 s[28:29], v145, v102
	v_cndmask_b32_e64 v52, v203, v52, vcc
	v_add_u32_e32 v252, 9, v0
	v_cmp_le_i32_e64 vcc, v168, v102
	v_cndmask_b32_e64 v53, v203, v53, s[28:29]
	v_add_u32_e32 v145, 10, v0
	v_cmp_le_i32_e64 s[28:29], v252, v102
	v_cndmask_b32_e64 v54, v203, v54, vcc
	v_add_u32_e32 v168, 11, v0
	v_cmp_le_i32_e64 vcc, v145, v102
	v_cndmask_b32_e64 v55, v203, v55, s[28:29]
	v_add_u32_e32 v252, 16, v0
	v_cmp_le_i32_e64 s[28:29], v168, v102
	v_cndmask_b32_e64 v56, v203, v56, vcc
	v_add_u32_e32 v145, 17, v0
	v_cmp_le_i32_e64 vcc, v252, v102
	v_cndmask_b32_e64 v57, v203, v57, s[28:29]
	v_add_u32_e32 v168, 18, v0
	v_cmp_le_i32_e64 s[28:29], v145, v102
	v_cndmask_b32_e64 v58, v203, v58, vcc
	v_add_u32_e32 v252, 19, v0
	v_cmp_le_i32_e64 vcc, v168, v102
	v_cndmask_b32_e64 v59, v203, v59, s[28:29]
	v_add_u32_e32 v145, 24, v0
	v_cmp_le_i32_e64 s[28:29], v252, v102
	v_cndmask_b32_e64 v60, v203, v60, vcc
	v_add_u32_e32 v168, 25, v0
	v_cmp_le_i32_e64 vcc, v145, v102
	v_cndmask_b32_e64 v61, v203, v61, s[28:29]
	v_add_u32_e32 v252, 26, v0
	v_cmp_le_i32_e64 s[28:29], v168, v102
	v_cndmask_b32_e64 v62, v203, v62, vcc
	v_add_u32_e32 v145, 27, v0
	v_cmp_le_i32_e64 vcc, v252, v102
	v_cndmask_b32_e64 v63, v203, v63, s[28:29]
	v_cmp_le_i32_e64 s[28:29], v145, v102
	v_cndmask_b32_e64 v64, v203, v64, vcc
	s_nop 1
	v_cndmask_b32_e64 v65, v203, v65, s[28:29]
	v_exp_f32_e32 v50, v50
	v_exp_f32_e32 v51, v51
	v_exp_f32_e32 v52, v52
	v_exp_f32_e32 v53, v53
	s_waitcnt lgkmcnt(11)
	v_mfma_f32_32x32x16_bf16 v[34:49], v[170:173], v[74:77], v[34:49]
	v_exp_f32_e32 v54, v54
	v_exp_f32_e32 v55, v55
	v_exp_f32_e32 v56, v56
	v_exp_f32_e32 v57, v57
	v_cvt_pk_bf16_f32 v212, v50, v51
	v_cvt_pk_bf16_f32 v213, v52, v53
	v_cvt_pk_bf16_f32 v214, v54, v55
	v_cvt_pk_bf16_f32 v215, v56, v57
	s_waitcnt lgkmcnt(10)
	v_mfma_f32_32x32x16_bf16 v[34:49], v[174:177], v[78:81], v[34:49]
	v_add_f32_e32 v163, v50, v52
	v_add_f32_e32 v237, v51, v53
	s_waitcnt lgkmcnt(6)
	v_mfma_f32_32x32x16_bf16 v[18:33], v[186:189], v[212:215], v[18:33]
	v_exp_f32_e32 v58, v58
	v_exp_f32_e32 v59, v59
	v_exp_f32_e32 v60, v60
	s_waitcnt lgkmcnt(4)
	v_mfma_f32_32x32x16_bf16 v[2:17], v[190:193], v[212:215], v[2:17]
	v_exp_f32_e32 v61, v61
	v_exp_f32_e32 v62, v62
	v_exp_f32_e32 v63, v63
	v_mfma_f32_32x32x16_bf16 v[34:49], v[178:181], v[82:85], v[34:49]
	v_exp_f32_e32 v64, v64
	v_exp_f32_e32 v65, v65
	v_add_f32_e32 v163, v163, v54
	v_add_f32_e32 v237, v237, v55
	v_mfma_f32_32x32x16_bf16 v[34:49], v[182:185], v[86:89], v[34:49]
	v_cvt_pk_bf16_f32 v216, v58, v59
	v_cvt_pk_bf16_f32 v217, v60, v61
	v_cvt_pk_bf16_f32 v218, v62, v63
	v_cvt_pk_bf16_f32 v219, v64, v65
	v_add_f32_e32 v163, v163, v56
	v_add_f32_e32 v237, v237, v57
	v_add_f32_e32 v163, v163, v58
	v_add_f32_e32 v237, v237, v59
	s_waitcnt lgkmcnt(2)
	v_mfma_f32_32x32x16_bf16 v[18:33], v[204:207], v[216:219], v[18:33]
	v_add_f32_e32 v163, v163, v60
	v_add_f32_e32 v237, v237, v61
	v_add_f32_e32 v163, v163, v62
	s_waitcnt lgkmcnt(0)
	v_mfma_f32_32x32x16_bf16 v[2:17], v[208:211], v[216:219], v[2:17]
	v_add_f32_e32 v237, v237, v63
	v_add_f32_e32 v163, v163, v64
	v_add_f32_e32 v237, v237, v65
	s_barrier
	ds_read_b64_tr_b16 v[170:171], v169 offset:17920
	ds_read_b64_tr_b16 v[172:173], v169 offset:19072
	ds_read_b64_tr_b16 v[174:175], v169 offset:17984
	ds_read_b64_tr_b16 v[176:177], v169 offset:19136
	ds_read_b64_tr_b16 v[178:179], v169 offset:20224
	ds_read_b64_tr_b16 v[180:181], v169 offset:21376
	ds_read_b64_tr_b16 v[182:183], v169 offset:20288
	ds_read_b64_tr_b16 v[184:185], v169 offset:21440
	s_cmp_eq_u32 s19, s37
	s_cbranch_scc1 .Lat_bw3_0
	s_waitcnt vmcnt(0)
	s_branch .Lat_bwd_0

.Lat_bwd_0:
	ds_write_b128 v112, v[242:245] offset:45056
	ds_write_b128 v113, v[246:249] offset:58368
	ds_write_b128 v115, v[164:167] offset:45184
	v_add_u32_e32 v0, s21, v121
	v_add_u32_e32 v145, 32, v0
	v_add_u32_e32 v168, 33, v0
	v_cmp_le_i32_e64 vcc, v145, v102
	v_add_u32_e32 v252, 34, v0
	v_cmp_le_i32_e64 s[28:29], v168, v102
	v_cndmask_b32_e64 v34, v203, v34, vcc
	v_add_u32_e32 v145, 35, v0
	v_cmp_le_i32_e64 vcc, v252, v102
	v_cndmask_b32_e64 v35, v203, v35, s[28:29]
	v_add_u32_e32 v168, 40, v0
	v_cmp_le_i32_e64 s[28:29], v145, v102
	v_cndmask_b32_e64 v36, v203, v36, vcc
	v_add_u32_e32 v252, 41, v0
	v_cmp_le_i32_e64 vcc, v168, v102
	v_cndmask_b32_e64 v37, v203, v37, s[28:29]
	v_add_u32_e32 v145, 42, v0
	v_cmp_le_i32_e64 s[28:29], v252, v102
	v_cndmask_b32_e64 v38, v203, v38, vcc
	v_add_u32_e32 v168, 43, v0
	v_cmp_le_i32_e64 vcc, v145, v102
	v_cndmask_b32_e64 v39, v203, v39, s[28:29]
	v_add_u32_e32 v252, 48, v0
	v_cmp_le_i32_e64 s[28:29], v168, v102
	v_cndmask_b32_e64 v40, v203, v40, vcc
	v_add_u32_e32 v145, 49, v0
	v_cmp_le_i32_e64 vcc, v252, v102
	v_cndmask_b32_e64 v41, v203, v41, s[28:29]
	v_add_u32_e32 v168, 50, v0
	v_cmp_le_i32_e64 s[28:29], v145, v102
	v_cndmask_b32_e64 v42, v203, v42, vcc
	v_add_u32_e32 v252, 51, v0
	v_cmp_le_i32_e64 vcc, v168, v102
	v_cndmask_b32_e64 v43, v203, v43, s[28:29]
	v_add_u32_e32 v145, 56, v0
	v_cmp_le_i32_e64 s[28:29], v252, v102
	v_cndmask_b32_e64 v44, v203, v44, vcc
	v_add_u32_e32 v168, 57, v0
	v_cmp_le_i32_e64 vcc, v145, v102
	v_cndmask_b32_e64 v45, v203, v45, s[28:29]
	v_add_u32_e32 v252, 58, v0
	v_cmp_le_i32_e64 s[28:29], v168, v102
	v_cndmask_b32_e64 v46, v203, v46, vcc
	v_add_u32_e32 v145, 59, v0
	v_cmp_le_i32_e64 vcc, v252, v102
	v_cndmask_b32_e64 v47, v203, v47, s[28:29]
	v_cmp_le_i32_e64 s[28:29], v145, v102
	v_cndmask_b32_e64 v48, v203, v48, vcc
	s_nop 1
	v_cndmask_b32_e64 v49, v203, v49, s[28:29]
	v_exp_f32_e32 v34, v34
	v_exp_f32_e32 v35, v35
	v_exp_f32_e32 v36, v36
	v_exp_f32_e32 v37, v37
	v_exp_f32_e32 v38, v38
	v_exp_f32_e32 v39, v39
	v_exp_f32_e32 v40, v40
	v_exp_f32_e32 v41, v41
	v_cvt_pk_bf16_f32 v212, v34, v35
	v_cvt_pk_bf16_f32 v213, v36, v37
	v_cvt_pk_bf16_f32 v214, v38, v39
	v_cvt_pk_bf16_f32 v215, v40, v41
	v_exp_f32_e32 v42, v42
	v_exp_f32_e32 v43, v43
	s_waitcnt lgkmcnt(9)
	v_mfma_f32_32x32x16_bf16 v[18:33], v[170:173], v[212:215], v[18:33]
	s_waitcnt lgkmcnt(7)
	v_mfma_f32_32x32x16_bf16 v[2:17], v[174:177], v[212:215], v[2:17]
	v_exp_f32_e32 v44, v44
	v_add_f32_e32 v163, v163, v34
	v_exp_f32_e32 v45, v45
	v_add_f32_e32 v237, v237, v35
	v_exp_f32_e32 v46, v46
	v_add_f32_e32 v163, v163, v36
	v_exp_f32_e32 v47, v47
	v_add_f32_e32 v237, v237, v37
	v_exp_f32_e32 v48, v48
	v_add_f32_e32 v163, v163, v38
	v_exp_f32_e32 v49, v49
	v_add_f32_e32 v237, v237, v39
	v_add_f32_e32 v163, v163, v40
	v_add_f32_e32 v237, v237, v41
	v_cvt_pk_bf16_f32 v216, v42, v43
	v_cvt_pk_bf16_f32 v217, v44, v45
	v_cvt_pk_bf16_f32 v218, v46, v47
	v_cvt_pk_bf16_f32 v219, v48, v49
	v_add_f32_e32 v163, v163, v42
	v_add_f32_e32 v237, v237, v43
	s_waitcnt lgkmcnt(5)
	v_mfma_f32_32x32x16_bf16 v[18:33], v[178:181], v[216:219], v[18:33]
	s_waitcnt lgkmcnt(3)
	v_mfma_f32_32x32x16_bf16 v[2:17], v[182:185], v[216:219], v[2:17]
	v_add_f32_e32 v163, v163, v44
	v_add_f32_e32 v237, v237, v45
	v_add_f32_e32 v163, v163, v46
	v_add_f32_e32 v237, v237, v47
	v_add_f32_e32 v163, v163, v48
	v_add_f32_e32 v237, v237, v49
	v_add_f32_e32 v163, v163, v237
	v_cmp_lt_f32_e32 vcc, 0x45800000, v163
	v_add_f32_e32 v143, v143, v163
	s_cbranch_vccnz .Lat_postb0

.Lat_bskip0:
	s_waitcnt lgkmcnt(0)
	s_barrier
	s_waitcnt vmcnt(0)
	ds_write_b128 v112, v[242:245] offset:45056
	ds_write_b128 v113, v[246:249] offset:58368
	ds_write_b128 v115, v[164:167] offset:45184
.Lat_btail0:
	s_add_i32 s19, s19, 1
	s_add_i32 s21, s21, 64
	s_cmp_le_u32 s19, s7
	s_cbranch_scc0 .LBB0_520
	s_branch .Lat_bandctl1
.Lat_bandctl1:
	s_add_i32 s12, s20, s21
	s_cmp_le_i32 s12, s38
	s_cbranch_scc0 .Lat_bskip1
	ds_read_b128 v[170:173], v140 offset:22528
	ds_read_b128 v[174:177], v140 offset:22560
	ds_read_b128 v[178:181], v140 offset:22592
	ds_read_b128 v[182:185], v140 offset:22624
	ds_read_b128 v[186:189], v140 offset:22656
	ds_read_b128 v[190:193], v140 offset:22688
	ds_read_b128 v[204:207], v141 offset:22528
	ds_read_b128 v[208:211], v141 offset:22560
	s_waitcnt lgkmcnt(7)
	v_mfma_f32_32x32x16_bf16 v[50:65], v[170:173], v[66:69], v[146:161]
	ds_read_b128 v[170:173], v141 offset:22592
	s_waitcnt lgkmcnt(7)
	v_mfma_f32_32x32x16_bf16 v[50:65], v[174:177], v[70:73], v[50:65]
	ds_read_b128 v[174:177], v141 offset:22624
	s_waitcnt lgkmcnt(7)
	v_mfma_f32_32x32x16_bf16 v[50:65], v[178:181], v[74:77], v[50:65]
	ds_read_b128 v[178:181], v141 offset:22656
	s_waitcnt lgkmcnt(7)
	v_mfma_f32_32x32x16_bf16 v[50:65], v[182:185], v[78:81], v[50:65]
	ds_read_b128 v[182:185], v141 offset:22688
	s_waitcnt lgkmcnt(7)
	v_mfma_f32_32x32x16_bf16 v[50:65], v[186:189], v[82:85], v[50:65]
	s_waitcnt lgkmcnt(6)
	v_mfma_f32_32x32x16_bf16 v[50:65], v[190:193], v[86:89], v[50:65]
	ds_read_b64_tr_b16 v[186:187], v250 offset:13312
	ds_read_b64_tr_b16 v[188:189], v250 offset:14464
	ds_read_b64_tr_b16 v[190:191], v250 offset:13376
	ds_read_b64_tr_b16 v[192:193], v250 offset:14528
	s_waitcnt lgkmcnt(9)
	v_mfma_f32_32x32x16_bf16 v[34:49], v[204:207], v[66:69], v[146:161]
	ds_read_b64_tr_b16 v[204:205], v250 offset:15616
	ds_read_b64_tr_b16 v[206:207], v250 offset:16768
	s_waitcnt lgkmcnt(10)
	v_mfma_f32_32x32x16_bf16 v[34:49], v[208:211], v[70:73], v[34:49]
	ds_read_b64_tr_b16 v[208:209], v250 offset:15680
	ds_read_b64_tr_b16 v[210:211], v250 offset:16832
	s_nop 5
	v_add_u32_e32 v0, s21, v121
	v_mov_b32_e32 v145, v0
	v_add_u32_e32 v168, 1, v0
	v_cmp_le_i32_e64 vcc, v145, v102
	v_add_u32_e32 v252, 2, v0
	v_cmp_le_i32_e64 s[28:29], v168, v102
	v_cndmask_b32_e64 v50, v203, v50, vcc
	v_add_u32_e32 v145, 3, v0
	v_cmp_le_i32_e64 vcc, v252, v102
	v_cndmask_b32_e64 v51, v203, v51, s[28:29]
	v_add_u32_e32 v168, 8, v0
	v_cmp_le_i32_e64 s[28:29], v145, v102
	v_cndmask_b32_e64 v52, v203, v52, vcc
	v_add_u32_e32 v252, 9, v0
	v_cmp_le_i32_e64 vcc, v168, v102
	v_cndmask_b32_e64 v53, v203, v53, s[28:29]
	v_add_u32_e32 v145, 10, v0
	v_cmp_le_i32_e64 s[28:29], v252, v102
	v_cndmask_b32_e64 v54, v203, v54, vcc
	v_add_u32_e32 v168, 11, v0
	v_cmp_le_i32_e64 vcc, v145, v102
	v_cndmask_b32_e64 v55, v203, v55, s[28:29]
	v_add_u32_e32 v252, 16, v0
	v_cmp_le_i32_e64 s[28:29], v168, v102
	v_cndmask_b32_e64 v56, v203, v56, vcc
	v_add_u32_e32 v145, 17, v0
	v_cmp_le_i32_e64 vcc, v252, v102
	v_cndmask_b32_e64 v57, v203, v57, s[28:29]
	v_add_u32_e32 v168, 18, v0
	v_cmp_le_i32_e64 s[28:29], v145, v102
	v_cndmask_b32_e64 v58, v203, v58, vcc
	v_add_u32_e32 v252, 19, v0
	v_cmp_le_i32_e64 vcc, v168, v102
	v_cndmask_b32_e64 v59, v203, v59, s[28:29]
	v_add_u32_e32 v145, 24, v0
	v_cmp_le_i32_e64 s[28:29], v252, v102
	v_cndmask_b32_e64 v60, v203, v60, vcc
	v_add_u32_e32 v168, 25, v0
	v_cmp_le_i32_e64 vcc, v145, v102
	v_cndmask_b32_e64 v61, v203, v61, s[28:29]
	v_add_u32_e32 v252, 26, v0
	v_cmp_le_i32_e64 s[28:29], v168, v102
	v_cndmask_b32_e64 v62, v203, v62, vcc
	v_add_u32_e32 v145, 27, v0
	v_cmp_le_i32_e64 vcc, v252, v102
	v_cndmask_b32_e64 v63, v203, v63, s[28:29]
	v_cmp_le_i32_e64 s[28:29], v145, v102
	v_cndmask_b32_e64 v64, v203, v64, vcc
	s_nop 1
	v_cndmask_b32_e64 v65, v203, v65, s[28:29]
	v_exp_f32_e32 v50, v50
	v_exp_f32_e32 v51, v51
	v_exp_f32_e32 v52, v52
	v_exp_f32_e32 v53, v53
	s_waitcnt lgkmcnt(11)
	v_mfma_f32_32x32x16_bf16 v[34:49], v[170:173], v[74:77], v[34:49]
	v_exp_f32_e32 v54, v54
	v_exp_f32_e32 v55, v55
	v_exp_f32_e32 v56, v56
	v_exp_f32_e32 v57, v57
	v_cvt_pk_bf16_f32 v212, v50, v51
	v_cvt_pk_bf16_f32 v213, v52, v53
	v_cvt_pk_bf16_f32 v214, v54, v55
	v_cvt_pk_bf16_f32 v215, v56, v57
	s_waitcnt lgkmcnt(10)
	v_mfma_f32_32x32x16_bf16 v[34:49], v[174:177], v[78:81], v[34:49]
	v_add_f32_e32 v163, v50, v52
	v_add_f32_e32 v237, v51, v53
	s_waitcnt lgkmcnt(6)
	v_mfma_f32_32x32x16_bf16 v[18:33], v[186:189], v[212:215], v[18:33]
	v_exp_f32_e32 v58, v58
	v_exp_f32_e32 v59, v59
	v_exp_f32_e32 v60, v60
	s_waitcnt lgkmcnt(4)
	v_mfma_f32_32x32x16_bf16 v[2:17], v[190:193], v[212:215], v[2:17]
	v_exp_f32_e32 v61, v61
	v_exp_f32_e32 v62, v62
	v_exp_f32_e32 v63, v63
	v_mfma_f32_32x32x16_bf16 v[34:49], v[178:181], v[82:85], v[34:49]
	v_exp_f32_e32 v64, v64
	v_exp_f32_e32 v65, v65
	v_add_f32_e32 v163, v163, v54
	v_add_f32_e32 v237, v237, v55
	v_mfma_f32_32x32x16_bf16 v[34:49], v[182:185], v[86:89], v[34:49]
	v_cvt_pk_bf16_f32 v216, v58, v59
	v_cvt_pk_bf16_f32 v217, v60, v61
	v_cvt_pk_bf16_f32 v218, v62, v63
	v_cvt_pk_bf16_f32 v219, v64, v65
	v_add_f32_e32 v163, v163, v56
	v_add_f32_e32 v237, v237, v57
	v_add_f32_e32 v163, v163, v58
	v_add_f32_e32 v237, v237, v59
	s_waitcnt lgkmcnt(2)
	v_mfma_f32_32x32x16_bf16 v[18:33], v[204:207], v[216:219], v[18:33]
	v_add_f32_e32 v163, v163, v60
	v_add_f32_e32 v237, v237, v61
	v_add_f32_e32 v163, v163, v62
	s_waitcnt lgkmcnt(0)
	v_mfma_f32_32x32x16_bf16 v[2:17], v[208:211], v[216:219], v[2:17]
	v_add_f32_e32 v237, v237, v63
	v_add_f32_e32 v163, v163, v64
	v_add_f32_e32 v237, v237, v65
	s_barrier
	ds_read_b64_tr_b16 v[170:171], v250 offset:17920
	ds_read_b64_tr_b16 v[172:173], v250 offset:19072
	ds_read_b64_tr_b16 v[174:175], v250 offset:17984
	ds_read_b64_tr_b16 v[176:177], v250 offset:19136
	ds_read_b64_tr_b16 v[178:179], v250 offset:20224
	ds_read_b64_tr_b16 v[180:181], v250 offset:21376
	ds_read_b64_tr_b16 v[182:183], v250 offset:20288
	ds_read_b64_tr_b16 v[184:185], v250 offset:21440
	s_cmp_eq_u32 s19, s37
	s_cbranch_scc1 .Lat_bw3_1
	s_waitcnt vmcnt(0)
	s_branch .Lat_bwd_1

.Lat_bwd_1:
	ds_write_b128 v112, v[90:93]
	ds_write_b128 v113, v[94:97] offset:13312
	ds_write_b128 v115, v[98:101] offset:128
	v_add_u32_e32 v0, s21, v121
	v_add_u32_e32 v145, 32, v0
	v_add_u32_e32 v168, 33, v0
	v_cmp_le_i32_e64 vcc, v145, v102
	v_add_u32_e32 v252, 34, v0
	v_cmp_le_i32_e64 s[28:29], v168, v102
	v_cndmask_b32_e64 v34, v203, v34, vcc
	v_add_u32_e32 v145, 35, v0
	v_cmp_le_i32_e64 vcc, v252, v102
	v_cndmask_b32_e64 v35, v203, v35, s[28:29]
	v_add_u32_e32 v168, 40, v0
	v_cmp_le_i32_e64 s[28:29], v145, v102
	v_cndmask_b32_e64 v36, v203, v36, vcc
	v_add_u32_e32 v252, 41, v0
	v_cmp_le_i32_e64 vcc, v168, v102
	v_cndmask_b32_e64 v37, v203, v37, s[28:29]
	v_add_u32_e32 v145, 42, v0
	v_cmp_le_i32_e64 s[28:29], v252, v102
	v_cndmask_b32_e64 v38, v203, v38, vcc
	v_add_u32_e32 v168, 43, v0
	v_cmp_le_i32_e64 vcc, v145, v102
	v_cndmask_b32_e64 v39, v203, v39, s[28:29]
	v_add_u32_e32 v252, 48, v0
	v_cmp_le_i32_e64 s[28:29], v168, v102
	v_cndmask_b32_e64 v40, v203, v40, vcc
	v_add_u32_e32 v145, 49, v0
	v_cmp_le_i32_e64 vcc, v252, v102
	v_cndmask_b32_e64 v41, v203, v41, s[28:29]
	v_add_u32_e32 v168, 50, v0
	v_cmp_le_i32_e64 s[28:29], v145, v102
	v_cndmask_b32_e64 v42, v203, v42, vcc
	v_add_u32_e32 v252, 51, v0
	v_cmp_le_i32_e64 vcc, v168, v102
	v_cndmask_b32_e64 v43, v203, v43, s[28:29]
	v_add_u32_e32 v145, 56, v0
	v_cmp_le_i32_e64 s[28:29], v252, v102
	v_cndmask_b32_e64 v44, v203, v44, vcc
	v_add_u32_e32 v168, 57, v0
	v_cmp_le_i32_e64 vcc, v145, v102
	v_cndmask_b32_e64 v45, v203, v45, s[28:29]
	v_add_u32_e32 v252, 58, v0
	v_cmp_le_i32_e64 s[28:29], v168, v102
	v_cndmask_b32_e64 v46, v203, v46, vcc
	v_add_u32_e32 v145, 59, v0
	v_cmp_le_i32_e64 vcc, v252, v102
	v_cndmask_b32_e64 v47, v203, v47, s[28:29]
	v_cmp_le_i32_e64 s[28:29], v145, v102
	v_cndmask_b32_e64 v48, v203, v48, vcc
	s_nop 1
	v_cndmask_b32_e64 v49, v203, v49, s[28:29]
	v_exp_f32_e32 v34, v34
	v_exp_f32_e32 v35, v35
	v_exp_f32_e32 v36, v36
	v_exp_f32_e32 v37, v37
	v_exp_f32_e32 v38, v38
	v_exp_f32_e32 v39, v39
	v_exp_f32_e32 v40, v40
	v_exp_f32_e32 v41, v41
	v_cvt_pk_bf16_f32 v212, v34, v35
	v_cvt_pk_bf16_f32 v213, v36, v37
	v_cvt_pk_bf16_f32 v214, v38, v39
	v_cvt_pk_bf16_f32 v215, v40, v41
	v_exp_f32_e32 v42, v42
	v_exp_f32_e32 v43, v43
	s_waitcnt lgkmcnt(9)
	v_mfma_f32_32x32x16_bf16 v[18:33], v[170:173], v[212:215], v[18:33]
	s_waitcnt lgkmcnt(7)
	v_mfma_f32_32x32x16_bf16 v[2:17], v[174:177], v[212:215], v[2:17]
	v_exp_f32_e32 v44, v44
	v_add_f32_e32 v163, v163, v34
	v_exp_f32_e32 v45, v45
	v_add_f32_e32 v237, v237, v35
	v_exp_f32_e32 v46, v46
	v_add_f32_e32 v163, v163, v36
	v_exp_f32_e32 v47, v47
	v_add_f32_e32 v237, v237, v37
	v_exp_f32_e32 v48, v48
	v_add_f32_e32 v163, v163, v38
	v_exp_f32_e32 v49, v49
	v_add_f32_e32 v237, v237, v39
	v_add_f32_e32 v163, v163, v40
	v_add_f32_e32 v237, v237, v41
	v_cvt_pk_bf16_f32 v216, v42, v43
	v_cvt_pk_bf16_f32 v217, v44, v45
	v_cvt_pk_bf16_f32 v218, v46, v47
	v_cvt_pk_bf16_f32 v219, v48, v49
	v_add_f32_e32 v163, v163, v42
	v_add_f32_e32 v237, v237, v43
	s_waitcnt lgkmcnt(5)
	v_mfma_f32_32x32x16_bf16 v[18:33], v[178:181], v[216:219], v[18:33]
	s_waitcnt lgkmcnt(3)
	v_mfma_f32_32x32x16_bf16 v[2:17], v[182:185], v[216:219], v[2:17]
	v_add_f32_e32 v163, v163, v44
	v_add_f32_e32 v237, v237, v45
	v_add_f32_e32 v163, v163, v46
	v_add_f32_e32 v237, v237, v47
	v_add_f32_e32 v163, v163, v48
	v_add_f32_e32 v237, v237, v49
	v_add_f32_e32 v163, v163, v237
	v_cmp_lt_f32_e32 vcc, 0x45800000, v163
	v_add_f32_e32 v143, v143, v163
	s_cbranch_vccnz .Lat_postb1

.Lat_bskip1:
	s_waitcnt lgkmcnt(0)
	s_barrier
	s_waitcnt vmcnt(0)
	ds_write_b128 v112, v[90:93]
	ds_write_b128 v113, v[94:97] offset:13312
	ds_write_b128 v115, v[98:101] offset:128

.Lat_bandctl2:
	s_add_i32 s12, s20, s21
	s_cmp_le_i32 s12, s38
	s_cbranch_scc0 .Lat_bskip2
	ds_read_b128 v[170:173], v140 offset:45056
	ds_read_b128 v[174:177], v140 offset:45088
	ds_read_b128 v[178:181], v140 offset:45120
	ds_read_b128 v[182:185], v140 offset:45152
	ds_read_b128 v[186:189], v140 offset:45184
	ds_read_b128 v[190:193], v140 offset:45216
	ds_read_b128 v[204:207], v141 offset:45056
	ds_read_b128 v[208:211], v141 offset:45088
	s_waitcnt lgkmcnt(7)
	v_mfma_f32_32x32x16_bf16 v[50:65], v[170:173], v[66:69], v[146:161]
	ds_read_b128 v[170:173], v141 offset:45120
	s_waitcnt lgkmcnt(7)
	v_mfma_f32_32x32x16_bf16 v[50:65], v[174:177], v[70:73], v[50:65]
	ds_read_b128 v[174:177], v141 offset:45152
	s_waitcnt lgkmcnt(7)
	v_mfma_f32_32x32x16_bf16 v[50:65], v[178:181], v[74:77], v[50:65]
	ds_read_b128 v[178:181], v141 offset:45184
	s_waitcnt lgkmcnt(7)
	v_mfma_f32_32x32x16_bf16 v[50:65], v[182:185], v[78:81], v[50:65]
	ds_read_b128 v[182:185], v141 offset:45216
	s_waitcnt lgkmcnt(7)
	v_mfma_f32_32x32x16_bf16 v[50:65], v[186:189], v[82:85], v[50:65]
	s_waitcnt lgkmcnt(6)
	v_mfma_f32_32x32x16_bf16 v[50:65], v[190:193], v[86:89], v[50:65]
	ds_read_b64_tr_b16 v[186:187], v251 offset:13312
	ds_read_b64_tr_b16 v[188:189], v251 offset:14464
	ds_read_b64_tr_b16 v[190:191], v251 offset:13376
	ds_read_b64_tr_b16 v[192:193], v251 offset:14528
	s_waitcnt lgkmcnt(9)
	v_mfma_f32_32x32x16_bf16 v[34:49], v[204:207], v[66:69], v[146:161]
	ds_read_b64_tr_b16 v[204:205], v251 offset:15616
	ds_read_b64_tr_b16 v[206:207], v251 offset:16768
	s_waitcnt lgkmcnt(10)
	v_mfma_f32_32x32x16_bf16 v[34:49], v[208:211], v[70:73], v[34:49]
	ds_read_b64_tr_b16 v[208:209], v251 offset:15680
	ds_read_b64_tr_b16 v[210:211], v251 offset:16832
	s_nop 5
	v_add_u32_e32 v0, s21, v121
	v_mov_b32_e32 v145, v0
	v_add_u32_e32 v168, 1, v0
	v_cmp_le_i32_e64 vcc, v145, v102
	v_add_u32_e32 v252, 2, v0
	v_cmp_le_i32_e64 s[28:29], v168, v102
	v_cndmask_b32_e64 v50, v203, v50, vcc
	v_add_u32_e32 v145, 3, v0
	v_cmp_le_i32_e64 vcc, v252, v102
	v_cndmask_b32_e64 v51, v203, v51, s[28:29]
	v_add_u32_e32 v168, 8, v0
	v_cmp_le_i32_e64 s[28:29], v145, v102
	v_cndmask_b32_e64 v52, v203, v52, vcc
	v_add_u32_e32 v252, 9, v0
	v_cmp_le_i32_e64 vcc, v168, v102
	v_cndmask_b32_e64 v53, v203, v53, s[28:29]
	v_add_u32_e32 v145, 10, v0
	v_cmp_le_i32_e64 s[28:29], v252, v102
	v_cndmask_b32_e64 v54, v203, v54, vcc
	v_add_u32_e32 v168, 11, v0
	v_cmp_le_i32_e64 vcc, v145, v102
	v_cndmask_b32_e64 v55, v203, v55, s[28:29]
	v_add_u32_e32 v252, 16, v0
	v_cmp_le_i32_e64 s[28:29], v168, v102
	v_cndmask_b32_e64 v56, v203, v56, vcc
	v_add_u32_e32 v145, 17, v0
	v_cmp_le_i32_e64 vcc, v252, v102
	v_cndmask_b32_e64 v57, v203, v57, s[28:29]
	v_add_u32_e32 v168, 18, v0
	v_cmp_le_i32_e64 s[28:29], v145, v102
	v_cndmask_b32_e64 v58, v203, v58, vcc
	v_add_u32_e32 v252, 19, v0
	v_cmp_le_i32_e64 vcc, v168, v102
	v_cndmask_b32_e64 v59, v203, v59, s[28:29]
	v_add_u32_e32 v145, 24, v0
	v_cmp_le_i32_e64 s[28:29], v252, v102
	v_cndmask_b32_e64 v60, v203, v60, vcc
	v_add_u32_e32 v168, 25, v0
	v_cmp_le_i32_e64 vcc, v145, v102
	v_cndmask_b32_e64 v61, v203, v61, s[28:29]
	v_add_u32_e32 v252, 26, v0
	v_cmp_le_i32_e64 s[28:29], v168, v102
	v_cndmask_b32_e64 v62, v203, v62, vcc
	v_add_u32_e32 v145, 27, v0
	v_cmp_le_i32_e64 vcc, v252, v102
	v_cndmask_b32_e64 v63, v203, v63, s[28:29]
	v_cmp_le_i32_e64 s[28:29], v145, v102
	v_cndmask_b32_e64 v64, v203, v64, vcc
	s_nop 1
	v_cndmask_b32_e64 v65, v203, v65, s[28:29]
	v_exp_f32_e32 v50, v50
	v_exp_f32_e32 v51, v51
	v_exp_f32_e32 v52, v52
	v_exp_f32_e32 v53, v53
	s_waitcnt lgkmcnt(11)
	v_mfma_f32_32x32x16_bf16 v[34:49], v[170:173], v[74:77], v[34:49]
	v_exp_f32_e32 v54, v54
	v_exp_f32_e32 v55, v55
	v_exp_f32_e32 v56, v56
	v_exp_f32_e32 v57, v57
	v_cvt_pk_bf16_f32 v212, v50, v51
	v_cvt_pk_bf16_f32 v213, v52, v53
	v_cvt_pk_bf16_f32 v214, v54, v55
	v_cvt_pk_bf16_f32 v215, v56, v57
	s_waitcnt lgkmcnt(10)
	v_mfma_f32_32x32x16_bf16 v[34:49], v[174:177], v[78:81], v[34:49]
	v_add_f32_e32 v163, v50, v52
	v_add_f32_e32 v237, v51, v53
	s_waitcnt lgkmcnt(6)
	v_mfma_f32_32x32x16_bf16 v[18:33], v[186:189], v[212:215], v[18:33]
	v_exp_f32_e32 v58, v58
	v_exp_f32_e32 v59, v59
	v_exp_f32_e32 v60, v60
	s_waitcnt lgkmcnt(4)
	v_mfma_f32_32x32x16_bf16 v[2:17], v[190:193], v[212:215], v[2:17]
	v_exp_f32_e32 v61, v61
	v_exp_f32_e32 v62, v62
	v_exp_f32_e32 v63, v63
	v_mfma_f32_32x32x16_bf16 v[34:49], v[178:181], v[82:85], v[34:49]
	v_exp_f32_e32 v64, v64
	v_exp_f32_e32 v65, v65
	v_add_f32_e32 v163, v163, v54
	v_add_f32_e32 v237, v237, v55
	v_mfma_f32_32x32x16_bf16 v[34:49], v[182:185], v[86:89], v[34:49]
	v_cvt_pk_bf16_f32 v216, v58, v59
	v_cvt_pk_bf16_f32 v217, v60, v61
	v_cvt_pk_bf16_f32 v218, v62, v63
	v_cvt_pk_bf16_f32 v219, v64, v65
	v_add_f32_e32 v163, v163, v56
	v_add_f32_e32 v237, v237, v57
	v_add_f32_e32 v163, v163, v58
	v_add_f32_e32 v237, v237, v59
	s_waitcnt lgkmcnt(2)
	v_mfma_f32_32x32x16_bf16 v[18:33], v[204:207], v[216:219], v[18:33]
	v_add_f32_e32 v163, v163, v60
	v_add_f32_e32 v237, v237, v61
	v_add_f32_e32 v163, v163, v62
	s_waitcnt lgkmcnt(0)
	v_mfma_f32_32x32x16_bf16 v[2:17], v[208:211], v[216:219], v[2:17]
	v_add_f32_e32 v237, v237, v63
	v_add_f32_e32 v163, v163, v64
	v_add_f32_e32 v237, v237, v65
	s_barrier
	ds_read_b64_tr_b16 v[170:171], v251 offset:17920
	ds_read_b64_tr_b16 v[172:173], v251 offset:19072
	ds_read_b64_tr_b16 v[174:175], v251 offset:17984
	ds_read_b64_tr_b16 v[176:177], v251 offset:19136
	ds_read_b64_tr_b16 v[178:179], v251 offset:20224
	ds_read_b64_tr_b16 v[180:181], v251 offset:21376
	ds_read_b64_tr_b16 v[182:183], v251 offset:20288
	ds_read_b64_tr_b16 v[184:185], v251 offset:21440
	s_cmp_eq_u32 s19, s37
	s_cbranch_scc1 .Lat_bw3_2
	s_waitcnt vmcnt(0)
	s_branch .Lat_bwd_2

.Lat_bwd_2:
	ds_write_b128 v112, v[220:223] offset:22528
	ds_write_b128 v113, v[224:227] offset:35840
	ds_write_b128 v115, v[228:231] offset:22656
	v_add_u32_e32 v0, s21, v121
	v_add_u32_e32 v145, 32, v0
	v_add_u32_e32 v168, 33, v0
	v_cmp_le_i32_e64 vcc, v145, v102
	v_add_u32_e32 v252, 34, v0
	v_cmp_le_i32_e64 s[28:29], v168, v102
	v_cndmask_b32_e64 v34, v203, v34, vcc
	v_add_u32_e32 v145, 35, v0
	v_cmp_le_i32_e64 vcc, v252, v102
	v_cndmask_b32_e64 v35, v203, v35, s[28:29]
	v_add_u32_e32 v168, 40, v0
	v_cmp_le_i32_e64 s[28:29], v145, v102
	v_cndmask_b32_e64 v36, v203, v36, vcc
	v_add_u32_e32 v252, 41, v0
	v_cmp_le_i32_e64 vcc, v168, v102
	v_cndmask_b32_e64 v37, v203, v37, s[28:29]
	v_add_u32_e32 v145, 42, v0
	v_cmp_le_i32_e64 s[28:29], v252, v102
	v_cndmask_b32_e64 v38, v203, v38, vcc
	v_add_u32_e32 v168, 43, v0
	v_cmp_le_i32_e64 vcc, v145, v102
	v_cndmask_b32_e64 v39, v203, v39, s[28:29]
	v_add_u32_e32 v252, 48, v0
	v_cmp_le_i32_e64 s[28:29], v168, v102
	v_cndmask_b32_e64 v40, v203, v40, vcc
	v_add_u32_e32 v145, 49, v0
	v_cmp_le_i32_e64 vcc, v252, v102
	v_cndmask_b32_e64 v41, v203, v41, s[28:29]
	v_add_u32_e32 v168, 50, v0
	v_cmp_le_i32_e64 s[28:29], v145, v102
	v_cndmask_b32_e64 v42, v203, v42, vcc
	v_add_u32_e32 v252, 51, v0
	v_cmp_le_i32_e64 vcc, v168, v102
	v_cndmask_b32_e64 v43, v203, v43, s[28:29]
	v_add_u32_e32 v145, 56, v0
	v_cmp_le_i32_e64 s[28:29], v252, v102
	v_cndmask_b32_e64 v44, v203, v44, vcc
	v_add_u32_e32 v168, 57, v0
	v_cmp_le_i32_e64 vcc, v145, v102
	v_cndmask_b32_e64 v45, v203, v45, s[28:29]
	v_add_u32_e32 v252, 58, v0
	v_cmp_le_i32_e64 s[28:29], v168, v102
	v_cndmask_b32_e64 v46, v203, v46, vcc
	v_add_u32_e32 v145, 59, v0
	v_cmp_le_i32_e64 vcc, v252, v102
	v_cndmask_b32_e64 v47, v203, v47, s[28:29]
	v_cmp_le_i32_e64 s[28:29], v145, v102
	v_cndmask_b32_e64 v48, v203, v48, vcc
	s_nop 1
	v_cndmask_b32_e64 v49, v203, v49, s[28:29]
	v_exp_f32_e32 v34, v34
	v_exp_f32_e32 v35, v35
	v_exp_f32_e32 v36, v36
	v_exp_f32_e32 v37, v37
	v_exp_f32_e32 v38, v38
	v_exp_f32_e32 v39, v39
	v_exp_f32_e32 v40, v40
	v_exp_f32_e32 v41, v41
	v_cvt_pk_bf16_f32 v212, v34, v35
	v_cvt_pk_bf16_f32 v213, v36, v37
	v_cvt_pk_bf16_f32 v214, v38, v39
	v_cvt_pk_bf16_f32 v215, v40, v41
	v_exp_f32_e32 v42, v42
	v_exp_f32_e32 v43, v43
	s_waitcnt lgkmcnt(9)
	v_mfma_f32_32x32x16_bf16 v[18:33], v[170:173], v[212:215], v[18:33]
	s_waitcnt lgkmcnt(7)
	v_mfma_f32_32x32x16_bf16 v[2:17], v[174:177], v[212:215], v[2:17]
	v_exp_f32_e32 v44, v44
	v_add_f32_e32 v163, v163, v34
	v_exp_f32_e32 v45, v45
	v_add_f32_e32 v237, v237, v35
	v_exp_f32_e32 v46, v46
	v_add_f32_e32 v163, v163, v36
	v_exp_f32_e32 v47, v47
	v_add_f32_e32 v237, v237, v37
	v_exp_f32_e32 v48, v48
	v_add_f32_e32 v163, v163, v38
	v_exp_f32_e32 v49, v49
	v_add_f32_e32 v237, v237, v39
	v_add_f32_e32 v163, v163, v40
	v_add_f32_e32 v237, v237, v41
	v_cvt_pk_bf16_f32 v216, v42, v43
	v_cvt_pk_bf16_f32 v217, v44, v45
	v_cvt_pk_bf16_f32 v218, v46, v47
	v_cvt_pk_bf16_f32 v219, v48, v49
	v_add_f32_e32 v163, v163, v42
	v_add_f32_e32 v237, v237, v43
	s_waitcnt lgkmcnt(5)
	v_mfma_f32_32x32x16_bf16 v[18:33], v[178:181], v[216:219], v[18:33]
	s_waitcnt lgkmcnt(3)
	v_mfma_f32_32x32x16_bf16 v[2:17], v[182:185], v[216:219], v[2:17]
	v_add_f32_e32 v163, v163, v44
	v_add_f32_e32 v237, v237, v45
	v_add_f32_e32 v163, v163, v46
	v_add_f32_e32 v237, v237, v47
	v_add_f32_e32 v163, v163, v48
	v_add_f32_e32 v237, v237, v49
	v_add_f32_e32 v163, v163, v237
	v_cmp_lt_f32_e32 vcc, 0x45800000, v163
	v_add_f32_e32 v143, v143, v163
	s_cbranch_vccnz .Lat_postb2

.Lat_bskip2:
	s_waitcnt lgkmcnt(0)
	s_barrier
	s_waitcnt vmcnt(0)
	ds_write_b128 v112, v[220:223] offset:22528
	ds_write_b128 v113, v[224:227] offset:35840
	ds_write_b128 v115, v[228:231] offset:22656

.LBB0_614:
	v_lshl_add_u32 v140, s44, 8, v142
	v_lshl_or_b32 v138, s43, 8, v144
	v_ashrrev_i32_e32 v141, 31, v140
	v_ashrrev_i32_e32 v139, 31, v138
	v_lshlrev_b64 v[136:137], 10, v[140:141]
	v_lshl_add_u64 v[136:137], v[136:137], 0, v[138:139]
	v_lshlrev_b64 v[136:137], 2, v[136:137]
	v_lshl_add_u64 v[216:217], s[12:13], 0, v[136:137]
	v_lshl_add_u64 v[218:219], s[4:5], 0, v[136:137]
	v_mov_b32_e32 v152, 0x10000
	v_mov_b32_e32 v153, 0
	v_mov_b32_e32 v150, 0x50000
	v_mov_b32_e32 v151, 0
	s_mov_b64 s[20:21], -1
	s_and_b64 vcc, exec, s[0:1]
	global_load_dwordx4 v[154:157], v[216:217], off
	global_load_dwordx4 v[158:161], v[216:217], off offset:64
	global_load_dwordx4 v[164:167], v[216:217], off offset:512
	global_load_dwordx4 v[168:171], v[216:217], off offset:576
	v_lshl_add_u64 v[216:217], v[216:217], 0, v[152:153]
	global_load_dwordx4 v[172:175], v[216:217], off
	global_load_dwordx4 v[176:179], v[216:217], off offset:64
	global_load_dwordx4 v[180:183], v[216:217], off offset:512
	global_load_dwordx4 v[184:187], v[216:217], off offset:576
	v_lshl_add_u64 v[216:217], v[216:217], 0, v[152:153]
	global_load_dwordx4 v[188:191], v[216:217], off
	global_load_dwordx4 v[204:207], v[216:217], off offset:64
	global_load_dwordx4 v[208:211], v[216:217], off offset:512
	global_load_dwordx4 v[212:215], v[216:217], off offset:576
	v_lshl_add_u64 v[216:217], v[216:217], 0, v[152:153]
	s_waitcnt vmcnt(8)
	v_pk_add_f32 v[128:129], v[128:129], v[156:157]
	v_pk_add_f32 v[126:127], v[126:127], v[154:155]
	v_pk_add_f32 v[124:125], v[124:125], v[160:161]
	v_pk_add_f32 v[122:123], v[122:123], v[158:159]
	v_pk_add_f32 v[120:121], v[120:121], v[166:167]
	v_pk_add_f32 v[118:119], v[118:119], v[164:165]
	v_pk_add_f32 v[116:117], v[116:117], v[170:171]
	v_pk_add_f32 v[114:115], v[114:115], v[168:169]
	global_store_dwordx4 v[218:219], v[126:129], off
	global_store_dwordx4 v[218:219], v[122:125], off offset:64
	global_store_dwordx4 v[218:219], v[118:121], off offset:512
	global_store_dwordx4 v[218:219], v[114:117], off offset:576
	v_lshl_add_u64 v[218:219], v[218:219], 0, v[152:153]
	global_load_dwordx4 v[154:157], v[216:217], off
	global_load_dwordx4 v[158:161], v[216:217], off offset:64
	global_load_dwordx4 v[164:167], v[216:217], off offset:512
	global_load_dwordx4 v[168:171], v[216:217], off offset:576
	v_lshl_add_u64 v[216:217], v[216:217], 0, v[150:151]
	s_waitcnt vmcnt(12)
	v_pk_add_f32 v[112:113], v[112:113], v[174:175]
	v_pk_add_f32 v[110:111], v[110:111], v[172:173]
	v_pk_add_f32 v[108:109], v[108:109], v[178:179]
	v_pk_add_f32 v[106:107], v[106:107], v[176:177]
	v_pk_add_f32 v[104:105], v[104:105], v[182:183]
	v_pk_add_f32 v[102:103], v[102:103], v[180:181]
	v_pk_add_f32 v[100:101], v[100:101], v[186:187]
	v_pk_add_f32 v[98:99], v[98:99], v[184:185]
	global_store_dwordx4 v[218:219], v[110:113], off
	global_store_dwordx4 v[218:219], v[106:109], off offset:64
	global_store_dwordx4 v[218:219], v[102:105], off offset:512
	global_store_dwordx4 v[218:219], v[98:101], off offset:576
	v_lshl_add_u64 v[218:219], v[218:219], 0, v[152:153]
	global_load_dwordx4 v[172:175], v[216:217], off
	global_load_dwordx4 v[176:179], v[216:217], off offset:64
	global_load_dwordx4 v[180:183], v[216:217], off offset:512
	global_load_dwordx4 v[184:187], v[216:217], off offset:576
	v_lshl_add_u64 v[216:217], v[216:217], 0, v[152:153]
	s_waitcnt vmcnt(16)
	v_pk_add_f32 v[96:97], v[96:97], v[190:191]
	v_pk_add_f32 v[94:95], v[94:95], v[188:189]
	v_pk_add_f32 v[92:93], v[92:93], v[206:207]
	v_pk_add_f32 v[90:91], v[90:91], v[204:205]
	v_pk_add_f32 v[88:89], v[88:89], v[210:211]
	v_pk_add_f32 v[86:87], v[86:87], v[208:209]
	v_pk_add_f32 v[84:85], v[84:85], v[214:215]
	v_pk_add_f32 v[82:83], v[82:83], v[212:213]
	global_store_dwordx4 v[218:219], v[94:97], off
	global_store_dwordx4 v[218:219], v[90:93], off offset:64
	global_store_dwordx4 v[218:219], v[86:89], off offset:512
	global_store_dwordx4 v[218:219], v[82:85], off offset:576
	v_lshl_add_u64 v[218:219], v[218:219], 0, v[152:153]
	global_load_dwordx4 v[188:191], v[216:217], off
	global_load_dwordx4 v[204:207], v[216:217], off offset:64
	global_load_dwordx4 v[208:211], v[216:217], off offset:512
	global_load_dwordx4 v[212:215], v[216:217], off offset:576
	v_lshl_add_u64 v[216:217], v[216:217], 0, v[152:153]
	s_waitcnt vmcnt(16)
	v_pk_add_f32 v[80:81], v[80:81], v[156:157]
	v_pk_add_f32 v[78:79], v[78:79], v[154:155]
	v_pk_add_f32 v[76:77], v[76:77], v[160:161]
	v_pk_add_f32 v[74:75], v[74:75], v[158:159]
	v_pk_add_f32 v[72:73], v[72:73], v[166:167]
	v_pk_add_f32 v[70:71], v[70:71], v[164:165]
	v_pk_add_f32 v[68:69], v[68:69], v[170:171]
	v_pk_add_f32 v[66:67], v[66:67], v[168:169]
	global_store_dwordx4 v[218:219], v[78:81], off
	global_store_dwordx4 v[218:219], v[74:77], off offset:64
	global_store_dwordx4 v[218:219], v[70:73], off offset:512
	global_store_dwordx4 v[218:219], v[66:69], off offset:576
	v_lshl_add_u64 v[218:219], v[218:219], 0, v[150:151]
	global_load_dwordx4 v[154:157], v[216:217], off
	global_load_dwordx4 v[158:161], v[216:217], off offset:64
	global_load_dwordx4 v[164:167], v[216:217], off offset:512
	global_load_dwordx4 v[168:171], v[216:217], off offset:576
	v_lshl_add_u64 v[216:217], v[216:217], 0, v[152:153]
	s_waitcnt vmcnt(16)
	v_pk_add_f32 v[64:65], v[64:65], v[174:175]
	v_pk_add_f32 v[62:63], v[62:63], v[172:173]
	v_pk_add_f32 v[60:61], v[60:61], v[178:179]
	v_pk_add_f32 v[58:59], v[58:59], v[176:177]
	v_pk_add_f32 v[56:57], v[56:57], v[182:183]
	v_pk_add_f32 v[54:55], v[54:55], v[180:181]
	v_pk_add_f32 v[52:53], v[52:53], v[186:187]
	v_pk_add_f32 v[50:51], v[50:51], v[184:185]
	global_store_dwordx4 v[218:219], v[62:65], off
	global_store_dwordx4 v[218:219], v[58:61], off offset:64
	global_store_dwordx4 v[218:219], v[54:57], off offset:512
	global_store_dwordx4 v[218:219], v[50:53], off offset:576
	v_lshl_add_u64 v[218:219], v[218:219], 0, v[152:153]
	global_load_dwordx4 v[172:175], v[216:217], off
	global_load_dwordx4 v[176:179], v[216:217], off offset:64
	global_load_dwordx4 v[180:183], v[216:217], off offset:512
	global_load_dwordx4 v[184:187], v[216:217], off offset:576
	v_lshl_add_u64 v[216:217], v[216:217], 0, v[152:153]
	s_waitcnt vmcnt(16)
	v_pk_add_f32 v[48:49], v[48:49], v[190:191]
	v_pk_add_f32 v[46:47], v[46:47], v[188:189]
	v_pk_add_f32 v[44:45], v[44:45], v[206:207]
	v_pk_add_f32 v[42:43], v[42:43], v[204:205]
	v_pk_add_f32 v[40:41], v[40:41], v[210:211]
	v_pk_add_f32 v[38:39], v[38:39], v[208:209]
	v_pk_add_f32 v[36:37], v[36:37], v[214:215]
	v_pk_add_f32 v[34:35], v[34:35], v[212:213]
	global_store_dwordx4 v[218:219], v[46:49], off
	global_store_dwordx4 v[218:219], v[42:45], off offset:64
	global_store_dwordx4 v[218:219], v[38:41], off offset:512
	global_store_dwordx4 v[218:219], v[34:37], off offset:576
	v_lshl_add_u64 v[218:219], v[218:219], 0, v[152:153]
	s_waitcnt vmcnt(12)
	v_pk_add_f32 v[32:33], v[32:33], v[156:157]
	v_pk_add_f32 v[30:31], v[30:31], v[154:155]
	v_pk_add_f32 v[28:29], v[28:29], v[160:161]
	v_pk_add_f32 v[26:27], v[26:27], v[158:159]
	v_pk_add_f32 v[24:25], v[24:25], v[166:167]
	v_pk_add_f32 v[22:23], v[22:23], v[164:165]
	v_pk_add_f32 v[20:21], v[20:21], v[170:171]
	v_pk_add_f32 v[18:19], v[18:19], v[168:169]
	global_store_dwordx4 v[218:219], v[30:33], off
	global_store_dwordx4 v[218:219], v[26:29], off offset:64
	global_store_dwordx4 v[218:219], v[22:25], off offset:512
	global_store_dwordx4 v[218:219], v[18:21], off offset:576
	v_lshl_add_u64 v[218:219], v[218:219], 0, v[152:153]
	s_waitcnt vmcnt(8)
	v_pk_add_f32 v[16:17], v[16:17], v[174:175]
	v_pk_add_f32 v[14:15], v[14:15], v[172:173]
	v_pk_add_f32 v[12:13], v[12:13], v[178:179]
	v_pk_add_f32 v[10:11], v[10:11], v[176:177]
	v_pk_add_f32 v[8:9], v[8:9], v[182:183]
	v_pk_add_f32 v[6:7], v[6:7], v[180:181]
	v_pk_add_f32 v[4:5], v[4:5], v[186:187]
	v_pk_add_f32 v[2:3], v[2:3], v[184:185]
	global_store_dwordx4 v[218:219], v[14:17], off
	global_store_dwordx4 v[218:219], v[10:13], off offset:64
	global_store_dwordx4 v[218:219], v[6:9], off offset:512
	global_store_dwordx4 v[218:219], v[2:5], off offset:576
	v_lshl_add_u64 v[218:219], v[218:219], 0, v[152:153]
	s_cbranch_vccnz .LBB0_598
	s_andn2_b64 vcc, exec, s[10:11]
	s_cbranch_vccnz .LBB0_597
	s_barrier
	s_branch .LBB0_597

.LBB0_892:
	v_lshl_add_u32 v140, s42, 8, v142
	v_lshl_or_b32 v138, s41, 8, v144
	v_ashrrev_i32_e32 v141, 31, v140
	v_ashrrev_i32_e32 v139, 31, v138
	v_lshlrev_b64 v[136:137], 10, v[140:141]
	v_lshl_add_u64 v[136:137], v[136:137], 0, v[138:139]
	v_lshlrev_b64 v[136:137], 2, v[136:137]
	v_lshl_add_u64 v[216:217], s[4:5], 0, v[136:137]
	v_lshl_add_u64 v[218:219], s[4:5], 0, v[136:137]
	v_mov_b32_e32 v152, 0x10000
	v_mov_b32_e32 v153, 0
	v_mov_b32_e32 v150, 0x50000
	v_mov_b32_e32 v151, 0
	s_mov_b32 s18, 0x80000
	s_mov_b32 s18, 0x90000
	s_mov_b32 s18, 0xa0000
	s_mov_b32 s18, 0xb0000
	s_mov_b64 s[18:19], -1
	s_and_b64 vcc, exec, s[0:1]
	global_load_dwordx4 v[154:157], v[216:217], off
	global_load_dwordx4 v[158:161], v[216:217], off offset:64
	global_load_dwordx4 v[164:167], v[216:217], off offset:512
	global_load_dwordx4 v[168:171], v[216:217], off offset:576
	v_lshl_add_u64 v[216:217], v[216:217], 0, v[152:153]
	global_load_dwordx4 v[172:175], v[216:217], off
	global_load_dwordx4 v[176:179], v[216:217], off offset:64
	global_load_dwordx4 v[180:183], v[216:217], off offset:512
	global_load_dwordx4 v[184:187], v[216:217], off offset:576
	v_lshl_add_u64 v[216:217], v[216:217], 0, v[152:153]
	global_load_dwordx4 v[188:191], v[216:217], off
	global_load_dwordx4 v[204:207], v[216:217], off offset:64
	global_load_dwordx4 v[208:211], v[216:217], off offset:512
	global_load_dwordx4 v[212:215], v[216:217], off offset:576
	v_lshl_add_u64 v[216:217], v[216:217], 0, v[152:153]
	s_waitcnt vmcnt(8)
	v_pk_add_f32 v[128:129], v[128:129], v[156:157]
	v_pk_add_f32 v[126:127], v[126:127], v[154:155]
	v_pk_add_f32 v[124:125], v[124:125], v[160:161]
	v_pk_add_f32 v[122:123], v[122:123], v[158:159]
	v_pk_add_f32 v[120:121], v[120:121], v[166:167]
	v_pk_add_f32 v[118:119], v[118:119], v[164:165]
	v_pk_add_f32 v[116:117], v[116:117], v[170:171]
	v_pk_add_f32 v[114:115], v[114:115], v[168:169]
	global_store_dwordx4 v[218:219], v[126:129], off
	global_store_dwordx4 v[218:219], v[122:125], off offset:64
	global_store_dwordx4 v[218:219], v[118:121], off offset:512
	global_store_dwordx4 v[218:219], v[114:117], off offset:576
	v_lshl_add_u64 v[218:219], v[218:219], 0, v[152:153]
	global_load_dwordx4 v[154:157], v[216:217], off
	global_load_dwordx4 v[158:161], v[216:217], off offset:64
	global_load_dwordx4 v[164:167], v[216:217], off offset:512
	global_load_dwordx4 v[168:171], v[216:217], off offset:576
	v_lshl_add_u64 v[216:217], v[216:217], 0, v[150:151]
	s_waitcnt vmcnt(12)
	v_pk_add_f32 v[112:113], v[112:113], v[174:175]
	v_pk_add_f32 v[110:111], v[110:111], v[172:173]
	v_pk_add_f32 v[108:109], v[108:109], v[178:179]
	v_pk_add_f32 v[106:107], v[106:107], v[176:177]
	v_pk_add_f32 v[104:105], v[104:105], v[182:183]
	v_pk_add_f32 v[102:103], v[102:103], v[180:181]
	v_pk_add_f32 v[100:101], v[100:101], v[186:187]
	v_pk_add_f32 v[98:99], v[98:99], v[184:185]
	global_store_dwordx4 v[218:219], v[110:113], off
	global_store_dwordx4 v[218:219], v[106:109], off offset:64
	global_store_dwordx4 v[218:219], v[102:105], off offset:512
	global_store_dwordx4 v[218:219], v[98:101], off offset:576
	v_lshl_add_u64 v[218:219], v[218:219], 0, v[152:153]
	global_load_dwordx4 v[172:175], v[216:217], off
	global_load_dwordx4 v[176:179], v[216:217], off offset:64
	global_load_dwordx4 v[180:183], v[216:217], off offset:512
	global_load_dwordx4 v[184:187], v[216:217], off offset:576
	v_lshl_add_u64 v[216:217], v[216:217], 0, v[152:153]
	s_waitcnt vmcnt(16)
	v_pk_add_f32 v[96:97], v[96:97], v[190:191]
	v_pk_add_f32 v[94:95], v[94:95], v[188:189]
	v_pk_add_f32 v[92:93], v[92:93], v[206:207]
	v_pk_add_f32 v[90:91], v[90:91], v[204:205]
	v_pk_add_f32 v[88:89], v[88:89], v[210:211]
	v_pk_add_f32 v[86:87], v[86:87], v[208:209]
	v_pk_add_f32 v[84:85], v[84:85], v[214:215]
	v_pk_add_f32 v[82:83], v[82:83], v[212:213]
	global_store_dwordx4 v[218:219], v[94:97], off
	global_store_dwordx4 v[218:219], v[90:93], off offset:64
	global_store_dwordx4 v[218:219], v[86:89], off offset:512
	global_store_dwordx4 v[218:219], v[82:85], off offset:576
	v_lshl_add_u64 v[218:219], v[218:219], 0, v[152:153]
	global_load_dwordx4 v[188:191], v[216:217], off
	global_load_dwordx4 v[204:207], v[216:217], off offset:64
	global_load_dwordx4 v[208:211], v[216:217], off offset:512
	global_load_dwordx4 v[212:215], v[216:217], off offset:576
	v_lshl_add_u64 v[216:217], v[216:217], 0, v[152:153]
	s_waitcnt vmcnt(16)
	v_pk_add_f32 v[80:81], v[80:81], v[156:157]
	v_pk_add_f32 v[78:79], v[78:79], v[154:155]
	v_pk_add_f32 v[76:77], v[76:77], v[160:161]
	v_pk_add_f32 v[74:75], v[74:75], v[158:159]
	v_pk_add_f32 v[72:73], v[72:73], v[166:167]
	v_pk_add_f32 v[70:71], v[70:71], v[164:165]
	v_pk_add_f32 v[68:69], v[68:69], v[170:171]
	v_pk_add_f32 v[66:67], v[66:67], v[168:169]
	global_store_dwordx4 v[218:219], v[78:81], off
	global_store_dwordx4 v[218:219], v[74:77], off offset:64
	global_store_dwordx4 v[218:219], v[70:73], off offset:512
	global_store_dwordx4 v[218:219], v[66:69], off offset:576
	v_lshl_add_u64 v[218:219], v[218:219], 0, v[150:151]
	global_load_dwordx4 v[154:157], v[216:217], off
	global_load_dwordx4 v[158:161], v[216:217], off offset:64
	global_load_dwordx4 v[164:167], v[216:217], off offset:512
	global_load_dwordx4 v[168:171], v[216:217], off offset:576
	v_lshl_add_u64 v[216:217], v[216:217], 0, v[152:153]
	s_waitcnt vmcnt(16)
	v_pk_add_f32 v[64:65], v[64:65], v[174:175]
	v_pk_add_f32 v[62:63], v[62:63], v[172:173]
	v_pk_add_f32 v[60:61], v[60:61], v[178:179]
	v_pk_add_f32 v[58:59], v[58:59], v[176:177]
	v_pk_add_f32 v[56:57], v[56:57], v[182:183]
	v_pk_add_f32 v[54:55], v[54:55], v[180:181]
	v_pk_add_f32 v[52:53], v[52:53], v[186:187]
	v_pk_add_f32 v[50:51], v[50:51], v[184:185]
	global_store_dwordx4 v[218:219], v[62:65], off
	global_store_dwordx4 v[218:219], v[58:61], off offset:64
	global_store_dwordx4 v[218:219], v[54:57], off offset:512
	global_store_dwordx4 v[218:219], v[50:53], off offset:576
	v_lshl_add_u64 v[218:219], v[218:219], 0, v[152:153]
	global_load_dwordx4 v[172:175], v[216:217], off
	global_load_dwordx4 v[176:179], v[216:217], off offset:64
	global_load_dwordx4 v[180:183], v[216:217], off offset:512
	global_load_dwordx4 v[184:187], v[216:217], off offset:576
	v_lshl_add_u64 v[216:217], v[216:217], 0, v[152:153]
	s_waitcnt vmcnt(16)
	v_pk_add_f32 v[48:49], v[48:49], v[190:191]
	v_pk_add_f32 v[46:47], v[46:47], v[188:189]
	v_pk_add_f32 v[44:45], v[44:45], v[206:207]
	v_pk_add_f32 v[42:43], v[42:43], v[204:205]
	v_pk_add_f32 v[40:41], v[40:41], v[210:211]
	v_pk_add_f32 v[38:39], v[38:39], v[208:209]
	v_pk_add_f32 v[36:37], v[36:37], v[214:215]
	v_pk_add_f32 v[34:35], v[34:35], v[212:213]
	global_store_dwordx4 v[218:219], v[46:49], off
	global_store_dwordx4 v[218:219], v[42:45], off offset:64
	global_store_dwordx4 v[218:219], v[38:41], off offset:512
	global_store_dwordx4 v[218:219], v[34:37], off offset:576
	v_lshl_add_u64 v[218:219], v[218:219], 0, v[152:153]
	s_waitcnt vmcnt(12)
	v_pk_add_f32 v[32:33], v[32:33], v[156:157]
	v_pk_add_f32 v[30:31], v[30:31], v[154:155]
	v_pk_add_f32 v[28:29], v[28:29], v[160:161]
	v_pk_add_f32 v[26:27], v[26:27], v[158:159]
	v_pk_add_f32 v[24:25], v[24:25], v[166:167]
	v_pk_add_f32 v[22:23], v[22:23], v[164:165]
	v_pk_add_f32 v[20:21], v[20:21], v[170:171]
	v_pk_add_f32 v[18:19], v[18:19], v[168:169]
	global_store_dwordx4 v[218:219], v[30:33], off
	global_store_dwordx4 v[218:219], v[26:29], off offset:64
	global_store_dwordx4 v[218:219], v[22:25], off offset:512
	global_store_dwordx4 v[218:219], v[18:21], off offset:576
	v_lshl_add_u64 v[218:219], v[218:219], 0, v[152:153]
	s_waitcnt vmcnt(8)
	v_pk_add_f32 v[16:17], v[16:17], v[174:175]
	v_pk_add_f32 v[14:15], v[14:15], v[172:173]
	v_pk_add_f32 v[12:13], v[12:13], v[178:179]
	v_pk_add_f32 v[10:11], v[10:11], v[176:177]
	v_pk_add_f32 v[8:9], v[8:9], v[182:183]
	v_pk_add_f32 v[6:7], v[6:7], v[180:181]
	v_pk_add_f32 v[4:5], v[4:5], v[186:187]
	v_pk_add_f32 v[2:3], v[2:3], v[184:185]
	global_store_dwordx4 v[218:219], v[14:17], off
	global_store_dwordx4 v[218:219], v[10:13], off offset:64
	global_store_dwordx4 v[218:219], v[6:9], off offset:512
	global_store_dwordx4 v[218:219], v[2:5], off offset:576
	v_lshl_add_u64 v[218:219], v[218:219], 0, v[152:153]
	s_cbranch_vccnz .LBB0_876
	s_andn2_b64 vcc, exec, s[10:11]
	s_cbranch_vccnz .LBB0_875
	s_barrier
	s_branch .LBB0_875
